# LDS bank-conflict fix: scan operand rows padded to 272 B (conflict-free ds_write_b128 in both scan prologues), arrays relocated
# speedup vs baseline: 1.0370x; 1.0146x over previous
; #define lane LANE_()
; template <int MODE>
; __device__ __forceinline__ void scan_prologue(const ScanP& P, int m0, int seqbase, int T, int h, int d, float* slab, LAS float* lw, float* bon, int lane) {
;     const int fr = lane & 15, fq = lane >> 4, m = m0 + fr, pos = m - seqbase; const bool hp = pos > 0, hn = pos < T - 1;
;     float* srow = slab + fr * 384;
;     f32x4 k4[4], kk4[4], r4[4]; float ss = 0.f;
;     v2u pk_[4][3], pv_[4][3], pr_[4][3];
;     const int offp_ = hp ? -PRP : 0, offn_ = hn ? PRP : 0; const unsigned mp_ = hp ? 0xffffffffu : 0u, mn_ = hn ? 0xffffffffu : 0u;
; #pragma unroll
;     for (int n = 0; n < 4; ++n) { const bf16* p = P.proj + (size_t)m * PRP + h * 64 + 16 * n + 4 * fq;
;         { v2u t; pk_[n][1] = *(const v2u*)(p + 512);
;           t = *(const v2u*)(p + 512 + offp_); pk_[n][0] = (v2u){t.x & mp_, t.y & mp_};
;           t = *(const v2u*)(p + 512 + offn_); pk_[n][2] = (v2u){t.x & mn_, t.y & mn_};
;           if (MODE != 1) { pv_[n][1] = *(const v2u*)(p + 1024);
;             t = *(const v2u*)(p + 1024 + offp_); pv_[n][0] = (v2u){t.x & mp_, t.y & mp_};
;             t = *(const v2u*)(p + 1024 + offn_); pv_[n][2] = (v2u){t.x & mn_, t.y & mn_}; }
;           if (MODE == 2) { pr_[n][1] = *(const v2u*)(p);
;             t = *(const v2u*)(p + offp_); pr_[n][0] = (v2u){t.x & mp_, t.y & mp_};
;             t = *(const v2u*)(p + offn_); pr_[n][2] = (v2u){t.x & mn_, t.y & mn_}; } } }
;     v4u xw_[2]; bf16x8 xa_[2];
; #pragma unroll
;     for (int ks = 0; ks < 2; ++ks) { xw_[ks] = *(const v4u*)(P.proj + (size_t)m * PRP + 1536 + d * 64 + ks * 32 + 8 * fq); xa_[ks] = *(const bf16x8*)(P.proj + (size_t)m * PRP + 1664 + d * 64 + ks * 32 + 8 * fq); }
.LBB0_289:
	s_not_b32 s4, s61
	s_add_i32 s14, s53, s4
	s_and_b64 s[4:5], s[82:83], exec
	s_cselect_b32 s4, s61, s14
	s_lshl_b32 s4, s4, 4
	v_mov_b32_e32 v212, v172
	s_add_i32 s4, s4, s52
	s_lshl_b32 s14, s87, 1
	v_and_b32_e32 v231, 15, v212
	v_or_b32_e32 v128, s4, v231
	s_waitcnt vmcnt(0)
	v_subrev_u32_e32 v129, s86, v128
	v_cmp_lt_i32_e64 s[4:5], 0, v129
	v_cmp_gt_i32_e32 vcc, s49, v129
	v_ashrrev_i32_e32 v129, 31, v128
	v_ashrrev_i32_e32 v138, 4, v212
	v_lshlrev_b64 v[128:129], 12, v[128:129]
	v_lshl_add_u64 v[128:129], s[64:65], 0, v[128:129]
	v_lshlrev_b32_e32 v154, 2, v138
	v_lshl_add_u64 v[132:133], v[128:129], 0, s[14:15]
	v_ashrrev_i32_e32 v155, 31, v154
	v_cndmask_b32_e64 v131, 0, -1, s[4:5]
	v_cndmask_b32_e64 v130, 0, v224, s[4:5]
	v_lshl_add_u64 v[132:133], v[154:155], 1, v[132:133]
	v_lshl_add_u64 v[130:131], v[132:133], 0, v[130:131]
	global_load_dwordx2 v[134:135], v[130:131], off offset:1024
	global_load_dwordx2 v[166:167], v[132:133], off offset:2048
	global_load_dwordx2 v[140:141], v[130:131], off offset:2048
	global_load_dwordx2 v[156:157], v[132:133], off offset:1056
	global_load_dwordx2 v[142:143], v[130:131], off offset:1056
	global_load_dwordx2 v[254:255], v[132:133], off offset:2080
	global_load_dwordx2 v[146:147], v[130:131], off offset:2080
	global_load_dwordx2 v[150:151], v[130:131], off offset:1088
	global_load_dwordx2 v[160:161], v[130:131], off offset:2112
	global_load_dwordx2 v[184:185], v[130:131], off offset:1120
	global_load_dwordx2 v[204:205], v[130:131], off offset:2144
	global_load_dwordx2 v[170:171], v[132:133], off offset:1024
	s_nop 0
	v_cndmask_b32_e32 v180, 0, v219, vcc
	v_mul_u32_u24_e32 v158, 0x180, v231
	s_mov_b32 s85, s15
	v_lshlrev_b32_e32 v164, 3, v138
	v_lshl_add_u64 v[128:129], v[128:129], 0, s[84:85]
	v_ashrrev_i32_e32 v165, 31, v164
	s_mov_b32 s91, 15
	s_waitcnt vmcnt(0)
	v_lshlrev_b32_e32 v240, 16, v170
	v_cndmask_b32_e64 v230, 0, v134, s[4:5]
	v_cndmask_b32_e64 v234, 0, v135, s[4:5]
	v_lshl_add_u64 v[134:135], v[132:133], 0, v[180:181]
	global_load_dwordx2 v[138:139], v[134:135], off offset:2048
	global_load_dwordx2 v[144:145], v[134:135], off offset:1056
	global_load_dwordx2 v[148:149], v[134:135], off offset:2080
	global_load_dwordx2 v[152:153], v[134:135], off offset:1088
	global_load_dwordx2 v[162:163], v[134:135], off offset:2112
	global_load_dwordx2 v[186:187], v[134:135], off offset:1120
	global_load_dwordx2 v[206:207], v[134:135], off offset:2144
	global_load_dwordx2 v[136:137], v[134:135], off offset:1024
	v_lshlrev_b32_e32 v180, 2, v158
	v_lshl_add_u32 v158, v212, 4, s94
	v_lshl_add_u64 v[176:177], s[62:63], 0, v[180:181]
	v_add_u32_e32 v180, 0x3c00, v158
	v_add_u32_e32 v158, s87, v154
	v_ashrrev_i32_e32 v159, 31, v158
	v_lshlrev_b64 v[168:169], 2, v[158:159]
	v_lshl_add_u64 v[158:159], s[8:9], 0, v[168:169]
	v_and_b32_e32 v241, 0xffff0000, v170
	v_lshlrev_b32_e32 v170, 16, v171
	v_and_b32_e32 v171, 0xffff0000, v171
	v_lshlrev_b32_e32 v232, 16, v230
	v_and_b32_e32 v233, 0xffff0000, v230
	v_lshlrev_b32_e32 v238, 16, v234
	v_and_b32_e32 v239, 0xffff0000, v234
	v_lshl_add_u64 v[176:177], v[154:155], 2, v[176:177]
	v_and_b32_e32 v154, -16, v212
	v_add_u32_e32 v234, s94, v154
	v_add_u32_e32 v154, 0x2200, v234
	s_waitcnt vmcnt(0)
	v_cndmask_b32_e32 v237, 0, v136, vcc
	v_cndmask_b32_e32 v242, 0, v137, vcc
	s_nop 0
	s_nop 0
	v_cndmask_b32_e64 v203, 0, v140, s[4:5]
	v_cndmask_b32_e64 v202, 0, v141, s[4:5]
	s_nop 0
	v_lshlrev_b32_e32 v246, 16, v202
	v_and_b32_e32 v247, 0xffff0000, v202
	v_lshlrev_b32_e32 v202, 16, v166
	v_cndmask_b32_e32 v195, 0, v138, vcc
	v_cndmask_b32_e32 v193, 0, v139, vcc
	s_nop 0
	s_nop 0
	v_cndmask_b32_e64 v201, 0, v142, s[4:5]
	v_cndmask_b32_e64 v200, 0, v143, s[4:5]
	s_nop 0
	v_lshlrev_b32_e32 v250, 16, v200
	v_and_b32_e32 v251, 0xffff0000, v200
	v_lshlrev_b32_e32 v200, 16, v156
	v_cndmask_b32_e32 v194, 0, v144, vcc
	v_cndmask_b32_e32 v192, 0, v145, vcc
	s_nop 0
	s_nop 0
	v_cndmask_b32_e64 v189, 0, v146, s[4:5]
	v_cndmask_b32_e64 v188, 0, v147, s[4:5]
	global_load_dwordx2 v[146:147], v[132:133], off offset:2112
	s_nop 0
	v_cndmask_b32_e32 v179, 0, v148, vcc
	v_cndmask_b32_e32 v178, 0, v149, vcc
	global_load_dwordx2 v[148:149], v[132:133], off offset:1088
	s_nop 0
	v_cndmask_b32_e64 v199, 0, v150, s[4:5]
	v_cndmask_b32_e64 v198, 0, v151, s[4:5]
	global_load_dwordx2 v[150:151], v[132:133], off offset:1120
	s_nop 0
	v_cndmask_b32_e32 v191, 0, v152, vcc
	v_cndmask_b32_e32 v190, 0, v153, vcc
	global_load_dwordx2 v[152:153], v[132:133], off offset:2144
	s_nop 0
	s_nop 0
	v_cndmask_b32_e64 v197, 0, v160, s[4:5]
	v_cndmask_b32_e64 v196, 0, v161, s[4:5]
	s_nop 0
	v_cndmask_b32_e32 v183, 0, v162, vcc
	v_cndmask_b32_e32 v182, 0, v163, vcc
	s_nop 0
	s_nop 0
	v_cndmask_b32_e64 v214, 0, v184, s[4:5]
	v_cndmask_b32_e64 v213, 0, v185, s[4:5]
	s_nop 0
	s_nop 0
	s_nop 0
	s_nop 0
	v_lshl_add_u64 v[132:133], v[164:165], 1, v[128:129]
	global_load_dwordx4 v[140:143], v[132:133], off offset:3072
	global_load_dwordx4 v[136:139], v[132:133], off offset:3328
	global_load_dwordx4 v[128:131], v[132:133], off offset:3136
	v_cndmask_b32_e32 v216, 0, v186, vcc
	v_cndmask_b32_e64 v229, 0, v204, s[4:5]
	v_cndmask_b32_e64 v217, 0, v205, s[4:5]
	s_nop 0
	v_add_co_u32_e64 v160, s[4:5], s45, v158
	v_cndmask_b32_e32 v215, 0, v187, vcc
	global_load_dwordx4 v[184:187], v[158:159], off offset:2048
	s_nop 0
	v_addc_co_u32_e64 v161, s[4:5], 0, v159, s[4:5]
	v_add_co_u32_e64 v162, s[4:5], s96, v158
	v_cndmask_b32_e32 v236, 0, v206, vcc
	v_cndmask_b32_e32 v235, 0, v207, vcc
	global_load_dwordx4 v[204:207], v[160:161], off
	s_nop 0
	s_nop 0
	s_nop 0
	s_nop 0
	global_load_dwordx4 v[132:135], v[132:133], off offset:3392
	s_nop 0
	s_nop 0
	v_addc_co_u32_e64 v163, s[4:5], 0, v159, s[4:5]
	global_load_dwordx4 v[208:211], v[162:163], off offset:2048
	v_cmp_eq_u32_e32 vcc, s88, v231
	s_waitcnt vmcnt(2)
; #define LAS __attribute__((address_space(3)))
; __device__ __forceinline__ float shx(float v, int o, int lane) { return __builtin_bit_cast(float, __builtin_amdgcn_ds_bpermute((lane ^ o) << 2, __builtin_bit_cast(int, v))); }
; #define lane LANE_()
; template <int MODE>
; __device__ __forceinline__ void scan_prologue(const ScanP& P, int m0, int seqbase, int T, int h, int d, float* slab, LAS float* lw, float* bon, int lane) {
;     ...
; #pragma unroll
;     for (int n = 0; n < 4; ++n) { const int c = 16 * n + 4 * fq, col = h * 64 + c;
;         k4[n] = CONV3_(pk_, 1);
;         if (MODE != 1) { const f32x4 v4 = CONV3_(pv_, 2); *(f32x4*)(srow + 320 + c) = v4; LAS float* xsel = (fr == (d ? 15 : 0)) ? lw + 2048 + c : lw + 2304 + lane * 4; *(LAS f32x4*)(xsel + 192) = v4; }
;         if (MODE == 2) { r4[n] = CONV3_(pr_, 0); *(LAS f32x4*)(lw + 1024 + fr * 64 + c) = r4[n]; }
;         kk4[n] = k4[n] * *(const f32x4*)(P.k_k + col);
;         ss += (kk4[n].x * kk4[n].x + kk4[n].y * kk4[n].y) + (kk4[n].z * kk4[n].z + kk4[n].w * kk4[n].w); }
;     ...
;     ss += shx(ss, 16, lane); ss += shx(ss, 32, lane);
	v_pk_mul_f32 v[170:171], v[206:207], v[170:171]
	v_pk_mul_f32 v[204:205], v[204:205], v[240:241]
	v_pk_fma_f32 v[170:171], v[186:187], v[238:239], v[170:171]
	v_pk_fma_f32 v[184:185], v[184:185], v[232:233], v[204:205]
	v_lshlrev_b32_e32 v204, 16, v242
	v_and_b32_e32 v205, 0xffff0000, v242
	v_lshlrev_b32_e32 v186, 16, v237
	v_and_b32_e32 v187, 0xffff0000, v237
	s_waitcnt vmcnt(0)
	v_pk_fma_f32 v[204:205], v[210:211], v[204:205], v[170:171]
	v_lshl_add_u64 v[170:171], s[80:81], 0, v[168:169]
	v_pk_fma_f32 v[206:207], v[208:209], v[186:187], v[184:185]
	global_load_dwordx4 v[208:211], v[170:171], off
	v_add_co_u32_e64 v184, s[4:5], s26, v170
	s_nop 0
	s_nop 0
	v_addc_co_u32_e64 v185, s[4:5], 0, v171, s[4:5]
	global_load_dwordx4 v[238:241], v[184:185], off offset:2048
	v_add_co_u32_e64 v186, s[4:5], s96, v170
	v_lshlrev_b32_e32 v232, 16, v203
	s_nop 0
	v_addc_co_u32_e64 v187, s[4:5], 0, v171, s[4:5]
	global_load_dwordx4 v[242:245], v[186:187], off
	v_and_b32_e32 v233, 0xffff0000, v203
	v_and_b32_e32 v203, 0xffff0000, v166
	v_lshlrev_b32_e32 v166, 16, v167
	v_and_b32_e32 v167, 0xffff0000, v167
	s_mov_b32 s4, 0
	s_waitcnt vmcnt(1)
	v_pk_mul_f32 v[166:167], v[240:241], v[166:167]
	v_pk_mul_f32 v[202:203], v[238:239], v[202:203]
	v_pk_fma_f32 v[166:167], v[210:211], v[246:247], v[166:167]
	global_load_dwordx4 v[246:249], v[162:163], off offset:2112
	v_pk_fma_f32 v[202:203], v[208:209], v[232:233], v[202:203]
	v_lshlrev_b32_e32 v208, 16, v195
	v_and_b32_e32 v209, 0xffff0000, v195
	v_lshlrev_b32_e32 v210, 16, v193
	v_and_b32_e32 v211, 0xffff0000, v193
	s_waitcnt vmcnt(1)
	v_pk_fma_f32 v[210:211], v[244:245], v[210:211], v[166:167]
	v_pk_fma_f32 v[208:209], v[242:243], v[208:209], v[202:203]
	global_load_dwordx4 v[242:245], v[160:161], off offset:64
	s_nop 0
	global_store_dwordx4 v[176:177], v[208:211], off offset:1280
	v_cndmask_b32_e32 v233, v180, v154, vcc
	v_lshl_add_u64 v[154:155], s[72:73], 0, v[168:169]
	global_load_dwordx4 v[238:241], v[154:155], off
	ds_write_b128 v233, v[208:211] offset:768
	v_and_b32_e32 v195, 0xffff0000, v192
	s_waitcnt vmcnt(0)
	v_pk_mul_f32 v[208:209], v[204:205], v[240:241]
	v_pk_mul_f32 v[210:211], v[206:207], v[238:239]
	v_pk_mul_f32 v[166:167], v[208:209], v[208:209]
	v_pk_mul_f32 v[202:203], v[210:211], v[210:211]
	s_nop 0
	v_pk_mov_b32 v[238:239], v[202:203], v[166:167] op_sel:[1,0]
	v_mov_b32_e32 v203, v167
	v_pk_add_f32 v[166:167], v[238:239], v[202:203]
	global_load_dwordx4 v[238:241], v[158:159], off offset:2112
	v_lshlrev_b32_e32 v202, 16, v201
	v_and_b32_e32 v203, 0xffff0000, v201
	v_and_b32_e32 v201, 0xffff0000, v156
	v_lshlrev_b32_e32 v156, 16, v157
	v_and_b32_e32 v157, 0xffff0000, v157
	v_pk_mul_f32 v[156:157], v[244:245], v[156:157]
	v_pk_mul_f32 v[200:201], v[242:243], v[200:201]
	global_load_dwordx4 v[242:245], v[186:187], off offset:64
	s_waitcnt vmcnt(1)
	v_pk_fma_f32 v[156:157], v[240:241], v[250:251], v[156:157]
	v_pk_fma_f32 v[200:201], v[238:239], v[202:203], v[200:201]
	global_load_dwordx4 v[238:241], v[184:185], off offset:2112
	v_lshlrev_b32_e32 v202, 16, v194
	v_and_b32_e32 v203, 0xffff0000, v194
	v_lshlrev_b32_e32 v194, 16, v192
	v_pk_fma_f32 v[192:193], v[248:249], v[194:195], v[156:157]
	global_load_dwordx4 v[248:251], v[170:171], off offset:64
	v_pk_fma_f32 v[194:195], v[246:247], v[202:203], v[200:201]
	v_lshlrev_b32_e32 v156, 16, v189
	v_and_b32_e32 v157, 0xffff0000, v189
	v_lshlrev_b32_e32 v246, 16, v188
	v_and_b32_e32 v247, 0xffff0000, v188
	v_lshlrev_b32_e32 v188, 16, v254
	v_and_b32_e32 v189, 0xffff0000, v254
	v_lshlrev_b32_e32 v144, 16, v255
	v_and_b32_e32 v145, 0xffff0000, v255
	s_waitcnt vmcnt(1)
	v_pk_mul_f32 v[144:145], v[240:241], v[144:145]
	v_pk_mul_f32 v[188:189], v[238:239], v[188:189]
	global_load_dwordx4 v[238:241], v[154:155], off offset:64
	s_waitcnt vmcnt(1)
	v_pk_fma_f32 v[144:145], v[250:251], v[246:247], v[144:145]
	v_pk_fma_f32 v[156:157], v[248:249], v[156:157], v[188:189]
	global_load_dwordx4 v[246:249], v[162:163], off offset:2176
	v_lshlrev_b32_e32 v188, 16, v179
	v_and_b32_e32 v189, 0xffff0000, v179
	v_lshlrev_b32_e32 v200, 16, v178
	v_and_b32_e32 v201, 0xffff0000, v178
	v_pk_fma_f32 v[202:203], v[244:245], v[200:201], v[144:145]
	v_pk_fma_f32 v[200:201], v[242:243], v[188:189], v[156:157]
	global_load_dwordx4 v[242:245], v[160:161], off offset:128
	s_nop 0
	global_store_dwordx4 v[176:177], v[200:203], off offset:1344
	s_nop 0
	v_add_u32_e32 v144, 0x2240, v234
	v_cndmask_b32_e32 v232, v180, v144, vcc
	ds_write_b128 v232, v[200:203] offset:768
	s_waitcnt vmcnt(3)
	v_pk_mul_f32 v[200:201], v[192:193], v[240:241]
	v_pk_mul_f32 v[202:203], v[194:195], v[238:239]
	global_load_dwordx4 v[238:241], v[158:159], off offset:2176
	s_nop 0
	s_nop 0
	v_pk_mul_f32 v[144:145], v[200:201], v[200:201]
	v_pk_mul_f32 v[156:157], v[202:203], v[202:203]
	s_nop 0
	v_pk_mov_b32 v[178:179], v[156:157], v[144:145] op_sel:[1,0]
	v_mov_b32_e32 v157, v145
	v_pk_add_f32 v[250:251], v[178:179], v[156:157]
	v_lshlrev_b32_e32 v178, 16, v148
	v_and_b32_e32 v179, 0xffff0000, v148
	v_lshlrev_b32_e32 v148, 16, v149
	v_and_b32_e32 v149, 0xffff0000, v149
	v_lshlrev_b32_e32 v144, 16, v199
	v_and_b32_e32 v145, 0xffff0000, v199
	v_lshlrev_b32_e32 v156, 16, v198
	v_and_b32_e32 v157, 0xffff0000, v198
	s_waitcnt vmcnt(2)
	v_pk_mul_f32 v[148:149], v[244:245], v[148:149]
	v_pk_mul_f32 v[178:179], v[242:243], v[178:179]
	global_load_dwordx4 v[242:245], v[184:185], off offset:2176
	s_waitcnt vmcnt(1)
; #define LAS __attribute__((address_space(3)))
; __device__ __forceinline__ float shx(float v, int o, int lane) { return __builtin_bit_cast(float, __builtin_amdgcn_ds_bpermute((lane ^ o) << 2, __builtin_bit_cast(int, v))); }
; #define lane LANE_()
; template <int MODE>
; __device__ __forceinline__ void scan_prologue(const ScanP& P, int m0, int seqbase, int T, int h, int d, float* slab, LAS float* lw, float* bon, int lane) {
;     ...
;     for (int n = 0; n < 4; ++n) { const int c = 16 * n + 4 * fq, col = h * 64 + c;
;         k4[n] = CONV3_(pk_, 1);
;         if (MODE != 1) { const f32x4 v4 = CONV3_(pv_, 2); *(f32x4*)(srow + 320 + c) = v4; LAS float* xsel = (fr == (d ? 15 : 0)) ? lw + 2048 + c : lw + 2304 + lane * 4; *(LAS f32x4*)(xsel + 192) = v4; }
;         if (MODE == 2) { r4[n] = CONV3_(pr_, 0); *(LAS f32x4*)(lw + 1024 + fr * 64 + c) = r4[n]; }
;         kk4[n] = k4[n] * *(const f32x4*)(P.k_k + col);
;         ss += (kk4[n].x * kk4[n].x + kk4[n].y * kk4[n].y) + (kk4[n].z * kk4[n].z + kk4[n].w * kk4[n].w); }
;     ...
;     ss += shx(ss, 16, lane); ss += shx(ss, 32, lane);
;     const float rs = __builtin_amdgcn_rsqf(ss + 1e-12f);
	v_pk_fma_f32 v[148:149], v[240:241], v[156:157], v[148:149]
	v_pk_fma_f32 v[144:145], v[238:239], v[144:145], v[178:179]
	global_load_dwordx4 v[238:241], v[170:171], off offset:128
	v_lshlrev_b32_e32 v156, 16, v191
	v_and_b32_e32 v157, 0xffff0000, v191
	v_lshlrev_b32_e32 v178, 16, v190
	v_and_b32_e32 v179, 0xffff0000, v190
	v_pk_fma_f32 v[188:189], v[248:249], v[178:179], v[148:149]
	v_pk_fma_f32 v[190:191], v[246:247], v[156:157], v[144:145]
	global_load_dwordx4 v[246:249], v[186:187], off offset:128
	v_lshlrev_b32_e32 v156, 16, v146
	v_and_b32_e32 v157, 0xffff0000, v146
	v_lshlrev_b32_e32 v146, 16, v147
	v_and_b32_e32 v147, 0xffff0000, v147
	v_lshlrev_b32_e32 v144, 16, v197
	v_and_b32_e32 v145, 0xffff0000, v197
	v_lshlrev_b32_e32 v148, 16, v196
	v_and_b32_e32 v149, 0xffff0000, v196
	v_lshlrev_b32_e32 v178, 16, v213
	v_and_b32_e32 v179, 0xffff0000, v213
	s_waitcnt vmcnt(2)
	v_pk_mul_f32 v[146:147], v[244:245], v[146:147]
	v_pk_mul_f32 v[156:157], v[242:243], v[156:157]
	global_load_dwordx4 v[242:245], v[154:155], off offset:128
	s_waitcnt vmcnt(2)
	v_pk_fma_f32 v[146:147], v[240:241], v[148:149], v[146:147]
	v_pk_fma_f32 v[144:145], v[238:239], v[144:145], v[156:157]
	global_load_dwordx4 v[238:241], v[158:159], off offset:2240
	v_lshlrev_b32_e32 v148, 16, v183
	v_and_b32_e32 v149, 0xffff0000, v183
	v_lshlrev_b32_e32 v156, 16, v182
	v_and_b32_e32 v157, 0xffff0000, v182
	s_waitcnt vmcnt(2)
	v_pk_fma_f32 v[146:147], v[248:249], v[156:157], v[146:147]
	v_pk_fma_f32 v[144:145], v[246:247], v[148:149], v[144:145]
	global_load_dwordx4 v[246:249], v[160:161], off offset:192
	v_add_u32_e32 v148, 0x2280, v234
	global_store_dwordx4 v[176:177], v[144:147], off offset:1408
	v_cndmask_b32_e32 v230, v180, v148, vcc
	ds_write_b128 v230, v[144:147] offset:768
	s_nop 0
	v_lshlrev_b32_e32 v182, 16, v150
	v_and_b32_e32 v183, 0xffff0000, v150
	v_lshlrev_b32_e32 v150, 16, v151
	v_and_b32_e32 v151, 0xffff0000, v151
	v_lshlrev_b32_e32 v148, 16, v214
	v_and_b32_e32 v149, 0xffff0000, v214
	s_waitcnt vmcnt(3)
	v_pk_mul_f32 v[196:197], v[188:189], v[244:245]
	v_pk_mul_f32 v[198:199], v[190:191], v[242:243]
	global_load_dwordx4 v[242:245], v[162:163], off offset:2240
	s_nop 0
	s_nop 0
	s_nop 0
	s_nop 0
	s_nop 0
	s_waitcnt vmcnt(2)
	v_pk_mul_f32 v[150:151], v[248:249], v[150:151]
	v_pk_mul_f32 v[156:157], v[246:247], v[182:183]
	global_load_dwordx4 v[246:249], v[170:171], off offset:192
	v_pk_fma_f32 v[146:147], v[240:241], v[178:179], v[150:151]
	v_pk_fma_f32 v[144:145], v[238:239], v[148:149], v[156:157]
	global_load_dwordx4 v[238:241], v[184:185], off offset:2240
	global_load_dwordx4 v[156:159], v[186:187], off offset:192
	v_lshlrev_b32_e32 v148, 16, v216
	v_and_b32_e32 v149, 0xffff0000, v216
	v_lshlrev_b32_e32 v150, 16, v215
	v_and_b32_e32 v151, 0xffff0000, v215
	s_waitcnt vmcnt(3)
	v_pk_fma_f32 v[178:179], v[244:245], v[150:151], v[146:147]
	v_pk_fma_f32 v[182:183], v[242:243], v[148:149], v[144:145]
	global_load_dwordx4 v[242:245], v[154:155], off offset:192
	v_lshlrev_b32_e32 v170, 16, v152
	v_and_b32_e32 v171, 0xffff0000, v152
	v_lshlrev_b32_e32 v152, 16, v153
	v_and_b32_e32 v153, 0xffff0000, v153
	v_lshlrev_b32_e32 v160, 16, v229
	v_and_b32_e32 v161, 0xffff0000, v229
	v_lshlrev_b32_e32 v162, 16, v217
	v_and_b32_e32 v163, 0xffff0000, v217
	s_waitcnt vmcnt(2)
	v_pk_mul_f32 v[150:151], v[240:241], v[152:153]
	v_pk_mul_f32 v[148:149], v[238:239], v[170:171]
	v_pk_fma_f32 v[146:147], v[248:249], v[162:163], v[150:151]
	v_pk_fma_f32 v[144:145], v[246:247], v[160:161], v[148:149]
	v_lshlrev_b32_e32 v148, 16, v236
	v_and_b32_e32 v149, 0xffff0000, v236
	v_lshlrev_b32_e32 v150, 16, v235
	v_and_b32_e32 v151, 0xffff0000, v235
	s_waitcnt vmcnt(1)
	v_pk_fma_f32 v[146:147], v[158:159], v[150:151], v[146:147]
	v_pk_fma_f32 v[144:145], v[156:157], v[148:149], v[144:145]
	v_add_u32_e32 v148, 0x22c0, v234
	global_store_dwordx4 v[176:177], v[144:147], off offset:1472
	v_cndmask_b32_e32 v229, v180, v148, vcc
	ds_write_b128 v229, v[144:147] offset:768
	s_nop 0
	v_lshl_or_b32 v180, v231, 6, s89
	s_waitcnt vmcnt(1)
	v_pk_mul_f32 v[186:187], v[182:183], v[242:243]
	v_pk_mul_f32 v[184:185], v[178:179], v[244:245]
	v_mul_f32_e32 v146, v186, v186
	v_pk_add_f32 v[144:145], v[166:167], v[166:167] op_sel:[0,1] op_sel_hi:[1,0]
	v_mul_f32_e32 v148, v187, v187
	v_mov_b32_e32 v145, v146
	v_pk_add_f32 v[146:147], v[250:251], v[250:251] op_sel:[0,1] op_sel_hi:[1,0]
	v_mul_f32_e32 v149, v184, v184
	v_mov_b32_e32 v147, v148
	v_pk_add_f32 v[144:145], v[144:145], v[146:147]
	v_mul_f32_e32 v146, v199, v199
	v_pk_fma_f32 v[146:147], v[198:199], v[198:199], v[146:147] op_sel_hi:[1,1,0]
	v_mul_f32_e32 v148, v197, v197
	v_mul_f32_e32 v150, v185, v185
	v_mov_b32_e32 v147, v149
	v_pk_fma_f32 v[148:149], v[196:197], v[196:197], v[148:149] op_sel_hi:[1,1,0]
	s_nop 0
	v_mov_b32_e32 v149, v150
	v_pk_add_f32 v[146:147], v[146:147], v[148:149]
	s_nop 0
	v_pk_add_f32 v[144:145], v[144:145], v[146:147]
	s_nop 0
	v_add_f32_e32 v144, v144, v145
	v_lshlrev_b32_e32 v145, 2, v212
	v_xor_b32_e32 v146, 64, v145
	ds_bpermute_b32 v146, v146, v144
	v_xor_b32_e32 v145, 0x80, v145
	s_waitcnt lgkmcnt(0)
	v_add_f32_e32 v144, v144, v146
	ds_bpermute_b32 v145, v145, v144
	s_waitcnt lgkmcnt(0)
; __device__ __forceinline__ unsigned pk2(float lo, float hi) { const f2 v = {lo, hi}; return __builtin_bit_cast(unsigned, __builtin_convertvector(v, bf16x2_hw)); }
; __device__ __forceinline__ float tanhf_(float x) { return 1.0f - 2.0f * __builtin_amdgcn_rcpf(1.0f + __builtin_amdgcn_exp2f(2.8853900817779268f * x)); }
; __device__ __forceinline__ float shx(float v, int o, int lane) { return __builtin_bit_cast(float, __builtin_amdgcn_ds_bpermute((lane ^ o) << 2, __builtin_bit_cast(int, v))); }
; #define lane LANE_()
; template <int MODE>
; __device__ __forceinline__ void scan_prologue(const ScanP& P, int m0, int seqbase, int T, int h, int d, float* slab, LAS float* lw, float* bon, int lane) {
;     ...
;     ss += shx(ss, 16, lane); ss += shx(ss, 32, lane);
;     const float rs = __builtin_amdgcn_rsqf(ss + 1e-12f);
;     f32x4 Dw[4], Da[4];
; #pragma unroll
;     for (int n = 0; n < 4; ++n) { Dw[n] = (f32x4){0.f, 0.f, 0.f, 0.f}; Da[n] = (f32x4){0.f, 0.f, 0.f, 0.f}; }
; #pragma unroll
;     for (int ks = 0; ks < 2; ++ks) {
;         const v4u xw = xw_[ks]; const bf16x8 xa = xa_[ks];
;         v4u tw;
; #pragma unroll
;         for (int e = 0; e < 4; ++e) tw[e] = pk2(tanhf_(bflo(xw[e])), tanhf_(bfhi(xw[e])));
;         const bf16x8 twv = __builtin_bit_cast(bf16x8, tw);
; #pragma unroll
;         for (int n = 0; n < 4; ++n) { const size_t wo = (size_t)(h * 64 + 16 * n + fr) * 64 + ks * 32 + 8 * fq;
;             Dw[n] = __builtin_amdgcn_mfma_f32_16x16x32_bf16(*(const bf16x8*)(P.upw + wo), twv, Dw[n], 0, 0, 0);
;             Da[n] = __builtin_amdgcn_mfma_f32_16x16x32_bf16(*(const bf16x8*)(P.upa + wo), xa, Da[n], 0, 0, 0); }
;     }
	v_add_f32_e32 v144, v144, v145
	v_add_f32_e32 v212, 0x2b8cbccc, v144
	v_lshlrev_b32_e32 v144, 16, v140
	v_and_b32_e32 v140, 0xffff0000, v140
	v_mul_f32_e32 v140, 0x4038aa3b, v140
	v_exp_f32_e32 v140, v140
	v_mul_f32_e32 v144, 0x4038aa3b, v144
	v_exp_f32_e32 v144, v144
	v_add_f32_e32 v140, 1.0, v140
	v_rcp_f32_e32 v145, v140
	v_lshlrev_b32_e32 v140, 16, v141
	v_and_b32_e32 v141, 0xffff0000, v141
	v_mul_f32_e32 v140, 0x4038aa3b, v140
	v_mul_f32_e32 v141, 0x4038aa3b, v141
	v_exp_f32_e32 v140, v140
	v_exp_f32_e32 v141, v141
	v_add_f32_e32 v144, 1.0, v144
	v_rcp_f32_e32 v144, v144
	v_add_f32_e32 v140, 1.0, v140
	v_add_f32_e32 v141, 1.0, v141
	v_rcp_f32_e32 v140, v140
	v_rcp_f32_e32 v141, v141
	v_pk_fma_f32 v[144:145], v[144:145], 2.0, 1.0 op_sel_hi:[1,0,0] neg_lo:[1,0,0] neg_hi:[1,0,0]
	v_pk_fma_f32 v[140:141], v[140:141], 2.0, 1.0 op_sel_hi:[1,0,0] neg_lo:[1,0,0] neg_hi:[1,0,0]
	s_nop 0
	v_cvt_pk_bf16_f32 v153, v140, v141
	v_lshlrev_b32_e32 v140, 16, v142
	v_and_b32_e32 v141, 0xffff0000, v142
	v_mul_f32_e32 v140, 0x4038aa3b, v140
	v_mul_f32_e32 v141, 0x4038aa3b, v141
	v_exp_f32_e32 v140, v140
	v_exp_f32_e32 v141, v141
	v_cvt_pk_bf16_f32 v152, v144, v145
	v_add_f32_e32 v140, 1.0, v140
	v_add_f32_e32 v141, 1.0, v141
	v_rcp_f32_e32 v140, v140
	v_rcp_f32_e32 v141, v141
	s_nop 0
	v_pk_fma_f32 v[140:141], v[140:141], 2.0, 1.0 op_sel_hi:[1,0,0] neg_lo:[1,0,0] neg_hi:[1,0,0]
	s_nop 0
	v_cvt_pk_bf16_f32 v154, v140, v141
	v_lshlrev_b32_e32 v140, 16, v143
	v_and_b32_e32 v141, 0xffff0000, v143
	v_mul_f32_e32 v140, 0x4038aa3b, v140
	v_mul_f32_e32 v141, 0x4038aa3b, v141
	v_exp_f32_e32 v140, v140
	v_exp_f32_e32 v141, v141
	v_add_f32_e32 v140, 1.0, v140
	v_add_f32_e32 v141, 1.0, v141
	v_rcp_f32_e32 v140, v140
	v_rcp_f32_e32 v141, v141
	s_nop 0
	v_pk_fma_f32 v[140:141], v[140:141], 2.0, 1.0 op_sel_hi:[1,0,0] neg_lo:[1,0,0] neg_hi:[1,0,0]
	s_nop 0
	v_cvt_pk_bf16_f32 v155, v140, v141
	v_lshl_add_u64 v[140:141], v[180:181], 0, v[164:165]
	v_lshlrev_b64 v[144:145], 1, v[140:141]
	v_lshl_add_u64 v[170:171], s[78:79], 0, v[144:145]
	global_load_dwordx4 v[246:249], v[170:171], off
	global_load_dwordx4 v[156:159], v[170:171], off offset:2048
	s_waitcnt vmcnt(0)
	v_mfma_f32_16x16x32_bf16 v[160:163], v[156:159], v[136:139], 0
	v_or_b32_e32 v156, 0x800, v180
	v_mov_b32_e32 v157, v181
	v_lshl_add_u64 v[156:157], v[156:157], 0, v[164:165]
	v_lshlrev_b64 v[236:237], 1, v[156:157]
	v_lshl_add_u64 v[166:167], s[74:75], 0, v[144:145]
	global_load_dwordx4 v[140:143], v[166:167], off
	global_load_dwordx4 v[148:151], v[166:167], off offset:2048
	v_lshl_add_u64 v[156:157], s[74:75], 0, v[236:237]
	global_load_dwordx4 v[144:147], v[156:157], off
	s_nop 0
	s_nop 0
	s_nop 0
	s_nop 0
	s_nop 0
	s_waitcnt vmcnt(0)
	v_mfma_f32_16x16x32_bf16 v[214:217], v[144:147], v[152:155], 0
	v_lshl_add_u64 v[156:157], s[78:79], 0, v[236:237]
	global_load_dwordx4 v[156:159], v[156:157], off
	s_waitcnt vmcnt(0)
	v_mfma_f32_16x16x32_bf16 v[236:239], v[156:159], v[136:139], 0
	v_or_b32_e32 v156, 0xc00, v180
	v_mov_b32_e32 v157, v181
	v_lshl_add_u64 v[156:157], v[156:157], 0, v[164:165]
	v_lshlrev_b64 v[244:245], 1, v[156:157]
	v_lshl_add_u64 v[156:157], s[74:75], 0, v[244:245]
	global_load_dwordx4 v[156:159], v[156:157], off
	v_mfma_f32_16x16x32_bf16 v[140:143], v[140:143], v[152:155], 0
	v_mfma_f32_16x16x32_bf16 v[148:151], v[148:151], v[152:155], 0
	s_waitcnt vmcnt(0)
	v_mfma_f32_16x16x32_bf16 v[240:243], v[156:159], v[152:155], 0
	global_load_dwordx4 v[156:159], v[166:167], off offset:64
	v_lshl_add_u64 v[152:153], s[78:79], 0, v[244:245]
	global_load_dwordx4 v[152:155], v[152:153], off
	v_mfma_f32_16x16x32_bf16 v[144:147], v[246:249], v[136:139], 0
	global_load_dwordx4 v[248:251], v[170:171], off offset:64
	s_waitcnt vmcnt(1)
	v_mfma_f32_16x16x32_bf16 v[244:247], v[152:155], v[136:139], 0
	v_lshlrev_b32_e32 v136, 16, v128
	v_and_b32_e32 v128, 0xffff0000, v128
	v_mul_f32_e32 v136, 0x4038aa3b, v136
	v_mul_f32_e32 v128, 0x4038aa3b, v128
	v_exp_f32_e32 v136, v136
	v_exp_f32_e32 v128, v128
	v_add_f32_e32 v136, 1.0, v136
	v_add_f32_e32 v128, 1.0, v128
	v_rcp_f32_e32 v136, v136
	v_rcp_f32_e32 v137, v128
	s_nop 0
	v_pk_fma_f32 v[136:137], v[136:137], 2.0, 1.0 op_sel_hi:[1,0,0] neg_lo:[1,0,0] neg_hi:[1,0,0]
	s_nop 0
	v_cvt_pk_bf16_f32 v128, v136, v137
	v_lshlrev_b32_e32 v136, 16, v129
	v_and_b32_e32 v129, 0xffff0000, v129
	v_mul_f32_e32 v136, 0x4038aa3b, v136
	v_mul_f32_e32 v129, 0x4038aa3b, v129
	v_exp_f32_e32 v136, v136
	v_exp_f32_e32 v129, v129
	v_add_f32_e32 v136, 1.0, v136
	v_add_f32_e32 v129, 1.0, v129
	v_rcp_f32_e32 v136, v136
	v_rcp_f32_e32 v137, v129
	s_nop 0
	v_pk_fma_f32 v[136:137], v[136:137], 2.0, 1.0 op_sel_hi:[1,0,0] neg_lo:[1,0,0] neg_hi:[1,0,0]
	s_nop 0
	v_cvt_pk_bf16_f32 v129, v136, v137
	v_lshlrev_b32_e32 v136, 16, v130
	v_and_b32_e32 v130, 0xffff0000, v130
	v_mul_f32_e32 v136, 0x4038aa3b, v136
	v_mul_f32_e32 v130, 0x4038aa3b, v130
	v_exp_f32_e32 v136, v136
	v_exp_f32_e32 v130, v130
	v_add_f32_e32 v136, 1.0, v136
	v_add_f32_e32 v130, 1.0, v130
	v_rcp_f32_e32 v136, v136
	v_rcp_f32_e32 v137, v130
	s_nop 0
	v_pk_fma_f32 v[136:137], v[136:137], 2.0, 1.0 op_sel_hi:[1,0,0] neg_lo:[1,0,0] neg_hi:[1,0,0]
	s_nop 0
	v_cvt_pk_bf16_f32 v130, v136, v137
	v_lshlrev_b32_e32 v136, 16, v131
	v_and_b32_e32 v131, 0xffff0000, v131
	v_mul_f32_e32 v136, 0x4038aa3b, v136
	v_mul_f32_e32 v131, 0x4038aa3b, v131
	v_exp_f32_e32 v136, v136
	v_exp_f32_e32 v131, v131
	v_add_f32_e32 v136, 1.0, v136
	v_add_f32_e32 v131, 1.0, v131
	v_rcp_f32_e32 v136, v136
	v_rcp_f32_e32 v137, v131
	s_nop 0
	v_pk_fma_f32 v[136:137], v[136:137], 2.0, 1.0 op_sel_hi:[1,0,0] neg_lo:[1,0,0] neg_hi:[1,0,0]
	s_nop 0
	v_cvt_pk_bf16_f32 v131, v136, v137
	global_load_dwordx4 v[136:139], v[166:167], off offset:2112
	s_nop 0
	v_mfma_f32_16x16x32_bf16 v[152:155], v[156:159], v[128:131], v[140:143]
	global_load_dwordx4 v[140:143], v[170:171], off offset:2112
	s_nop 0
	s_waitcnt vmcnt(2)
; #define LAS __attribute__((address_space(3)))
; __device__ __forceinline__ float sigmoidf_(float x) { return __builtin_amdgcn_rcpf(1.0f + __builtin_amdgcn_exp2f(-1.4426950408889634f * x)); }
; #define lane LANE_()
; template <int MODE>
; __device__ __forceinline__ void scan_prologue(const ScanP& P, int m0, int seqbase, int T, int h, int d, float* slab, LAS float* lw, float* bon, int lane) {
;     ...
;     float bp = 0.f;
; #pragma unroll
;     for (int n = 0; n < 4; ++n) { const int c = 16 * n + 4 * fq, col = h * 64 + c;
;         const f32x4 w0 = *(const f32x4*)(P.w0 + col), a0 = *(const f32x4*)(P.a0 + col), ka = *(const f32x4*)(P.k_a + col);
;         f32x4 wv, bv, kd, av;
; #pragma unroll
;         for (int i = 0; i < 4; ++i) { const float ic = sigmoidf_(Da[n][i] + a0[i]);
;             wv[i] = __builtin_amdgcn_exp2f(-DECAY_SCALE * 1.4426950408889634f * sigmoidf_(Dw[n][i] + w0[i]));
;             const float kk = kk4[n][i] * rs; av[i] = -kk; bv[i] = kk * ic; kd[i] = k4[n][i] * (1.0f + (ic - 1.0f) * ka[i]); }
;         *(LAS f32x4*)(lw + fr * 64 + c) = av; *(LAS f32x4*)(lw + 3072 + fr * 64 + c) = wv; *(LAS f32x4*)(lw + (MODE == 3 ? 1024 : 4096) + fr * 64 + c) = bv;
;         if (MODE != 1) *(f32x4*)(srow + 192 + c) = kd;
;         { LAS float* xsel = (fr == (d ? 15 : 0)) ? lw + 2048 + c : lw + 2304 + lane * 4;
;           if (MODE != 1) *(LAS f32x4*)(xsel + 128) = kd; }
	v_mfma_f32_16x16x32_bf16 v[156:159], v[248:251], v[132:135], v[144:147]
	s_nop 0
	s_waitcnt vmcnt(1)
	v_mfma_f32_16x16x32_bf16 v[144:147], v[136:139], v[128:131], v[148:151]
	s_nop 0
	s_waitcnt vmcnt(0)
	v_mfma_f32_16x16x32_bf16 v[148:151], v[140:143], v[132:135], v[160:163]
	v_or_b32_e32 v136, 0x820, v180
	v_mov_b32_e32 v137, v181
	v_or_b32_e32 v180, 0xc20, v180
	v_lshl_add_u64 v[136:137], v[136:137], 0, v[164:165]
	v_lshl_add_u64 v[160:161], v[180:181], 0, v[164:165]
	v_lshlrev_b64 v[140:141], 1, v[136:137]
	v_lshlrev_b64 v[164:165], 1, v[160:161]
	v_lshl_add_u64 v[136:137], s[74:75], 0, v[140:141]
	global_load_dwordx4 v[248:251], v[136:137], off
	v_lshl_add_u64 v[160:161], s[74:75], 0, v[164:165]
	s_nop 0
	v_lshl_add_u64 v[140:141], s[78:79], 0, v[140:141]
	global_load_dwordx4 v[160:163], v[160:161], off
	v_rsq_f32_e32 v180, v212
	global_load_dwordx4 v[140:143], v[140:141], off
	s_waitcnt vmcnt(2)
	v_mfma_f32_16x16x32_bf16 v[136:139], v[248:251], v[128:131], v[214:217]
	s_nop 2
	v_lshl_add_u64 v[214:215], s[76:77], 0, v[168:169]
	global_load_dwordx4 v[248:251], v[214:215], off
	v_lshl_add_u64 v[212:213], s[10:11], 0, v[168:169]
	v_lshl_add_u64 v[216:217], s[6:7], 0, v[168:169]
	global_load_dwordx4 v[168:171], v[216:217], off
	s_waitcnt vmcnt(3)
	v_mfma_f32_16x16x32_bf16 v[128:131], v[160:163], v[128:131], v[240:243]
	global_load_dwordx4 v[240:243], v[212:213], off
	v_lshl_add_u64 v[160:161], s[78:79], 0, v[164:165]
	global_load_dwordx4 v[160:163], v[160:161], off
	s_nop 0
	s_nop 0
	s_waitcnt vmcnt(4)
	v_mfma_f32_16x16x32_bf16 v[140:143], v[140:143], v[132:135], v[236:239]
	global_load_dwordx4 v[236:239], v[216:217], off offset:64
	s_nop 0
	s_waitcnt vmcnt(4)
	v_add_f32_e32 v156, v156, v248
	s_waitcnt vmcnt(1)
	v_mfma_f32_16x16x32_bf16 v[132:135], v[160:163], v[132:135], v[244:247]
	global_load_dwordx4 v[244:247], v[214:215], off offset:64
	s_nop 0
	v_add_f32_e32 v158, v158, v250
	v_mul_f32_e32 v156, 0xbfb8aa3b, v156
	v_mul_f32_e32 v158, 0xbfb8aa3b, v158
	v_exp_f32_e32 v156, v156
	v_exp_f32_e32 v158, v158
	v_add_f32_e32 v156, 1.0, v156
	v_add_f32_e32 v158, 1.0, v158
	v_rcp_f32_e32 v164, v156
	v_add_f32_e32 v156, v157, v249
	v_rcp_f32_e32 v166, v158
	v_add_f32_e32 v158, v159, v251
	global_load_dwordx4 v[248:251], v[212:213], off offset:64
	v_mul_f32_e32 v156, 0xbfb8aa3b, v156
	v_mul_f32_e32 v158, 0xbfb8aa3b, v158
	v_exp_f32_e32 v156, v156
	v_exp_f32_e32 v158, v158
	v_add_f32_e32 v156, 1.0, v156
	v_add_f32_e32 v158, 1.0, v158
	v_rcp_f32_e32 v165, v156
	v_rcp_f32_e32 v167, v158
	v_add_f32_e32 v152, v152, v240
	v_add_f32_e32 v153, v153, v241
	v_add_f32_e32 v154, v154, v242
	v_add_f32_e32 v155, v155, v243
	global_load_dwordx4 v[240:243], v[212:213], off offset:128
	v_mul_f32_e32 v152, 0xbfb8aa3b, v152
	v_mul_f32_e32 v153, 0xbfb8aa3b, v153
	v_mul_f32_e32 v154, 0xbfb8aa3b, v154
	v_mul_f32_e32 v155, 0xbfb8aa3b, v155
	v_exp_f32_e32 v152, v152
	v_exp_f32_e32 v153, v153
	v_exp_f32_e32 v154, v154
	v_exp_f32_e32 v155, v155
	v_add_f32_e32 v152, 1.0, v152
	v_add_f32_e32 v153, 1.0, v153
	v_add_f32_e32 v154, 1.0, v154
	v_add_f32_e32 v155, 1.0, v155
	v_rcp_f32_e32 v152, v152
	v_rcp_f32_e32 v153, v153
	v_rcp_f32_e32 v154, v154
	v_rcp_f32_e32 v155, v155
	v_mul_f32_e32 v152, 0xbf60028a, v152
	v_mul_f32_e32 v153, 0xbf60028a, v153
	v_pk_mul_f32 v[160:161], v[210:211], v[180:181] op_sel_hi:[1,0]
	v_mul_f32_e32 v154, 0xbf60028a, v154
	v_mul_f32_e32 v155, 0xbf60028a, v155
	v_pk_mul_f32 v[162:163], v[208:209], v[180:181] op_sel_hi:[1,0]
	global_load_dwordx4 v[208:211], v[214:215], off offset:128
	v_exp_f32_e32 v152, v152
	v_exp_f32_e32 v153, v153
	v_xor_b32_e32 v157, 0x80000000, v161
	v_xor_b32_e32 v156, 0x80000000, v160
	v_exp_f32_e32 v154, v154
	v_exp_f32_e32 v155, v155
	v_xor_b32_e32 v158, 0x80000000, v162
	v_xor_b32_e32 v159, 0x80000000, v163
	v_pk_mul_f32 v[160:161], v[160:161], v[164:165]
	v_pk_mul_f32 v[162:163], v[162:163], v[166:167]
	v_pk_add_f32 v[166:167], v[166:167], -1.0 op_sel_hi:[1,0]
	v_pk_add_f32 v[164:165], v[164:165], -1.0 op_sel_hi:[1,0]
	v_pk_fma_f32 v[166:167], v[170:171], v[166:167], 1.0 op_sel_hi:[1,1,0]
	v_pk_fma_f32 v[164:165], v[168:169], v[164:165], 1.0 op_sel_hi:[1,1,0]
	v_pk_mul_f32 v[168:169], v[204:205], v[166:167]
	v_pk_mul_f32 v[166:167], v[206:207], v[164:165]
	global_load_dwordx4 v[204:207], v[216:217], off offset:128
	v_lshl_add_u32 v164, v231, 8, v234
	v_lshl_add_u32 v164, v231, 4, v164
	ds_write_b128 v164, v[156:159]
	ds_write_b128 v164, v[152:155] offset:11520
	ds_write_b128 v164, v[160:163] offset:4352
	global_store_dwordx4 v[176:177], v[166:169], off offset:768
	ds_write_b128 v233, v[166:169] offset:512
	global_load_dwordx4 v[166:169], v[216:217], off offset:192
	s_nop 0
	s_nop 0
	s_nop 0
	s_waitcnt vmcnt(6)
	v_add_f32_e32 v148, v148, v244
	s_waitcnt vmcnt(5)
; #define LAS __attribute__((address_space(3)))
; __device__ __forceinline__ float sigmoidf_(float x) { return __builtin_amdgcn_rcpf(1.0f + __builtin_amdgcn_exp2f(-1.4426950408889634f * x)); }
; #define lane LANE_()
; template <int MODE>
; __device__ __forceinline__ void scan_prologue(const ScanP& P, int m0, int seqbase, int T, int h, int d, float* slab, LAS float* lw, float* bon, int lane) {
;     ...
;     for (int n = 0; n < 4; ++n) { const int c = 16 * n + 4 * fq, col = h * 64 + c;
;         const f32x4 w0 = *(const f32x4*)(P.w0 + col), a0 = *(const f32x4*)(P.a0 + col), ka = *(const f32x4*)(P.k_a + col);
;         f32x4 wv, bv, kd, av;
; #pragma unroll
;         for (int i = 0; i < 4; ++i) { const float ic = sigmoidf_(Da[n][i] + a0[i]);
;             wv[i] = __builtin_amdgcn_exp2f(-DECAY_SCALE * 1.4426950408889634f * sigmoidf_(Dw[n][i] + w0[i]));
;             const float kk = kk4[n][i] * rs; av[i] = -kk; bv[i] = kk * ic; kd[i] = k4[n][i] * (1.0f + (ic - 1.0f) * ka[i]); }
;         *(LAS f32x4*)(lw + fr * 64 + c) = av; *(LAS f32x4*)(lw + 3072 + fr * 64 + c) = wv; *(LAS f32x4*)(lw + (MODE == 3 ? 1024 : 4096) + fr * 64 + c) = bv;
;         if (MODE != 1) *(f32x4*)(srow + 192 + c) = kd;
;         { LAS float* xsel = (fr == (d ? 15 : 0)) ? lw + 2048 + c : lw + 2304 + lane * 4;
;           if (MODE != 1) *(LAS f32x4*)(xsel + 128) = kd; }
	v_add_f32_e32 v144, v144, v248
	v_add_f32_e32 v145, v145, v249
	v_add_f32_e32 v146, v146, v250
	v_add_f32_e32 v147, v147, v251
	global_load_dwordx4 v[248:251], v[214:215], off offset:192
	v_mul_f32_e32 v144, 0xbfb8aa3b, v144
	v_add_f32_e32 v149, v149, v245
	v_mul_f32_e32 v145, 0xbfb8aa3b, v145
	v_add_f32_e32 v150, v150, v246
	v_mul_f32_e32 v146, 0xbfb8aa3b, v146
	v_add_f32_e32 v151, v151, v247
	global_load_dwordx4 v[244:247], v[212:213], off offset:192
	v_mul_f32_e32 v147, 0xbfb8aa3b, v147
	v_mul_f32_e32 v148, 0xbfb8aa3b, v148
	v_exp_f32_e32 v144, v144
	v_mul_f32_e32 v149, 0xbfb8aa3b, v149
	v_exp_f32_e32 v145, v145
	v_mul_f32_e32 v150, 0xbfb8aa3b, v150
	v_exp_f32_e32 v146, v146
	v_mul_f32_e32 v151, 0xbfb8aa3b, v151
	v_exp_f32_e32 v147, v147
	v_exp_f32_e32 v148, v148
	v_exp_f32_e32 v149, v149
	v_exp_f32_e32 v150, v150
	v_exp_f32_e32 v151, v151
	v_add_f32_e32 v144, 1.0, v144
	v_add_f32_e32 v145, 1.0, v145
	v_add_f32_e32 v146, 1.0, v146
	v_add_f32_e32 v147, 1.0, v147
	v_add_f32_e32 v148, 1.0, v148
	v_rcp_f32_e32 v144, v144
	v_add_f32_e32 v149, 1.0, v149
	v_rcp_f32_e32 v145, v145
	v_add_f32_e32 v150, 1.0, v150
	v_rcp_f32_e32 v146, v146
	v_add_f32_e32 v151, 1.0, v151
	v_rcp_f32_e32 v147, v147
	v_rcp_f32_e32 v148, v148
	v_rcp_f32_e32 v149, v149
	v_rcp_f32_e32 v150, v150
	v_rcp_f32_e32 v151, v151
	v_mul_f32_e32 v144, 0xbf60028a, v144
	v_mul_f32_e32 v145, 0xbf60028a, v145
	v_pk_mul_f32 v[160:161], v[202:203], v[180:181] op_sel_hi:[1,0]
	v_mul_f32_e32 v146, 0xbf60028a, v146
	v_mul_f32_e32 v147, 0xbf60028a, v147
	v_pk_mul_f32 v[162:163], v[200:201], v[180:181] op_sel_hi:[1,0]
	v_exp_f32_e32 v144, v144
	v_exp_f32_e32 v145, v145
	v_xor_b32_e32 v157, 0x80000000, v161
	v_xor_b32_e32 v156, 0x80000000, v160
	v_exp_f32_e32 v146, v146
	v_exp_f32_e32 v147, v147
	v_xor_b32_e32 v158, 0x80000000, v162
	v_xor_b32_e32 v159, 0x80000000, v163
	v_pk_mul_f32 v[160:161], v[160:161], v[148:149]
	v_pk_mul_f32 v[162:163], v[162:163], v[150:151]
	v_pk_add_f32 v[150:151], v[150:151], -1.0 op_sel_hi:[1,0]
	v_pk_add_f32 v[148:149], v[148:149], -1.0 op_sel_hi:[1,0]
	v_pk_fma_f32 v[150:151], v[238:239], v[150:151], 1.0 op_sel_hi:[1,1,0]
	v_pk_fma_f32 v[148:149], v[236:237], v[148:149], 1.0 op_sel_hi:[1,1,0]
	v_pk_mul_f32 v[150:151], v[192:193], v[150:151]
	v_pk_mul_f32 v[148:149], v[194:195], v[148:149]
	ds_write_b128 v164, v[156:159] offset:64
	ds_write_b128 v164, v[144:147] offset:11584
	ds_write_b128 v164, v[160:163] offset:4416
	global_store_dwordx4 v[176:177], v[148:151], off offset:832
	ds_write_b128 v232, v[148:151] offset:512
	s_nop 0
	s_nop 0
	s_nop 0
	s_waitcnt vmcnt(7)
	v_add_f32_e32 v136, v136, v240
	s_waitcnt vmcnt(6)
	v_add_f32_e32 v140, v140, v208
	v_add_f32_e32 v142, v142, v210
	v_mul_f32_e32 v140, 0xbfb8aa3b, v140
	v_mul_f32_e32 v142, 0xbfb8aa3b, v142
	v_exp_f32_e32 v140, v140
	v_exp_f32_e32 v142, v142
	v_add_f32_e32 v137, v137, v241
	v_add_f32_e32 v138, v138, v242
	v_add_f32_e32 v140, 1.0, v140
	v_add_f32_e32 v142, 1.0, v142
	v_add_f32_e32 v139, v139, v243
	v_rcp_f32_e32 v152, v140
	v_mul_f32_e32 v136, 0xbfb8aa3b, v136
	v_add_f32_e32 v140, v141, v209
	v_mul_f32_e32 v137, 0xbfb8aa3b, v137
	v_rcp_f32_e32 v154, v142
	v_mul_f32_e32 v138, 0xbfb8aa3b, v138
	v_add_f32_e32 v142, v143, v211
	v_mul_f32_e32 v139, 0xbfb8aa3b, v139
	v_exp_f32_e32 v136, v136
	v_mul_f32_e32 v140, 0xbfb8aa3b, v140
	v_exp_f32_e32 v137, v137
	v_exp_f32_e32 v138, v138
	v_mul_f32_e32 v142, 0xbfb8aa3b, v142
	v_exp_f32_e32 v139, v139
	v_exp_f32_e32 v140, v140
	v_exp_f32_e32 v142, v142
	v_add_f32_e32 v136, 1.0, v136
	v_add_f32_e32 v137, 1.0, v137
	v_add_f32_e32 v138, 1.0, v138
	v_add_f32_e32 v139, 1.0, v139
	v_rcp_f32_e32 v136, v136
	v_add_f32_e32 v140, 1.0, v140
	v_rcp_f32_e32 v137, v137
	v_rcp_f32_e32 v138, v138
	v_add_f32_e32 v142, 1.0, v142
	v_rcp_f32_e32 v139, v139
	v_rcp_f32_e32 v153, v140
	v_rcp_f32_e32 v155, v142
	v_mul_f32_e32 v136, 0xbf60028a, v136
	v_mul_f32_e32 v137, 0xbf60028a, v137
	v_pk_mul_f32 v[148:149], v[198:199], v[180:181] op_sel_hi:[1,0]
	v_mul_f32_e32 v138, 0xbf60028a, v138
	v_mul_f32_e32 v139, 0xbf60028a, v139
	v_pk_mul_f32 v[150:151], v[196:197], v[180:181] op_sel_hi:[1,0]
	v_exp_f32_e32 v136, v136
	v_exp_f32_e32 v137, v137
	v_xor_b32_e32 v141, 0x80000000, v149
	v_xor_b32_e32 v140, 0x80000000, v148
	v_exp_f32_e32 v138, v138
	v_exp_f32_e32 v139, v139
	v_xor_b32_e32 v142, 0x80000000, v150
	v_xor_b32_e32 v143, 0x80000000, v151
	v_pk_mul_f32 v[148:149], v[148:149], v[152:153]
	v_pk_mul_f32 v[150:151], v[150:151], v[154:155]
	v_pk_add_f32 v[154:155], v[154:155], -1.0 op_sel_hi:[1,0]
	v_pk_add_f32 v[152:153], v[152:153], -1.0 op_sel_hi:[1,0]
	s_waitcnt vmcnt(5)
; #define GAS __attribute__((address_space(1)))
; #define LAS __attribute__((address_space(3)))
; __device__ __forceinline__ float sigmoidf_(float x) { return __builtin_amdgcn_rcpf(1.0f + __builtin_amdgcn_exp2f(-1.4426950408889634f * x)); }
; #define LDS_WAIT() asm volatile("s_waitcnt lgkmcnt(0)" ::: "memory")
; #define lane LANE_()
; template <int MODE>
; __device__ __forceinline__ void scan_prologue(const ScanP& P, int m0, int seqbase, int T, int h, int d, float* slab, LAS float* lw, float* bon, int lane) {
;     ...
;     for (int n = 0; n < 4; ++n) { const int c = 16 * n + 4 * fq, col = h * 64 + c;
;         const f32x4 w0 = *(const f32x4*)(P.w0 + col), a0 = *(const f32x4*)(P.a0 + col), ka = *(const f32x4*)(P.k_a + col);
;         f32x4 wv, bv, kd, av;
; #pragma unroll
;         for (int i = 0; i < 4; ++i) { const float ic = sigmoidf_(Da[n][i] + a0[i]);
;             wv[i] = __builtin_amdgcn_exp2f(-DECAY_SCALE * 1.4426950408889634f * sigmoidf_(Dw[n][i] + w0[i]));
;             const float kk = kk4[n][i] * rs; av[i] = -kk; bv[i] = kk * ic; kd[i] = k4[n][i] * (1.0f + (ic - 1.0f) * ka[i]); }
;         *(LAS f32x4*)(lw + fr * 64 + c) = av; *(LAS f32x4*)(lw + 3072 + fr * 64 + c) = wv; *(LAS f32x4*)(lw + (MODE == 3 ? 1024 : 4096) + fr * 64 + c) = bv;
;         if (MODE != 1) *(f32x4*)(srow + 192 + c) = kd;
;         { LAS float* xsel = (fr == (d ? 15 : 0)) ? lw + 2048 + c : lw + 2304 + lane * 4;
;           if (MODE != 1) *(LAS f32x4*)(xsel + 128) = kd; }
;         if (MODE == 2) { const f32x4 rk = *(const f32x4*)(P.r_k + col); const f32x4 t = r4[n] * kd * rk; bp += (t.x + t.y) + (t.z + t.w); }
;         if ((n & 1) == 1) asm volatile("" ::: "memory");
;     }
; template <int MODE>
; __device__ __forceinline__ void scan_item(const CAS Args* A, int l, int item, float* slab0, LAS float* ldsw, int lane) {
;     ...
;         asm volatile("" ::: "memory");
;     ...
;         const GAS float* sl = (const GAS float*)slab + lane;
;         LDS_WAIT();
;         float nw[1], nb[1], nk[1], nv[1];
;         { const LAS float* xl = ldsw + 2048 + lane; nw[0] = 0.f; nb[0] = 0.f; nk[0] = 0.f; nv[0] = 0.f; if (MODE != 1) { nk[0] = xl[128]; nv[0] = xl[192]; } }
	v_pk_fma_f32 v[146:147], v[206:207], v[154:155], 1.0 op_sel_hi:[1,1,0]
	v_pk_fma_f32 v[144:145], v[204:205], v[152:153], 1.0 op_sel_hi:[1,1,0]
	v_pk_mul_f32 v[146:147], v[188:189], v[146:147]
	v_pk_mul_f32 v[144:145], v[190:191], v[144:145]
	ds_write_b128 v164, v[140:143] offset:128
	ds_write_b128 v164, v[136:139] offset:11648
	ds_write_b128 v164, v[148:151] offset:4480
	global_store_dwordx4 v[176:177], v[144:147], off offset:896
	ds_write_b128 v230, v[144:147] offset:512
	s_nop 0
	s_nop 0
	s_nop 0
	s_waitcnt vmcnt(3)
	v_add_f32_e32 v132, v132, v248
	s_waitcnt vmcnt(2)
	v_add_f32_e32 v128, v128, v244
	v_add_f32_e32 v129, v129, v245
	v_add_f32_e32 v130, v130, v246
	v_add_f32_e32 v131, v131, v247
	v_mul_f32_e32 v128, 0xbfb8aa3b, v128
	v_add_f32_e32 v133, v133, v249
	v_mul_f32_e32 v129, 0xbfb8aa3b, v129
	v_add_f32_e32 v134, v134, v250
	v_mul_f32_e32 v130, 0xbfb8aa3b, v130
	v_add_f32_e32 v135, v135, v251
	v_mul_f32_e32 v131, 0xbfb8aa3b, v131
	v_mul_f32_e32 v132, 0xbfb8aa3b, v132
	v_exp_f32_e32 v128, v128
	v_mul_f32_e32 v133, 0xbfb8aa3b, v133
	v_exp_f32_e32 v129, v129
	v_mul_f32_e32 v134, 0xbfb8aa3b, v134
	v_exp_f32_e32 v130, v130
	v_mul_f32_e32 v135, 0xbfb8aa3b, v135
	v_exp_f32_e32 v131, v131
	v_exp_f32_e32 v132, v132
	v_exp_f32_e32 v133, v133
	v_exp_f32_e32 v134, v134
	v_exp_f32_e32 v135, v135
	v_add_f32_e32 v128, 1.0, v128
	v_add_f32_e32 v129, 1.0, v129
	v_add_f32_e32 v130, 1.0, v130
	v_add_f32_e32 v131, 1.0, v131
	v_add_f32_e32 v132, 1.0, v132
	v_rcp_f32_e32 v128, v128
	v_add_f32_e32 v133, 1.0, v133
	v_rcp_f32_e32 v129, v129
	v_add_f32_e32 v134, 1.0, v134
	v_rcp_f32_e32 v130, v130
	v_add_f32_e32 v135, 1.0, v135
	v_rcp_f32_e32 v131, v131
	v_rcp_f32_e32 v132, v132
	v_rcp_f32_e32 v133, v133
	v_rcp_f32_e32 v134, v134
	v_rcp_f32_e32 v135, v135
	v_mul_f32_e32 v128, 0xbf60028a, v128
	v_mul_f32_e32 v129, 0xbf60028a, v129
	v_pk_mul_f32 v[144:145], v[186:187], v[180:181] op_sel_hi:[1,0]
	v_mul_f32_e32 v130, 0xbf60028a, v130
	v_mul_f32_e32 v131, 0xbf60028a, v131
	v_pk_mul_f32 v[146:147], v[184:185], v[180:181] op_sel_hi:[1,0]
	v_exp_f32_e32 v128, v128
	v_exp_f32_e32 v129, v129
	v_xor_b32_e32 v141, 0x80000000, v145
	v_xor_b32_e32 v140, 0x80000000, v144
	v_exp_f32_e32 v130, v130
	v_exp_f32_e32 v131, v131
	v_xor_b32_e32 v142, 0x80000000, v146
	v_xor_b32_e32 v143, 0x80000000, v147
	v_pk_mul_f32 v[144:145], v[144:145], v[132:133]
	v_pk_mul_f32 v[146:147], v[146:147], v[134:135]
	v_pk_add_f32 v[134:135], v[134:135], -1.0 op_sel_hi:[1,0]
	v_pk_add_f32 v[132:133], v[132:133], -1.0 op_sel_hi:[1,0]
	v_pk_fma_f32 v[134:135], v[168:169], v[134:135], 1.0 op_sel_hi:[1,1,0]
	v_pk_fma_f32 v[132:133], v[166:167], v[132:133], 1.0 op_sel_hi:[1,1,0]
	v_pk_mul_f32 v[134:135], v[178:179], v[134:135]
	v_pk_mul_f32 v[132:133], v[182:183], v[132:133]
	ds_write_b128 v164, v[140:143] offset:192
	ds_write_b128 v164, v[128:131] offset:11712
	ds_write_b128 v164, v[144:147] offset:4544
	global_store_dwordx4 v[176:177], v[132:135], off offset:960
	ds_write_b128 v229, v[132:135] offset:512
	s_waitcnt lgkmcnt(0)
	ds_read2st64_b32 v[128:129], v228 offset0:36 offset1:37
	v_subrev_u32_e32 v244, s94, v228
	v_and_b32_e32 v245, 0xc0, v244
	v_and_b32_e32 v244, 60, v244
	v_add_u32_e32 v244, s94, v244
	v_sub_u32_e32 v240, 0, v245
	v_ashrrev_i32_e32 v241, 31, v240
	ds_read_b32 v232, v244 offset:9216
	ds_read_b32 v233, v244 offset:9280
	ds_read_b32 v234, v244 offset:9344
	ds_read_b32 v235, v244 offset:9408
	s_waitcnt lgkmcnt(0)
	v_mov_b32_e32 v130, v129
	s_setprio 1

; #define LAS __attribute__((address_space(3)))
; template <int MODE>
; __device__ __forceinline__ void scan_item(const CAS Args* A, int l, int item, float* slab0, LAS float* ldsw, int lane) {
;     ...
;             const LAS f32x4* ua = (const LAS f32x4*)(ldsw + s * 64); const LAS f32x4* ur = (const LAS f32x4*)(ldsw + 1024 + s * 64); const LAS f32x4* uw = (const LAS f32x4*)(ldsw + 3072 + s * 64); const LAS f32x4* ub = (const LAS f32x4*)(ldsw + (MODE == 3 ? 1024 : 4096) + s * 64);
;             f2 sa2 = (f2){0.f, 0.f}, sb2 = (f2){0.f, 0.f}, pa2 = (f2){0.f, 0.f}, pb2 = (f2){0.f, 0.f};
; #pragma unroll
;             for (int j = 0; j < 16; ++j) { const f32x4 aq = ua[j]; const f2 a0 = (f2){aq.x, aq.y}, a1 = (f2){aq.z, aq.w}; sa2 = S[2 * j] * a0 + sa2; sb2 = S[2 * j + 1] * a1 + sb2;
;                 if (MODE == 3) { pa2 = Pm[2 * j] * a0 + pa2; pb2 = Pm[2 * j + 1] * a1 + pb2; } }
;             const float sa = (sa2.x + sa2.y) + (sb2.x + sb2.y), pa = (pa2.x + pa2.y) + (pb2.x + pb2.y); const f2 pas = (f2){pa, pa};
;             const f2 sas = (f2){sa, sa}, vvs = (f2){vv, vv};
;             f2 y2 = (f2){0.f, 0.f}, y3 = (f2){0.f, 0.f};
;             f32x4 nwq[2], nbq[2], nrq[2];
;             nwq[0] = uw[0]; nwq[1] = uw[1]; nbq[0] = ub[0]; nbq[1] = ub[1]; nrq[0] = (f32x4){0.f, 0.f, 0.f, 0.f}; nrq[1] = nrq[0];
;             if (MODE == 2) { nrq[0] = ur[0]; nrq[1] = ur[1]; }
.LBB0_292:
	s_mul_i32 s5, s5, 0x110
	s_add_i32 s5, s94, s5
	v_mov_b32_e32 v170, s5
	ds_read_b128 v[136:139], v170
	ds_read_b128 v[144:147], v170 offset:16
	ds_read_b128 v[148:151], v170 offset:32
	ds_read_b128 v[152:155], v170 offset:48
	ds_read_b128 v[156:159], v170 offset:64
	ds_read_b128 v[160:163], v170 offset:80
	ds_read_b128 v[164:167], v170 offset:96
	ds_read_b128 v[176:179], v170 offset:112
	ds_read_b128 v[182:185], v170 offset:128
	ds_read_b128 v[186:189], v170 offset:144
	ds_read_b128 v[196:199], v170 offset:160
	ds_read_b128 v[200:203], v170 offset:176
	s_waitcnt lgkmcnt(11)
	v_pk_fma_f32 v[140:141], v[124:125], v[136:137], 0 op_sel_hi:[1,1,0]
	v_pk_fma_f32 v[142:143], v[126:127], v[138:139], 0 op_sel_hi:[1,1,0]
	v_pk_fma_f32 v[132:133], v[0:1], v[136:137], 0 op_sel_hi:[1,1,0]
	v_pk_fma_f32 v[134:135], v[2:3], v[138:139], 0 op_sel_hi:[1,1,0]
	s_waitcnt lgkmcnt(10)
	v_pk_fma_f32 v[140:141], v[120:121], v[144:145], v[140:141]
	v_pk_fma_f32 v[142:143], v[122:123], v[146:147], v[142:143]
	v_pk_fma_f32 v[132:133], v[4:5], v[144:145], v[132:133]
	v_pk_fma_f32 v[134:135], v[6:7], v[146:147], v[134:135]
	s_waitcnt lgkmcnt(9)
	v_pk_fma_f32 v[140:141], v[116:117], v[148:149], v[140:141]
	v_pk_fma_f32 v[142:143], v[118:119], v[150:151], v[142:143]
	v_pk_fma_f32 v[132:133], v[8:9], v[148:149], v[132:133]
	v_pk_fma_f32 v[134:135], v[10:11], v[150:151], v[134:135]
	s_waitcnt lgkmcnt(8)
	v_pk_fma_f32 v[140:141], v[112:113], v[152:153], v[140:141]
	v_pk_fma_f32 v[142:143], v[114:115], v[154:155], v[142:143]
	v_pk_fma_f32 v[132:133], v[12:13], v[152:153], v[132:133]
	v_pk_fma_f32 v[134:135], v[14:15], v[154:155], v[134:135]
	ds_read_b128 v[204:207], v170 offset:192
	ds_read_b128 v[208:211], v170 offset:208
	ds_read_b128 v[212:215], v170 offset:224
	ds_read_b128 v[246:249], v170 offset:240
	s_waitcnt lgkmcnt(11)
	v_pk_fma_f32 v[140:141], v[108:109], v[156:157], v[140:141]
	v_pk_fma_f32 v[142:143], v[110:111], v[158:159], v[142:143]
	v_pk_fma_f32 v[132:133], v[16:17], v[156:157], v[132:133]
	v_pk_fma_f32 v[134:135], v[18:19], v[158:159], v[134:135]
	s_waitcnt lgkmcnt(10)
	v_pk_fma_f32 v[140:141], v[104:105], v[160:161], v[140:141]
	v_pk_fma_f32 v[142:143], v[106:107], v[162:163], v[142:143]
	v_pk_fma_f32 v[132:133], v[20:21], v[160:161], v[132:133]
	v_pk_fma_f32 v[134:135], v[22:23], v[162:163], v[134:135]
	s_waitcnt lgkmcnt(9)
	v_pk_fma_f32 v[140:141], v[100:101], v[164:165], v[140:141]
	v_pk_fma_f32 v[142:143], v[102:103], v[166:167], v[142:143]
	v_pk_fma_f32 v[132:133], v[24:25], v[164:165], v[132:133]
	v_pk_fma_f32 v[134:135], v[26:27], v[166:167], v[134:135]
	s_waitcnt lgkmcnt(8)
	v_pk_fma_f32 v[140:141], v[96:97], v[176:177], v[140:141]
	v_pk_fma_f32 v[142:143], v[98:99], v[178:179], v[142:143]
	v_pk_fma_f32 v[132:133], v[28:29], v[176:177], v[132:133]
	v_pk_fma_f32 v[134:135], v[30:31], v[178:179], v[134:135]
	s_waitcnt lgkmcnt(7)
	v_pk_fma_f32 v[140:141], v[92:93], v[182:183], v[140:141]
	v_pk_fma_f32 v[142:143], v[94:95], v[184:185], v[142:143]
	v_pk_fma_f32 v[132:133], v[32:33], v[182:183], v[132:133]
	v_pk_fma_f32 v[134:135], v[34:35], v[184:185], v[134:135]
	s_waitcnt lgkmcnt(6)
	v_pk_fma_f32 v[140:141], v[88:89], v[186:187], v[140:141]
	v_pk_fma_f32 v[142:143], v[90:91], v[188:189], v[142:143]
	v_pk_fma_f32 v[132:133], v[36:37], v[186:187], v[132:133]
	v_pk_fma_f32 v[134:135], v[38:39], v[188:189], v[134:135]
	s_waitcnt lgkmcnt(5)
	v_pk_fma_f32 v[140:141], v[84:85], v[196:197], v[140:141]
	v_pk_fma_f32 v[142:143], v[86:87], v[198:199], v[142:143]
	v_pk_fma_f32 v[132:133], v[40:41], v[196:197], v[132:133]
	v_pk_fma_f32 v[134:135], v[42:43], v[198:199], v[134:135]
	s_waitcnt lgkmcnt(4)
	v_pk_fma_f32 v[140:141], v[80:81], v[200:201], v[140:141]
	v_pk_fma_f32 v[142:143], v[82:83], v[202:203], v[142:143]
	v_pk_fma_f32 v[132:133], v[44:45], v[200:201], v[132:133]
	v_pk_fma_f32 v[134:135], v[46:47], v[202:203], v[134:135]
	s_waitcnt lgkmcnt(3)
	v_pk_fma_f32 v[140:141], v[76:77], v[204:205], v[140:141]
	v_pk_fma_f32 v[142:143], v[78:79], v[206:207], v[142:143]
	v_pk_fma_f32 v[132:133], v[48:49], v[204:205], v[132:133]
	v_pk_fma_f32 v[134:135], v[50:51], v[206:207], v[134:135]
	s_waitcnt lgkmcnt(2)
	v_pk_fma_f32 v[140:141], v[72:73], v[208:209], v[140:141]
	v_pk_fma_f32 v[142:143], v[74:75], v[210:211], v[142:143]
	v_pk_fma_f32 v[132:133], v[52:53], v[208:209], v[132:133]
	v_pk_fma_f32 v[134:135], v[54:55], v[210:211], v[134:135]
	s_waitcnt lgkmcnt(1)
	v_pk_fma_f32 v[140:141], v[68:69], v[212:213], v[140:141]
	v_pk_fma_f32 v[142:143], v[70:71], v[214:215], v[142:143]
	v_pk_fma_f32 v[132:133], v[56:57], v[212:213], v[132:133]
	v_pk_fma_f32 v[134:135], v[58:59], v[214:215], v[134:135]
	s_waitcnt lgkmcnt(0)
	v_pk_fma_f32 v[140:141], v[64:65], v[246:247], v[140:141]
	v_pk_fma_f32 v[142:143], v[66:67], v[248:249], v[142:143]
	v_pk_fma_f32 v[132:133], v[60:61], v[246:247], v[132:133]
	v_pk_fma_f32 v[134:135], v[62:63], v[248:249], v[134:135]
	v_mov_b32_e32 v136, v142
	v_mov_b32_e32 v137, v140
	v_mov_b32_e32 v140, v143
	v_pk_add_f32 v[136:137], v[136:137], v[140:141]
	v_mov_b32_e32 v138, v134
	v_mov_b32_e32 v139, v132
	v_mov_b32_e32 v132, v135
	v_pk_add_f32 v[132:133], v[138:139], v[132:133]
	v_pk_add_f32 v[134:135], v[136:137], v[136:137] op_sel:[0,1] op_sel_hi:[0,1]
	ds_read_b128 v[136:139], v170 offset:11520
	ds_read_b128 v[140:143], v170 offset:11536
	ds_read_b128 v[144:147], v170 offset:4352
	ds_read_b128 v[148:151], v170 offset:4368
	ds_read_b128 v[152:155], v170 offset:11552
	ds_read_b128 v[156:159], v170 offset:11568
	ds_read_b128 v[160:163], v170 offset:4384
	ds_read_b128 v[164:167], v170 offset:4400
	v_pk_add_f32 v[132:133], v[132:133], v[132:133] op_sel:[0,1] op_sel_hi:[0,1]
	s_waitcnt lgkmcnt(5)
; #define RL2(x, j) (f2){__builtin_bit_cast(float, __builtin_amdgcn_readlane(__builtin_bit_cast(int, x), 2 * (j))), __builtin_bit_cast(float, __builtin_amdgcn_readlane(__builtin_bit_cast(int, x), 2 * (j) + 1))}
; template <int MODE>
; __device__ __forceinline__ void scan_item(const CAS Args* A, int l, int item, float* slab0, LAS float* ldsw, int lane) {
;     ...
; #pragma unroll
;             for (int g = 0; g < 8; ++g) {
;                 const f32x4 cwq0 = nwq[0], cwq1 = nwq[1], cbq0 = nbq[0], cbq1 = nbq[1], crq0 = nrq[0], crq1 = nrq[1];
;                 if (g < 7) { nwq[0] = uw[2 * g + 2]; nwq[1] = uw[2 * g + 3]; nbq[0] = ub[2 * g + 2]; nbq[1] = ub[2 * g + 3];
;                     if (MODE == 2) { nrq[0] = ur[2 * g + 2]; nrq[1] = ur[2 * g + 3]; } }
;                 f2 bb[4], ww[4], kq[4], rr[4];
;                 ww[0] = (f2){cwq0.x, cwq0.y}; ww[1] = (f2){cwq0.z, cwq0.w}; ww[2] = (f2){cwq1.x, cwq1.y}; ww[3] = (f2){cwq1.z, cwq1.w};
;                 bb[0] = (f2){cbq0.x, cbq0.y}; bb[1] = (f2){cbq0.z, cbq0.w}; bb[2] = (f2){cbq1.x, cbq1.y}; bb[3] = (f2){cbq1.z, cbq1.w};
;                 rr[0] = (f2){crq0.x, crq0.y}; rr[1] = (f2){crq0.z, crq0.w}; rr[2] = (f2){crq1.x, crq1.y}; rr[3] = (f2){crq1.z, crq1.w};
; #pragma unroll
;                 for (int q = 0; q < 4; ++q) { const int j = g * 4 + q; if (MODE != 1) kq[q] = RL2(ck, j); }
;                 __builtin_amdgcn_sched_barrier(0);
; #pragma unroll
;                 for (int q = 0; q < 4; ++q) { const int j = g * 4 + q;
;                     f2 t = sas * bb[q];
;                     if (MODE != 1) t = vvs * kq[q] + t;
;                     S[j] = S[j] * ww[q] + t;
;                     if (MODE == 3) Pm[j] = Pm[j] * ww[q] + pas * bb[q];
;                     if (MODE == 2) { if (j & 1) y3 = S[j] * rr[q] + y3; else y2 = S[j] * rr[q] + y2; } }
;             }
	v_pk_mul_f32 v[168:169], v[144:145], v[134:135]
	v_pk_mul_f32 v[144:145], v[144:145], v[132:133]
	v_pk_fma_f32 v[124:125], v[124:125], v[136:137], v[168:169]
	v_pk_fma_f32 v[0:1], v[0:1], v[136:137], v[144:145]
	v_pk_mul_f32 v[136:137], v[146:147], v[134:135]
	v_pk_fma_f32 v[126:127], v[126:127], v[138:139], v[136:137]
	v_fmac_f32_dpp v124, v232, v130 row_newbcast:0 row_mask:0xf bank_mask:0xf
	v_fmac_f32_dpp v125, v232, v130 row_newbcast:1 row_mask:0xf bank_mask:0xf
	v_pk_mul_f32 v[136:137], v[146:147], v[132:133]
	v_pk_fma_f32 v[2:3], v[2:3], v[138:139], v[136:137]
	s_waitcnt lgkmcnt(4)
	v_pk_mul_f32 v[136:137], v[148:149], v[134:135]
	v_pk_fma_f32 v[120:121], v[120:121], v[140:141], v[136:137]
	v_fmac_f32_dpp v126, v232, v130 row_newbcast:2 row_mask:0xf bank_mask:0xf
	v_fmac_f32_dpp v127, v232, v130 row_newbcast:3 row_mask:0xf bank_mask:0xf
	v_pk_mul_f32 v[136:137], v[148:149], v[132:133]
	v_pk_fma_f32 v[4:5], v[4:5], v[140:141], v[136:137]
	v_pk_mul_f32 v[136:137], v[150:151], v[134:135]
	v_pk_fma_f32 v[122:123], v[122:123], v[142:143], v[136:137]
	v_fmac_f32_dpp v120, v232, v130 row_newbcast:4 row_mask:0xf bank_mask:0xf
	v_fmac_f32_dpp v121, v232, v130 row_newbcast:5 row_mask:0xf bank_mask:0xf
	v_pk_mul_f32 v[136:137], v[150:151], v[132:133]
	v_pk_fma_f32 v[6:7], v[6:7], v[142:143], v[136:137]
	ds_read_b128 v[136:139], v170 offset:11584
	ds_read_b128 v[140:143], v170 offset:11600
	ds_read_b128 v[144:147], v170 offset:4416
	ds_read_b128 v[148:151], v170 offset:4432
	s_waitcnt lgkmcnt(5)
	v_pk_mul_f32 v[168:169], v[134:135], v[160:161]
	v_pk_mul_f32 v[160:161], v[132:133], v[160:161]
	v_pk_fma_f32 v[116:117], v[116:117], v[152:153], v[168:169]
	v_fmac_f32_dpp v122, v232, v130 row_newbcast:6 row_mask:0xf bank_mask:0xf
	v_fmac_f32_dpp v123, v232, v130 row_newbcast:7 row_mask:0xf bank_mask:0xf
	v_pk_fma_f32 v[8:9], v[8:9], v[152:153], v[160:161]
	v_pk_mul_f32 v[152:153], v[134:135], v[162:163]
	v_pk_fma_f32 v[118:119], v[118:119], v[154:155], v[152:153]
	v_fmac_f32_dpp v116, v232, v130 row_newbcast:8 row_mask:0xf bank_mask:0xf
	v_fmac_f32_dpp v117, v232, v130 row_newbcast:9 row_mask:0xf bank_mask:0xf
	v_pk_mul_f32 v[152:153], v[132:133], v[162:163]
	v_pk_fma_f32 v[10:11], v[10:11], v[154:155], v[152:153]
	s_waitcnt lgkmcnt(4)
	v_pk_mul_f32 v[152:153], v[134:135], v[164:165]
	v_pk_fma_f32 v[112:113], v[112:113], v[156:157], v[152:153]
	v_fmac_f32_dpp v118, v232, v130 row_newbcast:10 row_mask:0xf bank_mask:0xf
	v_fmac_f32_dpp v119, v232, v130 row_newbcast:11 row_mask:0xf bank_mask:0xf
	v_pk_mul_f32 v[152:153], v[132:133], v[164:165]
	v_pk_fma_f32 v[12:13], v[12:13], v[156:157], v[152:153]
	v_pk_mul_f32 v[152:153], v[134:135], v[166:167]
	v_pk_fma_f32 v[114:115], v[114:115], v[158:159], v[152:153]
	v_fmac_f32_dpp v112, v232, v130 row_newbcast:12 row_mask:0xf bank_mask:0xf
	v_fmac_f32_dpp v113, v232, v130 row_newbcast:13 row_mask:0xf bank_mask:0xf
	v_pk_mul_f32 v[152:153], v[132:133], v[166:167]
	v_pk_fma_f32 v[14:15], v[14:15], v[158:159], v[152:153]
	ds_read_b128 v[152:155], v170 offset:11616
	ds_read_b128 v[156:159], v170 offset:11632
	ds_read_b128 v[160:163], v170 offset:4448
	ds_read_b128 v[164:167], v170 offset:4464
	s_waitcnt lgkmcnt(5)
	v_pk_mul_f32 v[168:169], v[134:135], v[144:145]
	v_pk_mul_f32 v[144:145], v[132:133], v[144:145]
	v_pk_fma_f32 v[108:109], v[108:109], v[136:137], v[168:169]
	v_fmac_f32_dpp v114, v232, v130 row_newbcast:14 row_mask:0xf bank_mask:0xf
	v_fmac_f32_dpp v115, v232, v130 row_newbcast:15 row_mask:0xf bank_mask:0xf
	v_pk_fma_f32 v[16:17], v[16:17], v[136:137], v[144:145]
	v_pk_mul_f32 v[136:137], v[134:135], v[146:147]
	v_pk_fma_f32 v[110:111], v[110:111], v[138:139], v[136:137]
	v_fmac_f32_dpp v108, v233, v130 row_newbcast:0 row_mask:0xf bank_mask:0xf
	v_fmac_f32_dpp v109, v233, v130 row_newbcast:1 row_mask:0xf bank_mask:0xf
	v_pk_mul_f32 v[136:137], v[132:133], v[146:147]
	v_pk_fma_f32 v[18:19], v[18:19], v[138:139], v[136:137]
	s_waitcnt lgkmcnt(4)
	v_pk_mul_f32 v[136:137], v[134:135], v[148:149]
	v_pk_fma_f32 v[104:105], v[104:105], v[140:141], v[136:137]
	v_fmac_f32_dpp v110, v233, v130 row_newbcast:2 row_mask:0xf bank_mask:0xf
	v_fmac_f32_dpp v111, v233, v130 row_newbcast:3 row_mask:0xf bank_mask:0xf
	v_pk_mul_f32 v[136:137], v[132:133], v[148:149]
	v_pk_fma_f32 v[20:21], v[20:21], v[140:141], v[136:137]
	v_pk_mul_f32 v[136:137], v[134:135], v[150:151]
	v_pk_fma_f32 v[106:107], v[106:107], v[142:143], v[136:137]
	v_fmac_f32_dpp v104, v233, v130 row_newbcast:4 row_mask:0xf bank_mask:0xf
	v_fmac_f32_dpp v105, v233, v130 row_newbcast:5 row_mask:0xf bank_mask:0xf
	v_pk_mul_f32 v[136:137], v[132:133], v[150:151]
	v_pk_fma_f32 v[22:23], v[22:23], v[142:143], v[136:137]
	ds_read_b128 v[136:139], v170 offset:11648
	ds_read_b128 v[140:143], v170 offset:11664
	ds_read_b128 v[144:147], v170 offset:4480
	ds_read_b128 v[148:151], v170 offset:4496
	s_waitcnt lgkmcnt(5)
	v_pk_mul_f32 v[168:169], v[134:135], v[160:161]
	v_pk_mul_f32 v[160:161], v[132:133], v[160:161]
	v_pk_fma_f32 v[100:101], v[100:101], v[152:153], v[168:169]
	v_fmac_f32_dpp v106, v233, v130 row_newbcast:6 row_mask:0xf bank_mask:0xf
	v_fmac_f32_dpp v107, v233, v130 row_newbcast:7 row_mask:0xf bank_mask:0xf
	v_pk_fma_f32 v[24:25], v[24:25], v[152:153], v[160:161]
	v_pk_mul_f32 v[152:153], v[134:135], v[162:163]
	v_pk_fma_f32 v[102:103], v[102:103], v[154:155], v[152:153]
	v_fmac_f32_dpp v100, v233, v130 row_newbcast:8 row_mask:0xf bank_mask:0xf
	v_fmac_f32_dpp v101, v233, v130 row_newbcast:9 row_mask:0xf bank_mask:0xf
	v_pk_mul_f32 v[152:153], v[132:133], v[162:163]
	v_pk_fma_f32 v[26:27], v[26:27], v[154:155], v[152:153]
	s_waitcnt lgkmcnt(4)
; #define RL2(x, j) (f2){__builtin_bit_cast(float, __builtin_amdgcn_readlane(__builtin_bit_cast(int, x), 2 * (j))), __builtin_bit_cast(float, __builtin_amdgcn_readlane(__builtin_bit_cast(int, x), 2 * (j) + 1))}
; template <int MODE>
; __device__ __forceinline__ void scan_item(const CAS Args* A, int l, int item, float* slab0, LAS float* ldsw, int lane) {
;     ...
; #pragma unroll
;             for (int g = 0; g < 8; ++g) {
;                 const f32x4 cwq0 = nwq[0], cwq1 = nwq[1], cbq0 = nbq[0], cbq1 = nbq[1], crq0 = nrq[0], crq1 = nrq[1];
;                 if (g < 7) { nwq[0] = uw[2 * g + 2]; nwq[1] = uw[2 * g + 3]; nbq[0] = ub[2 * g + 2]; nbq[1] = ub[2 * g + 3];
;                     if (MODE == 2) { nrq[0] = ur[2 * g + 2]; nrq[1] = ur[2 * g + 3]; } }
;                 f2 bb[4], ww[4], kq[4], rr[4];
;                 ww[0] = (f2){cwq0.x, cwq0.y}; ww[1] = (f2){cwq0.z, cwq0.w}; ww[2] = (f2){cwq1.x, cwq1.y}; ww[3] = (f2){cwq1.z, cwq1.w};
;                 bb[0] = (f2){cbq0.x, cbq0.y}; bb[1] = (f2){cbq0.z, cbq0.w}; bb[2] = (f2){cbq1.x, cbq1.y}; bb[3] = (f2){cbq1.z, cbq1.w};
;                 rr[0] = (f2){crq0.x, crq0.y}; rr[1] = (f2){crq0.z, crq0.w}; rr[2] = (f2){crq1.x, crq1.y}; rr[3] = (f2){crq1.z, crq1.w};
; #pragma unroll
;                 for (int q = 0; q < 4; ++q) { const int j = g * 4 + q; if (MODE != 1) kq[q] = RL2(ck, j); }
;                 __builtin_amdgcn_sched_barrier(0);
; #pragma unroll
;                 for (int q = 0; q < 4; ++q) { const int j = g * 4 + q;
;                     f2 t = sas * bb[q];
;                     if (MODE != 1) t = vvs * kq[q] + t;
;                     S[j] = S[j] * ww[q] + t;
;                     if (MODE == 3) Pm[j] = Pm[j] * ww[q] + pas * bb[q];
;                     if (MODE == 2) { if (j & 1) y3 = S[j] * rr[q] + y3; else y2 = S[j] * rr[q] + y2; } }
;             }
	v_pk_mul_f32 v[152:153], v[134:135], v[164:165]
	v_pk_fma_f32 v[96:97], v[96:97], v[156:157], v[152:153]
	v_fmac_f32_dpp v102, v233, v130 row_newbcast:10 row_mask:0xf bank_mask:0xf
	v_fmac_f32_dpp v103, v233, v130 row_newbcast:11 row_mask:0xf bank_mask:0xf
	v_pk_mul_f32 v[152:153], v[132:133], v[164:165]
	v_pk_fma_f32 v[28:29], v[28:29], v[156:157], v[152:153]
	v_pk_mul_f32 v[152:153], v[134:135], v[166:167]
	v_pk_fma_f32 v[98:99], v[98:99], v[158:159], v[152:153]
	v_fmac_f32_dpp v96, v233, v130 row_newbcast:12 row_mask:0xf bank_mask:0xf
	v_fmac_f32_dpp v97, v233, v130 row_newbcast:13 row_mask:0xf bank_mask:0xf
	v_pk_mul_f32 v[152:153], v[132:133], v[166:167]
	v_pk_fma_f32 v[30:31], v[30:31], v[158:159], v[152:153]
	ds_read_b128 v[152:155], v170 offset:11680
	ds_read_b128 v[156:159], v170 offset:11696
	ds_read_b128 v[160:163], v170 offset:4512
	ds_read_b128 v[164:167], v170 offset:4528
	s_waitcnt lgkmcnt(5)
	v_pk_mul_f32 v[168:169], v[134:135], v[144:145]
	v_pk_mul_f32 v[144:145], v[132:133], v[144:145]
	v_pk_fma_f32 v[92:93], v[92:93], v[136:137], v[168:169]
	v_fmac_f32_dpp v98, v233, v130 row_newbcast:14 row_mask:0xf bank_mask:0xf
	v_fmac_f32_dpp v99, v233, v130 row_newbcast:15 row_mask:0xf bank_mask:0xf
	v_pk_fma_f32 v[32:33], v[32:33], v[136:137], v[144:145]
	v_pk_mul_f32 v[136:137], v[134:135], v[146:147]
	v_pk_fma_f32 v[94:95], v[94:95], v[138:139], v[136:137]
	v_fmac_f32_dpp v92, v234, v130 row_newbcast:0 row_mask:0xf bank_mask:0xf
	v_fmac_f32_dpp v93, v234, v130 row_newbcast:1 row_mask:0xf bank_mask:0xf
	v_pk_mul_f32 v[136:137], v[132:133], v[146:147]
	v_pk_fma_f32 v[34:35], v[34:35], v[138:139], v[136:137]
	s_waitcnt lgkmcnt(4)
	v_pk_mul_f32 v[136:137], v[134:135], v[148:149]
	v_pk_fma_f32 v[88:89], v[88:89], v[140:141], v[136:137]
	v_fmac_f32_dpp v94, v234, v130 row_newbcast:2 row_mask:0xf bank_mask:0xf
	v_fmac_f32_dpp v95, v234, v130 row_newbcast:3 row_mask:0xf bank_mask:0xf
	v_pk_mul_f32 v[136:137], v[132:133], v[148:149]
	v_pk_fma_f32 v[36:37], v[36:37], v[140:141], v[136:137]
	v_pk_mul_f32 v[136:137], v[134:135], v[150:151]
	v_pk_fma_f32 v[90:91], v[90:91], v[142:143], v[136:137]
	v_fmac_f32_dpp v88, v234, v130 row_newbcast:4 row_mask:0xf bank_mask:0xf
	v_fmac_f32_dpp v89, v234, v130 row_newbcast:5 row_mask:0xf bank_mask:0xf
	v_pk_mul_f32 v[136:137], v[132:133], v[150:151]
	v_pk_fma_f32 v[38:39], v[38:39], v[142:143], v[136:137]
	ds_read_b128 v[136:139], v170 offset:11712
	ds_read_b128 v[140:143], v170 offset:11728
	ds_read_b128 v[144:147], v170 offset:4544
	ds_read_b128 v[148:151], v170 offset:4560
	s_waitcnt lgkmcnt(5)
	v_pk_mul_f32 v[168:169], v[134:135], v[160:161]
	v_pk_mul_f32 v[160:161], v[132:133], v[160:161]
	v_pk_fma_f32 v[84:85], v[84:85], v[152:153], v[168:169]
	v_fmac_f32_dpp v90, v234, v130 row_newbcast:6 row_mask:0xf bank_mask:0xf
	v_fmac_f32_dpp v91, v234, v130 row_newbcast:7 row_mask:0xf bank_mask:0xf
	v_pk_fma_f32 v[40:41], v[40:41], v[152:153], v[160:161]
	v_pk_mul_f32 v[152:153], v[134:135], v[162:163]
	v_pk_fma_f32 v[86:87], v[86:87], v[154:155], v[152:153]
	v_fmac_f32_dpp v84, v234, v130 row_newbcast:8 row_mask:0xf bank_mask:0xf
	v_fmac_f32_dpp v85, v234, v130 row_newbcast:9 row_mask:0xf bank_mask:0xf
	v_pk_mul_f32 v[152:153], v[132:133], v[162:163]
	v_pk_fma_f32 v[42:43], v[42:43], v[154:155], v[152:153]
	s_waitcnt lgkmcnt(4)
	v_pk_mul_f32 v[152:153], v[134:135], v[164:165]
	v_pk_fma_f32 v[80:81], v[80:81], v[156:157], v[152:153]
	v_fmac_f32_dpp v86, v234, v130 row_newbcast:10 row_mask:0xf bank_mask:0xf
	v_fmac_f32_dpp v87, v234, v130 row_newbcast:11 row_mask:0xf bank_mask:0xf
	v_pk_mul_f32 v[152:153], v[132:133], v[164:165]
	v_pk_fma_f32 v[44:45], v[44:45], v[156:157], v[152:153]
	v_pk_mul_f32 v[152:153], v[134:135], v[166:167]
	v_pk_fma_f32 v[82:83], v[82:83], v[158:159], v[152:153]
	v_fmac_f32_dpp v80, v234, v130 row_newbcast:12 row_mask:0xf bank_mask:0xf
	v_fmac_f32_dpp v81, v234, v130 row_newbcast:13 row_mask:0xf bank_mask:0xf
	v_pk_mul_f32 v[152:153], v[132:133], v[166:167]
	v_pk_fma_f32 v[46:47], v[46:47], v[158:159], v[152:153]
	ds_read_b128 v[152:155], v170 offset:11744
	ds_read_b128 v[156:159], v170 offset:11760
	ds_read_b128 v[160:163], v170 offset:4576
	ds_read_b128 v[164:167], v170 offset:4592
	s_waitcnt lgkmcnt(5)
; __device__ __forceinline__ unsigned f2bf(float f) { return pk2(f, f) & 0xffffu; }
; #define RL2(x, j) (f2){__builtin_bit_cast(float, __builtin_amdgcn_readlane(__builtin_bit_cast(int, x), 2 * (j))), __builtin_bit_cast(float, __builtin_amdgcn_readlane(__builtin_bit_cast(int, x), 2 * (j) + 1))}
; #define lane LANE_()
; template <int MODE>
; __device__ __forceinline__ void scan_item(const CAS Args* A, int l, int item, float* slab0, LAS float* ldsw, int lane) {
;     ...
; #pragma unroll
;             for (int g = 0; g < 8; ++g) {
;                 const f32x4 cwq0 = nwq[0], cwq1 = nwq[1], cbq0 = nbq[0], cbq1 = nbq[1], crq0 = nrq[0], crq1 = nrq[1];
;                 if (g < 7) { nwq[0] = uw[2 * g + 2]; nwq[1] = uw[2 * g + 3]; nbq[0] = ub[2 * g + 2]; nbq[1] = ub[2 * g + 3];
;                     if (MODE == 2) { nrq[0] = ur[2 * g + 2]; nrq[1] = ur[2 * g + 3]; } }
;                 f2 bb[4], ww[4], kq[4], rr[4];
;                 ww[0] = (f2){cwq0.x, cwq0.y}; ww[1] = (f2){cwq0.z, cwq0.w}; ww[2] = (f2){cwq1.x, cwq1.y}; ww[3] = (f2){cwq1.z, cwq1.w};
;                 bb[0] = (f2){cbq0.x, cbq0.y}; bb[1] = (f2){cbq0.z, cbq0.w}; bb[2] = (f2){cbq1.x, cbq1.y}; bb[3] = (f2){cbq1.z, cbq1.w};
;                 rr[0] = (f2){crq0.x, crq0.y}; rr[1] = (f2){crq0.z, crq0.w}; rr[2] = (f2){crq1.x, crq1.y}; rr[3] = (f2){crq1.z, crq1.w};
; #pragma unroll
;                 for (int q = 0; q < 4; ++q) { const int j = g * 4 + q; if (MODE != 1) kq[q] = RL2(ck, j); }
;                 __builtin_amdgcn_sched_barrier(0);
; #pragma unroll
;                 for (int q = 0; q < 4; ++q) { const int j = g * 4 + q;
;                     f2 t = sas * bb[q];
;                     if (MODE != 1) t = vvs * kq[q] + t;
;                     S[j] = S[j] * ww[q] + t;
;                     if (MODE == 3) Pm[j] = Pm[j] * ww[q] + pas * bb[q];
;                     if (MODE == 2) { if (j & 1) y3 = S[j] * rr[q] + y3; else y2 = S[j] * rr[q] + y2; } }
;             }
;             if (MODE == 2) yb[(size_t)(t0 + s) * 512 + h * 64 + lane] = (bf16)f2bf((y2.x + y2.y) + (y3.x + y3.y));
;         }
	v_pk_mul_f32 v[168:169], v[134:135], v[144:145]
	v_pk_mul_f32 v[144:145], v[132:133], v[144:145]
	v_pk_fma_f32 v[76:77], v[76:77], v[136:137], v[168:169]
	v_fmac_f32_dpp v82, v234, v130 row_newbcast:14 row_mask:0xf bank_mask:0xf
	v_fmac_f32_dpp v83, v234, v130 row_newbcast:15 row_mask:0xf bank_mask:0xf
	v_pk_fma_f32 v[48:49], v[48:49], v[136:137], v[144:145]
	v_pk_mul_f32 v[136:137], v[134:135], v[146:147]
	v_pk_fma_f32 v[78:79], v[78:79], v[138:139], v[136:137]
	v_fmac_f32_dpp v76, v235, v130 row_newbcast:0 row_mask:0xf bank_mask:0xf
	v_fmac_f32_dpp v77, v235, v130 row_newbcast:1 row_mask:0xf bank_mask:0xf
	v_pk_mul_f32 v[136:137], v[132:133], v[146:147]
	v_pk_fma_f32 v[50:51], v[50:51], v[138:139], v[136:137]
	s_waitcnt lgkmcnt(4)
	v_pk_mul_f32 v[136:137], v[134:135], v[148:149]
	v_pk_fma_f32 v[72:73], v[72:73], v[140:141], v[136:137]
	v_fmac_f32_dpp v78, v235, v130 row_newbcast:2 row_mask:0xf bank_mask:0xf
	v_fmac_f32_dpp v79, v235, v130 row_newbcast:3 row_mask:0xf bank_mask:0xf
	v_pk_mul_f32 v[136:137], v[132:133], v[148:149]
	v_pk_fma_f32 v[52:53], v[52:53], v[140:141], v[136:137]
	v_pk_mul_f32 v[136:137], v[134:135], v[150:151]
	v_pk_fma_f32 v[74:75], v[74:75], v[142:143], v[136:137]
	v_fmac_f32_dpp v72, v235, v130 row_newbcast:4 row_mask:0xf bank_mask:0xf
	v_fmac_f32_dpp v73, v235, v130 row_newbcast:5 row_mask:0xf bank_mask:0xf
	v_pk_mul_f32 v[136:137], v[132:133], v[150:151]
	v_pk_fma_f32 v[54:55], v[54:55], v[142:143], v[136:137]
	s_waitcnt lgkmcnt(1)
	v_pk_mul_f32 v[136:137], v[134:135], v[160:161]
	s_add_i32 s4, s4, 1
	v_pk_fma_f32 v[68:69], v[68:69], v[152:153], v[136:137]
	v_fmac_f32_dpp v74, v235, v130 row_newbcast:6 row_mask:0xf bank_mask:0xf
	v_fmac_f32_dpp v75, v235, v130 row_newbcast:7 row_mask:0xf bank_mask:0xf
	v_pk_mul_f32 v[136:137], v[132:133], v[160:161]
	s_add_i32 s91, s91, -1
	v_pk_fma_f32 v[56:57], v[56:57], v[152:153], v[136:137]
	v_pk_mul_f32 v[136:137], v[134:135], v[162:163]
	s_cmp_eq_u32 s4, 16
	v_pk_fma_f32 v[70:71], v[70:71], v[154:155], v[136:137]
	v_fmac_f32_dpp v68, v235, v130 row_newbcast:8 row_mask:0xf bank_mask:0xf
	v_fmac_f32_dpp v69, v235, v130 row_newbcast:9 row_mask:0xf bank_mask:0xf
	v_pk_mul_f32 v[136:137], v[132:133], v[162:163]
	s_nop 0
	v_pk_fma_f32 v[58:59], v[58:59], v[154:155], v[136:137]
	s_waitcnt lgkmcnt(0)
	v_pk_mul_f32 v[136:137], v[134:135], v[164:165]
	s_nop 0
	v_pk_fma_f32 v[64:65], v[64:65], v[156:157], v[136:137]
	v_fmac_f32_dpp v70, v235, v130 row_newbcast:10 row_mask:0xf bank_mask:0xf
	v_fmac_f32_dpp v71, v235, v130 row_newbcast:11 row_mask:0xf bank_mask:0xf
	v_pk_mul_f32 v[136:137], v[132:133], v[164:165]
	v_pk_mul_f32 v[132:133], v[132:133], v[166:167]
	v_pk_fma_f32 v[60:61], v[60:61], v[156:157], v[136:137]
	v_pk_mul_f32 v[134:135], v[134:135], v[166:167]
	v_pk_fma_f32 v[62:63], v[62:63], v[158:159], v[132:133]
	v_pk_fma_f32 v[66:67], v[66:67], v[158:159], v[134:135]
	v_fmac_f32_dpp v64, v235, v130 row_newbcast:12 row_mask:0xf bank_mask:0xf
	v_fmac_f32_dpp v65, v235, v130 row_newbcast:13 row_mask:0xf bank_mask:0xf
	v_fmac_f32_dpp v66, v235, v130 row_newbcast:14 row_mask:0xf bank_mask:0xf
	v_fmac_f32_dpp v67, v235, v130 row_newbcast:15 row_mask:0xf bank_mask:0xf
	s_cbranch_scc1 .LBB0_288
	s_waitcnt vmcnt(0)
	v_mov_b32_e32 v232, v236
	v_mov_b32_e32 v233, v237
	v_mov_b32_e32 v234, v238
	v_mov_b32_e32 v235, v239
	v_mov_b32_e32 v130, v129
	s_branch .LBB0_290

; #define lane LANE_()
; template <int MODE>
; __device__ __forceinline__ void scan_prologue(const ScanP& P, int m0, int seqbase, int T, int h, int d, float* slab, LAS float* lw, float* bon, int lane) {
;     const int fr = lane & 15, fq = lane >> 4, m = m0 + fr, pos = m - seqbase; const bool hp = pos > 0, hn = pos < T - 1;
;     float* srow = slab + fr * 384;
;     f32x4 k4[4], kk4[4], r4[4]; float ss = 0.f;
;     v2u pk_[4][3], pv_[4][3], pr_[4][3];
;     const int offp_ = hp ? -PRP : 0, offn_ = hn ? PRP : 0; const unsigned mp_ = hp ? 0xffffffffu : 0u, mn_ = hn ? 0xffffffffu : 0u;
; #pragma unroll
;     for (int n = 0; n < 4; ++n) { const bf16* p = P.proj + (size_t)m * PRP + h * 64 + 16 * n + 4 * fq;
;         { v2u t; pk_[n][1] = *(const v2u*)(p + 512);
;           t = *(const v2u*)(p + 512 + offp_); pk_[n][0] = (v2u){t.x & mp_, t.y & mp_};
;           t = *(const v2u*)(p + 512 + offn_); pk_[n][2] = (v2u){t.x & mn_, t.y & mn_};
;           if (MODE != 1) { pv_[n][1] = *(const v2u*)(p + 1024);
;             t = *(const v2u*)(p + 1024 + offp_); pv_[n][0] = (v2u){t.x & mp_, t.y & mp_};
;             t = *(const v2u*)(p + 1024 + offn_); pv_[n][2] = (v2u){t.x & mn_, t.y & mn_}; }
;           if (MODE == 2) { pr_[n][1] = *(const v2u*)(p);
;             t = *(const v2u*)(p + offp_); pr_[n][0] = (v2u){t.x & mp_, t.y & mp_};
;             t = *(const v2u*)(p + offn_); pr_[n][2] = (v2u){t.x & mn_, t.y & mn_}; } } }
;     v4u xw_[2]; bf16x8 xa_[2];
; #pragma unroll
;     for (int ks = 0; ks < 2; ++ks) { xw_[ks] = *(const v4u*)(P.proj + (size_t)m * PRP + 1536 + d * 64 + ks * 32 + 8 * fq); xa_[ks] = *(const bf16x8*)(P.proj + (size_t)m * PRP + 1664 + d * 64 + ks * 32 + 8 * fq); }
.LBB0_549:
	s_not_b32 s4, s11
	s_add_i32 s8, s3, s4
	s_and_b64 s[4:5], s[82:83], exec
	s_cselect_b32 s4, s11, s8
	s_lshl_b32 s44, s4, 4
	v_mov_b32_e32 v184, v128
	s_add_i32 s44, s44, s47
	s_lshl_b32 s14, s53, 1
	v_and_b32_e32 v178, 15, v184
	v_or_b32_e32 v138, s44, v178
	v_subrev_u32_e32 v64, s52, v138
	v_ashrrev_i32_e32 v139, 31, v138
	v_ashrrev_i32_e32 v90, 4, v184
	v_cmp_lt_i32_e64 s[4:5], 0, v64
	v_cmp_gt_i32_e32 vcc, s46, v64
	s_waitcnt vmcnt(1)
	v_lshlrev_b64 v[64:65], 12, v[138:139]
	v_lshl_add_u64 v[80:81], s[60:61], 0, v[64:65]
	v_lshlrev_b32_e32 v64, 2, v90
	v_lshl_add_u64 v[68:69], v[80:81], 0, s[14:15]
	v_ashrrev_i32_e32 v65, 31, v64
	v_cndmask_b32_e64 v67, 0, -1, s[4:5]
	v_cndmask_b32_e64 v66, 0, v224, s[4:5]
	v_lshl_add_u64 v[86:87], v[64:65], 1, v[68:69]
	v_lshl_add_u64 v[84:85], v[86:87], 0, v[66:67]
	global_load_dwordx2 v[70:71], v[86:87], off offset:1024
	global_load_dwordx2 v[208:209], v[86:87], off offset:2048
	global_load_dwordx2 v[72:73], v[84:85], off offset:2048
	global_load_dwordx2 v[210:211], v[86:87], off
	global_load_dwordx2 v[76:77], v[84:85], off
	global_load_dwordx2 v[212:213], v[86:87], off offset:1056
	global_load_dwordx2 v[88:89], v[84:85], off offset:1056
	global_load_dwordx2 v[214:215], v[86:87], off offset:2080
	global_load_dwordx2 v[94:95], v[84:85], off offset:2080
	global_load_dwordx2 v[216:217], v[86:87], off offset:32
	global_load_dwordx2 v[100:101], v[84:85], off offset:32
	global_load_dwordx2 v[228:229], v[86:87], off offset:1088
	global_load_dwordx2 v[104:105], v[84:85], off offset:1088
	global_load_dwordx2 v[126:127], v[86:87], off offset:2112
	global_load_dwordx2 v[118:119], v[84:85], off offset:2112
	global_load_dwordx2 v[230:231], v[86:87], off offset:64
	global_load_dwordx2 v[124:125], v[84:85], off offset:64
	global_load_dwordx2 v[232:233], v[86:87], off offset:1120
	global_load_dwordx2 v[154:155], v[84:85], off offset:1120
	global_load_dwordx2 v[234:235], v[86:87], off offset:2144
	global_load_dwordx2 v[164:165], v[84:85], off offset:2144
	global_load_dwordx2 v[236:237], v[86:87], off offset:96
	global_load_dwordx2 v[200:201], v[84:85], off offset:96
	global_load_dwordx2 v[66:67], v[84:85], off offset:1024
	v_cndmask_b32_e32 v180, 0, v219, vcc
	v_lshl_add_u64 v[82:83], v[86:87], 0, v[180:181]
	global_load_dwordx2 v[68:69], v[82:83], off offset:1024
	global_load_dwordx2 v[74:75], v[82:83], off offset:2048
	global_load_dwordx2 v[78:79], v[82:83], off
	global_load_dwordx2 v[92:93], v[82:83], off offset:1056
	global_load_dwordx2 v[98:99], v[82:83], off offset:2080
	global_load_dwordx2 v[102:103], v[82:83], off offset:32
	global_load_dwordx2 v[106:107], v[82:83], off offset:1088
	global_load_dwordx2 v[120:121], v[82:83], off offset:2112
	global_load_dwordx2 v[152:153], v[82:83], off offset:64
	global_load_dwordx2 v[162:163], v[82:83], off offset:1120
	global_load_dwordx2 v[182:183], v[82:83], off offset:2144
	global_load_dwordx2 v[202:203], v[82:83], off offset:96
	s_nop 0
	v_mul_u32_u24_e32 v96, 0x180, v178
	v_lshlrev_b32_e32 v180, 2, v96
	v_lshl_add_u32 v108, v184, 4, s94
	v_lshl_add_u64 v[96:97], s[56:57], 0, v[180:181]
	v_add_u32_e32 v180, 0x2400, v108
	v_add_u32_e32 v108, s53, v64
	v_ashrrev_i32_e32 v109, 31, v108
	v_lshlrev_b64 v[150:151], 2, v[108:109]
	v_lshl_add_u64 v[110:111], s[62:63], 0, v[150:151]
	global_load_dwordx4 v[204:207], v[110:111], off offset:2048
	s_mov_b32 s85, s15
	v_lshlrev_b32_e32 v170, 3, v90
	v_lshl_add_u64 v[80:81], v[80:81], 0, s[84:85]
	v_ashrrev_i32_e32 v171, 31, v170
	v_lshl_add_u64 v[80:81], v[170:171], 1, v[80:81]
	global_load_dwordx4 v[238:241], v[80:81], off offset:3072
	global_load_dwordx4 v[242:245], v[80:81], off offset:3328
	global_load_dwordx4 v[246:249], v[80:81], off offset:3136
	v_lshlrev_b32_e32 v185, 8, v178
	v_lshl_add_u32 v185, v178, 4, v185
	s_waitcnt vmcnt(16)
	v_cndmask_b32_e64 v167, 0, v66, s[4:5]
	v_cndmask_b32_e64 v175, 0, v67, s[4:5]
	s_nop 0
	v_lshlrev_b32_e32 v186, 16, v70
	v_and_b32_e32 v187, 0xffff0000, v70
	v_lshlrev_b32_e32 v70, 16, v71
	v_and_b32_e32 v71, 0xffff0000, v71
	v_lshlrev_b32_e32 v166, 16, v167
	v_and_b32_e32 v167, 0xffff0000, v167
	v_lshlrev_b32_e32 v174, 16, v175
	v_and_b32_e32 v175, 0xffff0000, v175
	s_waitcnt vmcnt(15)
	v_cndmask_b32_e32 v188, 0, v68, vcc
	v_cndmask_b32_e32 v193, 0, v69, vcc
	s_nop 0
	s_nop 0
	v_cndmask_b32_e64 v141, 0, v72, s[4:5]
	v_cndmask_b32_e64 v140, 0, v73, s[4:5]
	s_nop 0
	s_waitcnt vmcnt(14)
	v_cndmask_b32_e32 v117, 0, v74, vcc
	v_cndmask_b32_e32 v116, 0, v75, vcc
	s_nop 0
	s_nop 0
	v_cndmask_b32_e64 v115, 0, v76, s[4:5]
	v_cndmask_b32_e64 v114, 0, v77, s[4:5]
	s_nop 0
	s_waitcnt vmcnt(13)
	v_cndmask_b32_e32 v113, 0, v78, vcc
	v_cndmask_b32_e32 v112, 0, v79, vcc
	global_load_dwordx4 v[76:79], v[110:111], off
	s_nop 0
	s_nop 0
	v_cndmask_b32_e64 v145, 0, v88, s[4:5]
	v_cndmask_b32_e64 v144, 0, v89, s[4:5]
	global_load_dwordx4 v[88:91], v[110:111], off offset:2112
	s_nop 0
	s_waitcnt vmcnt(14)
	v_cndmask_b32_e32 v143, 0, v92, vcc
	v_cndmask_b32_e32 v142, 0, v93, vcc
	s_nop 0
	s_nop 0
	v_cndmask_b32_e64 v157, 0, v94, s[4:5]
	v_cndmask_b32_e64 v156, 0, v95, s[4:5]
	s_nop 0
	s_waitcnt vmcnt(13)
	v_cndmask_b32_e32 v147, 0, v98, vcc
	v_cndmask_b32_e32 v146, 0, v99, vcc
	s_nop 0
	s_nop 0
	v_cndmask_b32_e64 v123, 0, v100, s[4:5]
	v_cndmask_b32_e64 v122, 0, v101, s[4:5]
	s_nop 0
	s_waitcnt vmcnt(12)
	v_cndmask_b32_e32 v99, 0, v102, vcc
	v_cndmask_b32_e32 v98, 0, v103, vcc
	s_nop 0
	s_nop 0
	v_cndmask_b32_e64 v160, 0, v104, s[4:5]
	v_cndmask_b32_e64 v158, 0, v105, s[4:5]
	s_nop 0
	s_waitcnt vmcnt(11)
; #define LAS __attribute__((address_space(3)))
; #define lane LANE_()
; template <int MODE>
; __device__ __forceinline__ void scan_prologue(const ScanP& P, int m0, int seqbase, int T, int h, int d, float* slab, LAS float* lw, float* bon, int lane) {
;     ...
; #pragma unroll
;     for (int n = 0; n < 4; ++n) { const int c = 16 * n + 4 * fq, col = h * 64 + c;
;         k4[n] = CONV3_(pk_, 1);
;         if (MODE != 1) { const f32x4 v4 = CONV3_(pv_, 2); *(f32x4*)(srow + 320 + c) = v4; LAS float* xsel = (fr == (d ? 15 : 0)) ? lw + 2048 + c : lw + 2304 + lane * 4; *(LAS f32x4*)(xsel + 192) = v4; }
;         if (MODE == 2) { r4[n] = CONV3_(pr_, 0); *(LAS f32x4*)(lw + 1024 + fr * 64 + c) = r4[n]; }
;         kk4[n] = k4[n] * *(const f32x4*)(P.k_k + col);
;         ss += (kk4[n].x * kk4[n].x + kk4[n].y * kk4[n].y) + (kk4[n].z * kk4[n].z + kk4[n].w * kk4[n].w); }
	v_cndmask_b32_e32 v149, 0, v106, vcc
	v_cndmask_b32_e32 v148, 0, v107, vcc
	s_nop 0
	s_nop 0
	v_cndmask_b32_e64 v159, 0, v118, s[4:5]
	v_cndmask_b32_e64 v161, 0, v119, s[4:5]
	s_nop 0
	s_waitcnt vmcnt(10)
	v_cndmask_b32_e32 v198, 0, v120, vcc
	v_cndmask_b32_e32 v189, 0, v121, vcc
	s_nop 0
	s_nop 0
	v_cndmask_b32_e64 v173, 0, v124, s[4:5]
	v_cndmask_b32_e64 v172, 0, v125, s[4:5]
	s_nop 0
	s_waitcnt vmcnt(9)
	v_cndmask_b32_e32 v169, 0, v152, vcc
	v_cndmask_b32_e32 v168, 0, v153, vcc
	s_nop 0
	s_nop 0
	v_cndmask_b32_e64 v195, 0, v154, s[4:5]
	v_cndmask_b32_e64 v194, 0, v155, s[4:5]
	s_nop 0
	s_waitcnt vmcnt(8)
	v_cndmask_b32_e32 v197, 0, v162, vcc
	v_cndmask_b32_e32 v196, 0, v163, vcc
	s_nop 0
	s_nop 0
	v_cndmask_b32_e64 v192, 0, v164, s[4:5]
	v_cndmask_b32_e64 v191, 0, v165, s[4:5]
	s_nop 0
	s_nop 0
	s_nop 0
	s_nop 0
	s_waitcnt vmcnt(7)
	v_cndmask_b32_e32 v182, 0, v182, vcc
	s_nop 0
	v_cndmask_b32_e64 v177, 0, v200, s[4:5]
	v_cndmask_b32_e64 v176, 0, v201, s[4:5]
	v_add_co_u32_e64 v124, s[4:5], s45, v110
	v_cndmask_b32_e32 v179, 0, v183, vcc
	s_nop 0
	v_addc_co_u32_e64 v125, s[4:5], 0, v111, s[4:5]
	global_load_dwordx4 v[92:95], v[124:125], off offset:64
	v_add_co_u32_e64 v108, s[4:5], s96, v110
	s_waitcnt vmcnt(7)
	v_cndmask_b32_e32 v190, 0, v202, vcc
	v_cndmask_b32_e32 v183, 0, v203, vcc
	s_nop 0
	s_nop 0
	s_nop 0
	s_nop 0
	global_load_dwordx4 v[80:83], v[80:81], off offset:3392
	v_addc_co_u32_e64 v109, s[4:5], 0, v111, s[4:5]
	global_load_dwordx4 v[152:155], v[108:109], off offset:-4096
	global_load_dwordx4 v[162:165], v[108:109], off offset:2048
	global_load_dwordx4 v[84:87], v[108:109], off
	global_load_dwordx4 v[100:103], v[108:109], off offset:2112
	s_nop 0
	s_nop 0
	s_nop 0
	v_cmp_eq_u32_e32 vcc, s48, v178
	s_waitcnt vmcnt(3)
	v_pk_mul_f32 v[70:71], v[154:155], v[70:71]
	v_pk_mul_f32 v[152:153], v[152:153], v[186:187]
	v_pk_fma_f32 v[70:71], v[206:207], v[174:175], v[70:71]
	v_pk_fma_f32 v[118:119], v[204:205], v[166:167], v[152:153]
	v_lshlrev_b32_e32 v120, 16, v188
	v_and_b32_e32 v121, 0xffff0000, v188
	v_lshl_add_u64 v[174:175], s[70:71], 0, v[150:151]
	global_load_dwordx4 v[72:75], v[174:175], off
	global_load_dwordx4 v[104:107], v[174:175], off offset:64
	s_waitcnt vmcnt(4)
	v_pk_fma_f32 v[154:155], v[162:163], v[120:121], v[118:119]
	v_add_co_u32_e64 v120, s[4:5], s26, v174
	v_lshlrev_b32_e32 v152, 16, v193
	s_nop 0
	v_addc_co_u32_e64 v121, s[4:5], 0, v175, s[4:5]
	global_load_dwordx4 v[200:203], v[120:121], off offset:2048
	v_and_b32_e32 v153, 0xffff0000, v193
	s_nop 0
	v_pk_fma_f32 v[152:153], v[164:165], v[152:153], v[70:71]
	s_nop 0
	v_add_co_u32_e64 v118, s[4:5], s96, v174
	v_lshlrev_b32_e32 v70, 16, v141
	s_nop 0
	v_addc_co_u32_e64 v119, s[4:5], 0, v175, s[4:5]
	global_load_dwordx4 v[204:207], v[118:119], off
	v_and_b32_e32 v71, 0xffff0000, v141
	v_lshlrev_b32_e32 v166, 16, v140
	v_and_b32_e32 v167, 0xffff0000, v140
	v_lshlrev_b32_e32 v140, 16, v208
	v_and_b32_e32 v141, 0xffff0000, v208
	v_lshlrev_b32_e32 v68, 16, v209
	v_and_b32_e32 v69, 0xffff0000, v209
	s_waitcnt vmcnt(1)
	v_pk_mul_f32 v[68:69], v[202:203], v[68:69]
	v_pk_mul_f32 v[140:141], v[200:201], v[140:141]
	global_load_dwordx4 v[200:203], v[120:121], off offset:2112
	v_pk_fma_f32 v[68:69], v[74:75], v[166:167], v[68:69]
	v_and_b32_e32 v166, -16, v184
	v_pk_fma_f32 v[140:141], v[72:73], v[70:71], v[140:141]
	v_lshlrev_b32_e32 v162, 16, v117
	v_and_b32_e32 v163, 0xffff0000, v117
	v_lshlrev_b32_e32 v70, 16, v116
	v_and_b32_e32 v71, 0xffff0000, v116
	v_add_u32_e32 v188, s94, v166
	s_waitcnt vmcnt(1)
	v_pk_fma_f32 v[70:71], v[206:207], v[70:71], v[68:69]
	v_pk_fma_f32 v[68:69], v[204:205], v[162:163], v[140:141]
	global_load_dwordx4 v[204:207], v[118:119], off offset:64
	v_lshl_add_u64 v[140:141], v[64:65], 2, v[96:97]
	v_add_u32_e32 v64, 0x2200, v188
	v_cndmask_b32_e32 v187, v180, v64, vcc
	v_add_co_u32_e64 v116, s[4:5], s26, v110
	global_store_dwordx4 v[140:141], v[68:71], off offset:1280
	ds_write_b128 v187, v[68:71] offset:768
	v_addc_co_u32_e64 v117, s[4:5], 0, v111, s[4:5]
	global_load_dwordx4 v[162:165], v[116:117], off offset:2048
	s_nop 0
	s_nop 0
	s_nop 0
	v_lshlrev_b32_e32 v64, 16, v115
	v_and_b32_e32 v65, 0xffff0000, v115
	v_lshlrev_b32_e32 v96, 16, v114
	v_and_b32_e32 v97, 0xffff0000, v114
	v_lshlrev_b32_e32 v114, 16, v210
	v_and_b32_e32 v115, 0xffff0000, v210
	v_lshlrev_b32_e32 v66, 16, v211
	v_and_b32_e32 v67, 0xffff0000, v211
	global_load_dwordx4 v[208:211], v[110:111], off offset:64
	v_add3_u32 v193, s94, v185, v166
	s_waitcnt vmcnt(1)
	v_pk_mul_f32 v[66:67], v[164:165], v[66:67]
	v_pk_mul_f32 v[114:115], v[162:163], v[114:115]
	v_pk_fma_f32 v[66:67], v[78:79], v[96:97], v[66:67]
	v_pk_fma_f32 v[64:65], v[76:77], v[64:65], v[114:115]
	v_lshlrev_b32_e32 v68, 16, v113
	v_and_b32_e32 v69, 0xffff0000, v113
	v_lshlrev_b32_e32 v70, 16, v112
	v_and_b32_e32 v71, 0xffff0000, v112
	v_lshl_add_u64 v[112:113], s[64:65], 0, v[150:151]
	global_load_dwordx4 v[72:75], v[112:113], off
	v_pk_fma_f32 v[70:71], v[86:87], v[70:71], v[66:67]
	v_pk_fma_f32 v[68:69], v[84:85], v[68:69], v[64:65]
	global_load_dwordx4 v[84:87], v[116:117], off offset:2112
	s_nop 0
	ds_write_b128 v193, v[68:71] offset:4352
	v_lshlrev_b32_e32 v162, 16, v144
	v_and_b32_e32 v163, 0xffff0000, v144
	v_lshlrev_b32_e32 v144, 16, v212
	s_waitcnt vmcnt(1)
; #define LAS __attribute__((address_space(3)))
; #define lane LANE_()
; template <int MODE>
; __device__ __forceinline__ void scan_prologue(const ScanP& P, int m0, int seqbase, int T, int h, int d, float* slab, LAS float* lw, float* bon, int lane) {
;     ...
; #pragma unroll
;     for (int n = 0; n < 4; ++n) { const int c = 16 * n + 4 * fq, col = h * 64 + c;
;         k4[n] = CONV3_(pk_, 1);
;         if (MODE != 1) { const f32x4 v4 = CONV3_(pv_, 2); *(f32x4*)(srow + 320 + c) = v4; LAS float* xsel = (fr == (d ? 15 : 0)) ? lw + 2048 + c : lw + 2304 + lane * 4; *(LAS f32x4*)(xsel + 192) = v4; }
;         if (MODE == 2) { r4[n] = CONV3_(pr_, 0); *(LAS f32x4*)(lw + 1024 + fr * 64 + c) = r4[n]; }
;         kk4[n] = k4[n] * *(const f32x4*)(P.k_k + col);
;         ss += (kk4[n].x * kk4[n].x + kk4[n].y * kk4[n].y) + (kk4[n].z * kk4[n].z + kk4[n].w * kk4[n].w); }
	v_pk_mul_f32 v[164:165], v[152:153], v[74:75]
	v_pk_mul_f32 v[166:167], v[154:155], v[72:73]
	v_pk_mul_f32 v[64:65], v[164:165], v[164:165]
	v_pk_mul_f32 v[66:67], v[166:167], v[166:167]
	s_nop 0
	v_pk_mov_b32 v[96:97], v[66:67], v[64:65] op_sel:[1,0]
	v_mov_b32_e32 v67, v65
	v_pk_add_f32 v[114:115], v[96:97], v[66:67]
	v_lshlrev_b32_e32 v96, 16, v145
	v_and_b32_e32 v97, 0xffff0000, v145
	v_and_b32_e32 v145, 0xffff0000, v212
	v_lshlrev_b32_e32 v78, 16, v213
	v_and_b32_e32 v79, 0xffff0000, v213
	v_pk_mul_f32 v[78:79], v[94:95], v[78:79]
	v_pk_mul_f32 v[144:145], v[92:93], v[144:145]
	global_load_dwordx4 v[92:95], v[108:109], off offset:64
	v_pk_fma_f32 v[66:67], v[90:91], v[162:163], v[78:79]
	v_pk_fma_f32 v[64:65], v[88:89], v[96:97], v[144:145]
	global_load_dwordx4 v[88:91], v[112:113], off offset:64
	v_lshlrev_b32_e32 v78, 16, v143
	v_and_b32_e32 v79, 0xffff0000, v143
	v_lshlrev_b32_e32 v96, 16, v142
	v_and_b32_e32 v97, 0xffff0000, v142
	v_pk_fma_f32 v[142:143], v[102:103], v[96:97], v[66:67]
	v_pk_fma_f32 v[144:145], v[100:101], v[78:79], v[64:65]
	global_load_dwordx4 v[100:103], v[110:111], off offset:2176
	v_lshlrev_b32_e32 v78, 16, v157
	v_and_b32_e32 v79, 0xffff0000, v157
	v_lshlrev_b32_e32 v96, 16, v156
	v_and_b32_e32 v97, 0xffff0000, v156
	v_lshlrev_b32_e32 v156, 16, v214
	v_and_b32_e32 v157, 0xffff0000, v214
	v_lshlrev_b32_e32 v74, 16, v215
	v_and_b32_e32 v75, 0xffff0000, v215
	global_load_dwordx4 v[212:215], v[124:125], off offset:128
	v_pk_mul_f32 v[74:75], v[202:203], v[74:75]
	v_pk_mul_f32 v[156:157], v[200:201], v[156:157]
	global_load_dwordx4 v[200:203], v[108:109], off offset:2176
	v_pk_fma_f32 v[66:67], v[106:107], v[96:97], v[74:75]
	v_pk_fma_f32 v[64:65], v[104:105], v[78:79], v[156:157]
	global_load_dwordx4 v[104:107], v[174:175], off offset:128
	v_lshlrev_b32_e32 v74, 16, v147
	v_and_b32_e32 v75, 0xffff0000, v147
	v_lshlrev_b32_e32 v78, 16, v146
	v_and_b32_e32 v79, 0xffff0000, v146
	v_pk_fma_f32 v[64:65], v[204:205], v[74:75], v[64:65]
	v_add_u32_e32 v74, 0x2240, v188
	v_pk_fma_f32 v[66:67], v[206:207], v[78:79], v[66:67]
	v_cndmask_b32_e32 v186, v180, v74, vcc
	global_store_dwordx4 v[140:141], v[64:67], off offset:1344
	ds_write_b128 v186, v[64:67] offset:768
	s_nop 0
	s_nop 0
	s_nop 0
	v_lshlrev_b32_e32 v96, 16, v216
	v_and_b32_e32 v97, 0xffff0000, v216
	v_lshlrev_b32_e32 v72, 16, v217
	v_and_b32_e32 v73, 0xffff0000, v217
	v_lshlrev_b32_e32 v74, 16, v123
	v_and_b32_e32 v75, 0xffff0000, v123
	v_lshlrev_b32_e32 v78, 16, v122
	v_and_b32_e32 v79, 0xffff0000, v122
	v_lshlrev_b32_e32 v146, 16, v158
	v_and_b32_e32 v147, 0xffff0000, v158
	v_lshlrev_b32_e32 v158, 16, v159
	v_and_b32_e32 v159, 0xffff0000, v159
	s_waitcnt vmcnt(7)
	v_pk_mul_f32 v[72:73], v[86:87], v[72:73]
	v_pk_mul_f32 v[96:97], v[84:85], v[96:97]
	global_load_dwordx4 v[84:87], v[120:121], off offset:2176
	v_pk_fma_f32 v[66:67], v[210:211], v[78:79], v[72:73]
	v_pk_fma_f32 v[64:65], v[208:209], v[74:75], v[96:97]
	global_load_dwordx4 v[206:209], v[118:119], off offset:128
	v_lshlrev_b32_e32 v72, 16, v99
	v_and_b32_e32 v73, 0xffff0000, v99
	v_lshlrev_b32_e32 v74, 16, v98
	v_and_b32_e32 v75, 0xffff0000, v98
	s_waitcnt vmcnt(8)
	v_pk_fma_f32 v[66:67], v[94:95], v[74:75], v[66:67]
	v_pk_fma_f32 v[64:65], v[92:93], v[72:73], v[64:65]
	global_load_dwordx4 v[92:95], v[110:111], off offset:128
	s_nop 0
	ds_write_b128 v193, v[64:67] offset:4416
	v_lshlrev_b32_e32 v204, 16, v228
	v_and_b32_e32 v205, 0xffff0000, v228
	v_lshlrev_b32_e32 v76, 16, v229
	v_and_b32_e32 v77, 0xffff0000, v229
	s_waitcnt vmcnt(8)
	v_pk_mul_f32 v[156:157], v[142:143], v[90:91]
	v_pk_mul_f32 v[162:163], v[144:145], v[88:89]
	global_load_dwordx4 v[88:91], v[116:117], off offset:2176
	v_pk_mul_f32 v[72:73], v[156:157], v[156:157]
	v_pk_mul_f32 v[74:75], v[162:163], v[162:163]
	s_nop 0
	v_pk_mov_b32 v[78:79], v[74:75], v[72:73] op_sel:[1,0]
	v_mov_b32_e32 v75, v73
	v_pk_add_f32 v[122:123], v[78:79], v[74:75]
	v_lshlrev_b32_e32 v78, 16, v160
	v_and_b32_e32 v79, 0xffff0000, v160
	v_lshlrev_b32_e32 v160, 16, v161
	v_and_b32_e32 v161, 0xffff0000, v161
	s_waitcnt vmcnt(7)
	v_pk_mul_f32 v[76:77], v[214:215], v[76:77]
	global_load_dwordx4 v[214:217], v[108:109], off offset:128
	v_pk_mul_f32 v[96:97], v[212:213], v[204:205]
	global_load_dwordx4 v[210:213], v[112:113], off offset:128
	v_pk_fma_f32 v[74:75], v[102:103], v[146:147], v[76:77]
	v_pk_fma_f32 v[72:73], v[100:101], v[78:79], v[96:97]
	v_lshlrev_b32_e32 v76, 16, v149
	v_and_b32_e32 v77, 0xffff0000, v149
	v_lshlrev_b32_e32 v78, 16, v148
	v_and_b32_e32 v79, 0xffff0000, v148
	s_waitcnt vmcnt(8)
	v_pk_fma_f32 v[146:147], v[202:203], v[78:79], v[74:75]
	global_load_dwordx4 v[202:205], v[110:111], off offset:2240
	v_pk_fma_f32 v[148:149], v[200:201], v[76:77], v[72:73]
	v_lshlrev_b32_e32 v200, 16, v126
	v_and_b32_e32 v201, 0xffff0000, v126
	v_lshlrev_b32_e32 v126, 16, v127
	v_and_b32_e32 v127, 0xffff0000, v127
	s_waitcnt vmcnt(6)
	v_pk_mul_f32 v[96:97], v[84:85], v[200:201]
	v_pk_mul_f32 v[98:99], v[86:87], v[126:127]
	global_load_dwordx4 v[84:87], v[124:125], off offset:192
	v_pk_fma_f32 v[76:77], v[104:105], v[158:159], v[96:97]
	v_lshlrev_b32_e32 v96, 16, v198
	v_and_b32_e32 v97, 0xffff0000, v198
	global_load_dwordx4 v[198:201], v[108:109], off offset:2240
	v_pk_fma_f32 v[78:79], v[106:107], v[160:161], v[98:99]
	v_lshlrev_b32_e32 v98, 16, v189
	v_and_b32_e32 v99, 0xffff0000, v189
	s_waitcnt vmcnt(7)
; #define LAS __attribute__((address_space(3)))
; __device__ __forceinline__ float shx(float v, int o, int lane) { return __builtin_bit_cast(float, __builtin_amdgcn_ds_bpermute((lane ^ o) << 2, __builtin_bit_cast(int, v))); }
; #define lane LANE_()
; template <int MODE>
; __device__ __forceinline__ void scan_prologue(const ScanP& P, int m0, int seqbase, int T, int h, int d, float* slab, LAS float* lw, float* bon, int lane) {
;     ...
;     for (int n = 0; n < 4; ++n) { const int c = 16 * n + 4 * fq, col = h * 64 + c;
;         k4[n] = CONV3_(pk_, 1);
;         if (MODE != 1) { const f32x4 v4 = CONV3_(pv_, 2); *(f32x4*)(srow + 320 + c) = v4; LAS float* xsel = (fr == (d ? 15 : 0)) ? lw + 2048 + c : lw + 2304 + lane * 4; *(LAS f32x4*)(xsel + 192) = v4; }
;         if (MODE == 2) { r4[n] = CONV3_(pr_, 0); *(LAS f32x4*)(lw + 1024 + fr * 64 + c) = r4[n]; }
;         kk4[n] = k4[n] * *(const f32x4*)(P.k_k + col);
;         ss += (kk4[n].x * kk4[n].x + kk4[n].y * kk4[n].y) + (kk4[n].z * kk4[n].z + kk4[n].w * kk4[n].w); }
;     ...
;     ss += shx(ss, 16, lane); ss += shx(ss, 32, lane);
;     const float rs = __builtin_amdgcn_rsqf(ss + 1e-12f);
	v_pk_fma_f32 v[72:73], v[206:207], v[96:97], v[76:77]
	v_add_u32_e32 v76, 0x2280, v188
	v_pk_fma_f32 v[74:75], v[208:209], v[98:99], v[78:79]
	global_load_dwordx4 v[206:209], v[174:175], off offset:192
	v_cndmask_b32_e32 v189, v180, v76, vcc
	global_store_dwordx4 v[140:141], v[72:75], off offset:1408
	ds_write_b128 v189, v[72:75] offset:768
	s_nop 0
	s_nop 0
	s_nop 0
	v_lshlrev_b32_e32 v160, 16, v230
	v_and_b32_e32 v161, 0xffff0000, v230
	v_lshlrev_b32_e32 v100, 16, v231
	v_and_b32_e32 v101, 0xffff0000, v231
	global_load_dwordx4 v[228:231], v[120:121], off offset:2240
	v_lshlrev_b32_e32 v126, 16, v173
	v_and_b32_e32 v127, 0xffff0000, v173
	v_lshlrev_b32_e32 v158, 16, v172
	v_and_b32_e32 v159, 0xffff0000, v172
	s_waitcnt vmcnt(8)
	v_pk_mul_f32 v[78:79], v[90:91], v[100:101]
	v_pk_mul_f32 v[76:77], v[88:89], v[160:161]
	global_load_dwordx4 v[88:91], v[118:119], off offset:192
	v_pk_fma_f32 v[74:75], v[94:95], v[158:159], v[78:79]
	v_pk_fma_f32 v[72:73], v[92:93], v[126:127], v[76:77]
	global_load_dwordx4 v[92:95], v[110:111], off offset:192
	v_lshlrev_b32_e32 v76, 16, v169
	v_and_b32_e32 v77, 0xffff0000, v169
	v_lshlrev_b32_e32 v78, 16, v168
	v_and_b32_e32 v79, 0xffff0000, v168
	s_waitcnt vmcnt(9)
	v_pk_fma_f32 v[78:79], v[216:217], v[78:79], v[74:75]
	v_pk_fma_f32 v[76:77], v[214:215], v[76:77], v[72:73]
	global_load_dwordx4 v[214:217], v[116:117], off offset:2240
	s_nop 0
	ds_write_b128 v193, v[76:79] offset:4480
	v_lshlrev_b32_e32 v160, 16, v232
	v_and_b32_e32 v161, 0xffff0000, v232
	v_lshlrev_b32_e32 v102, 16, v233
	v_and_b32_e32 v103, 0xffff0000, v233
	v_lshlrev_b32_e32 v100, 16, v195
	v_and_b32_e32 v101, 0xffff0000, v195
	v_lshlrev_b32_e32 v158, 16, v194
	v_and_b32_e32 v159, 0xffff0000, v194
	s_waitcnt vmcnt(9)
	v_pk_mul_f32 v[168:169], v[146:147], v[212:213]
	v_pk_mul_f32 v[172:173], v[148:149], v[210:211]
	global_load_dwordx4 v[210:213], v[108:109], off offset:192
	s_nop 0
	s_nop 0
	s_nop 0
	s_nop 0
	s_waitcnt vmcnt(8)
	v_pk_mul_f32 v[98:99], v[86:87], v[102:103]
	v_pk_mul_f32 v[96:97], v[84:85], v[160:161]
	global_load_dwordx4 v[84:87], v[112:113], off offset:192
	v_pk_fma_f32 v[74:75], v[204:205], v[158:159], v[98:99]
	v_pk_fma_f32 v[72:73], v[202:203], v[100:101], v[96:97]
	v_lshlrev_b32_e32 v96, 16, v197
	v_and_b32_e32 v97, 0xffff0000, v197
	v_lshlrev_b32_e32 v98, 16, v196
	v_and_b32_e32 v99, 0xffff0000, v196
	s_waitcnt vmcnt(8)
	v_pk_fma_f32 v[158:159], v[200:201], v[98:99], v[74:75]
	v_pk_fma_f32 v[160:161], v[198:199], v[96:97], v[72:73]
	v_lshlrev_b32_e32 v124, 16, v234
	v_and_b32_e32 v125, 0xffff0000, v234
	v_lshlrev_b32_e32 v118, 16, v192
	v_and_b32_e32 v119, 0xffff0000, v192
	v_lshlrev_b32_e32 v106, 16, v235
	v_and_b32_e32 v107, 0xffff0000, v235
	v_lshlrev_b32_e32 v120, 16, v191
	v_and_b32_e32 v121, 0xffff0000, v191
	s_waitcnt vmcnt(5)
	v_pk_mul_f32 v[96:97], v[228:229], v[124:125]
	v_pk_mul_f32 v[98:99], v[230:231], v[106:107]
	v_pk_fma_f32 v[72:73], v[206:207], v[118:119], v[96:97]
	v_lshlrev_b32_e32 v96, 16, v182
	v_and_b32_e32 v97, 0xffff0000, v182
	v_pk_fma_f32 v[74:75], v[208:209], v[120:121], v[98:99]
	v_lshlrev_b32_e32 v98, 16, v179
	v_and_b32_e32 v99, 0xffff0000, v179
	s_waitcnt vmcnt(4)
	v_pk_fma_f32 v[72:73], v[88:89], v[96:97], v[72:73]
	v_add_u32_e32 v96, 0x22c0, v188
	v_pk_fma_f32 v[74:75], v[90:91], v[98:99], v[74:75]
	v_cndmask_b32_e32 v192, v180, v96, vcc
	global_store_dwordx4 v[140:141], v[72:75], off offset:1472
	ds_write_b128 v192, v[72:75] offset:768
	s_nop 0
	s_nop 0
	s_nop 0
	v_lshlrev_b32_e32 v110, 16, v236
	v_and_b32_e32 v111, 0xffff0000, v236
	v_lshlrev_b32_e32 v104, 16, v237
	v_and_b32_e32 v105, 0xffff0000, v237
	v_lshlrev_b32_e32 v106, 16, v177
	v_and_b32_e32 v107, 0xffff0000, v177
	v_lshlrev_b32_e32 v108, 16, v176
	v_and_b32_e32 v109, 0xffff0000, v176
	v_lshl_or_b32 v180, v178, 6, s49
	v_or_b32_e32 v120, 0xc00, v180
	v_mov_b32_e32 v121, v181
	v_lshl_add_u64 v[120:121], v[120:121], 0, v[170:171]
	v_lshlrev_b64 v[124:125], 1, v[120:121]
	v_lshl_add_u64 v[120:121], s[76:77], 0, v[124:125]
	global_load_dwordx4 v[194:197], v[120:121], off
	v_cmp_gt_u32_e32 vcc, 16, v184
	s_waitcnt vmcnt(4)
	v_pk_mul_f32 v[98:99], v[216:217], v[104:105]
	v_pk_mul_f32 v[96:97], v[214:215], v[110:111]
	v_pk_fma_f32 v[74:75], v[94:95], v[108:109], v[98:99]
	v_pk_fma_f32 v[72:73], v[92:93], v[106:107], v[96:97]
	v_lshlrev_b32_e32 v96, 16, v190
	v_and_b32_e32 v97, 0xffff0000, v190
	v_lshlrev_b32_e32 v98, 16, v183
	v_and_b32_e32 v99, 0xffff0000, v183
	s_waitcnt vmcnt(3)
	v_pk_fma_f32 v[74:75], v[212:213], v[98:99], v[74:75]
	v_pk_fma_f32 v[72:73], v[210:211], v[96:97], v[72:73]
	s_nop 0
	ds_write_b128 v193, v[72:75] offset:4544
	v_or_b32_e32 v112, 0x800, v180
	v_mov_b32_e32 v113, v181
	v_lshl_add_u64 v[112:113], v[112:113], 0, v[170:171]
	v_lshlrev_b64 v[116:117], 1, v[112:113]
	v_lshl_add_u64 v[112:113], s[76:77], 0, v[116:117]
	global_load_dwordx4 v[88:91], v[112:113], off
	v_lshl_add_u64 v[116:117], s[78:79], 0, v[116:117]
	global_load_dwordx4 v[116:119], v[116:117], off
	s_waitcnt vmcnt(4)
	v_pk_mul_f32 v[176:177], v[160:161], v[84:85]
	v_pk_mul_f32 v[174:175], v[158:159], v[86:87]
	v_mul_f32_e32 v98, v176, v176
	v_pk_add_f32 v[96:97], v[114:115], v[114:115] op_sel:[0,1] op_sel_hi:[1,0]
	v_mul_f32_e32 v100, v177, v177
	v_mov_b32_e32 v97, v98
	v_pk_add_f32 v[98:99], v[122:123], v[122:123] op_sel:[0,1] op_sel_hi:[1,0]
	v_mul_f32_e32 v101, v174, v174
	v_mov_b32_e32 v99, v100
	v_pk_add_f32 v[96:97], v[96:97], v[98:99]
	v_mul_f32_e32 v98, v173, v173
	v_pk_fma_f32 v[98:99], v[172:173], v[172:173], v[98:99] op_sel_hi:[1,1,0]
	v_mul_f32_e32 v100, v169, v169
	v_mul_f32_e32 v102, v175, v175
	v_mov_b32_e32 v99, v101
	v_pk_fma_f32 v[100:101], v[168:169], v[168:169], v[100:101] op_sel_hi:[1,1,0]
	v_mov_b32_e32 v101, v102
	v_pk_add_f32 v[98:99], v[98:99], v[100:101]
	s_nop 0
	v_pk_add_f32 v[96:97], v[96:97], v[98:99]
	s_nop 0
	v_add_f32_e32 v96, v96, v97
	v_lshlrev_b32_e32 v97, 2, v184
	v_xor_b32_e32 v191, 64, v97
	ds_bpermute_b32 v98, v191, v96
	v_xor_b32_e32 v190, 0x80, v97
	s_waitcnt lgkmcnt(0)
; __device__ __forceinline__ unsigned pk2(float lo, float hi) { const f2 v = {lo, hi}; return __builtin_bit_cast(unsigned, __builtin_convertvector(v, bf16x2_hw)); }
; __device__ __forceinline__ float tanhf_(float x) { return 1.0f - 2.0f * __builtin_amdgcn_rcpf(1.0f + __builtin_amdgcn_exp2f(2.8853900817779268f * x)); }
; __device__ __forceinline__ float shx(float v, int o, int lane) { return __builtin_bit_cast(float, __builtin_amdgcn_ds_bpermute((lane ^ o) << 2, __builtin_bit_cast(int, v))); }
; #define lane LANE_()
; template <int MODE>
; __device__ __forceinline__ void scan_prologue(const ScanP& P, int m0, int seqbase, int T, int h, int d, float* slab, LAS float* lw, float* bon, int lane) {
;     ...
;     ss += shx(ss, 16, lane); ss += shx(ss, 32, lane);
;     const float rs = __builtin_amdgcn_rsqf(ss + 1e-12f);
;     f32x4 Dw[4], Da[4];
; #pragma unroll
;     for (int n = 0; n < 4; ++n) { Dw[n] = (f32x4){0.f, 0.f, 0.f, 0.f}; Da[n] = (f32x4){0.f, 0.f, 0.f, 0.f}; }
; #pragma unroll
;     for (int ks = 0; ks < 2; ++ks) {
;         const v4u xw = xw_[ks]; const bf16x8 xa = xa_[ks];
;         v4u tw;
; #pragma unroll
;         for (int e = 0; e < 4; ++e) tw[e] = pk2(tanhf_(bflo(xw[e])), tanhf_(bfhi(xw[e])));
;         const bf16x8 twv = __builtin_bit_cast(bf16x8, tw);
; #pragma unroll
;         for (int n = 0; n < 4; ++n) { const size_t wo = (size_t)(h * 64 + 16 * n + fr) * 64 + ks * 32 + 8 * fq;
;             Dw[n] = __builtin_amdgcn_mfma_f32_16x16x32_bf16(*(const bf16x8*)(P.upw + wo), twv, Dw[n], 0, 0, 0);
;             Da[n] = __builtin_amdgcn_mfma_f32_16x16x32_bf16(*(const bf16x8*)(P.upa + wo), xa, Da[n], 0, 0, 0); }
;     }
	v_add_f32_e32 v96, v96, v98
	ds_bpermute_b32 v97, v190, v96
	s_waitcnt lgkmcnt(0)
	v_add_f32_e32 v96, v96, v97
	v_add_f32_e32 v193, 0x2b8cbccc, v96
	v_lshlrev_b32_e32 v96, 16, v238
	v_and_b32_e32 v92, 0xffff0000, v238
	v_mul_f32_e32 v92, 0x4038aa3b, v92
	v_exp_f32_e32 v92, v92
	v_mul_f32_e32 v96, 0x4038aa3b, v96
	v_exp_f32_e32 v96, v96
	v_add_f32_e32 v92, 1.0, v92
	v_rcp_f32_e32 v97, v92
	v_lshlrev_b32_e32 v92, 16, v239
	v_and_b32_e32 v93, 0xffff0000, v239
	v_mul_f32_e32 v92, 0x4038aa3b, v92
	v_mul_f32_e32 v93, 0x4038aa3b, v93
	v_exp_f32_e32 v92, v92
	v_exp_f32_e32 v93, v93
	v_add_f32_e32 v96, 1.0, v96
	v_rcp_f32_e32 v96, v96
	v_add_f32_e32 v92, 1.0, v92
	v_add_f32_e32 v93, 1.0, v93
	v_rcp_f32_e32 v92, v92
	v_rcp_f32_e32 v93, v93
	v_pk_fma_f32 v[96:97], v[96:97], 2.0, 1.0 op_sel_hi:[1,0,0] neg_lo:[1,0,0] neg_hi:[1,0,0]
	v_pk_fma_f32 v[92:93], v[92:93], 2.0, 1.0 op_sel_hi:[1,0,0] neg_lo:[1,0,0] neg_hi:[1,0,0]
	s_nop 0
	v_cvt_pk_bf16_f32 v105, v92, v93
	v_lshlrev_b32_e32 v92, 16, v240
	v_and_b32_e32 v93, 0xffff0000, v240
	v_mul_f32_e32 v92, 0x4038aa3b, v92
	v_mul_f32_e32 v93, 0x4038aa3b, v93
	v_exp_f32_e32 v92, v92
	v_exp_f32_e32 v93, v93
	v_cvt_pk_bf16_f32 v104, v96, v97
	v_add_f32_e32 v92, 1.0, v92
	v_add_f32_e32 v93, 1.0, v93
	v_rcp_f32_e32 v92, v92
	v_rcp_f32_e32 v93, v93
	s_nop 0
	v_pk_fma_f32 v[92:93], v[92:93], 2.0, 1.0 op_sel_hi:[1,0,0] neg_lo:[1,0,0] neg_hi:[1,0,0]
	s_nop 0
	v_cvt_pk_bf16_f32 v106, v92, v93
	v_lshlrev_b32_e32 v92, 16, v241
	v_and_b32_e32 v93, 0xffff0000, v241
	v_mul_f32_e32 v92, 0x4038aa3b, v92
	v_mul_f32_e32 v93, 0x4038aa3b, v93
	v_exp_f32_e32 v92, v92
	v_exp_f32_e32 v93, v93
	v_add_f32_e32 v92, 1.0, v92
	v_add_f32_e32 v93, 1.0, v93
	v_rcp_f32_e32 v92, v92
	v_rcp_f32_e32 v93, v93
	s_nop 0
	v_pk_fma_f32 v[92:93], v[92:93], 2.0, 1.0 op_sel_hi:[1,0,0] neg_lo:[1,0,0] neg_hi:[1,0,0]
	s_nop 0
	v_cvt_pk_bf16_f32 v107, v92, v93
	v_lshl_add_u64 v[92:93], v[180:181], 0, v[170:171]
	v_lshlrev_b64 v[96:97], 1, v[92:93]
	v_lshl_add_u64 v[178:179], s[76:77], 0, v[96:97]
	global_load_dwordx4 v[84:87], v[178:179], off offset:2048
	global_load_dwordx4 v[202:205], v[178:179], off offset:64
	global_load_dwordx4 v[210:213], v[178:179], off offset:2112
	global_load_dwordx4 v[92:95], v[178:179], off
	v_lshl_add_u64 v[182:183], s[78:79], 0, v[96:97]
	global_load_dwordx4 v[198:201], v[182:183], off
	global_load_dwordx4 v[100:103], v[182:183], off offset:2048
	global_load_dwordx4 v[206:209], v[182:183], off offset:64
	global_load_dwordx4 v[214:217], v[182:183], off offset:2112
	s_nop 0
	s_waitcnt vmcnt(4)
	v_mfma_f32_16x16x32_bf16 v[108:111], v[92:95], v[104:107], 0
	s_nop 0
	s_nop 0
	v_mfma_f32_16x16x32_bf16 v[96:99], v[84:87], v[104:107], 0
	v_mfma_f32_16x16x32_bf16 v[112:115], v[88:91], v[104:107], 0
	v_mfma_f32_16x16x32_bf16 v[120:123], v[194:197], v[104:107], 0
	v_lshl_add_u64 v[104:105], s[78:79], 0, v[124:125]
	global_load_dwordx4 v[104:107], v[104:105], off
	s_waitcnt vmcnt(4)
	v_mfma_f32_16x16x32_bf16 v[92:95], v[198:201], v[242:245], 0
	s_waitcnt vmcnt(3)
	v_mfma_f32_16x16x32_bf16 v[100:103], v[100:103], v[242:245], 0
	v_mfma_f32_16x16x32_bf16 v[116:119], v[116:119], v[242:245], 0
	s_waitcnt vmcnt(0)
	v_mfma_f32_16x16x32_bf16 v[124:127], v[104:107], v[242:245], 0
	v_lshlrev_b32_e32 v88, 16, v246
	v_and_b32_e32 v84, 0xffff0000, v246
	v_mul_f32_e32 v88, 0x4038aa3b, v88
	v_mul_f32_e32 v84, 0x4038aa3b, v84
	v_exp_f32_e32 v88, v88
	v_exp_f32_e32 v84, v84
	v_add_f32_e32 v88, 1.0, v88
	v_add_f32_e32 v84, 1.0, v84
	v_rcp_f32_e32 v88, v88
	v_rcp_f32_e32 v89, v84
	s_nop 0
	v_pk_fma_f32 v[88:89], v[88:89], 2.0, 1.0 op_sel_hi:[1,0,0] neg_lo:[1,0,0] neg_hi:[1,0,0]
	s_nop 0
	v_cvt_pk_bf16_f32 v84, v88, v89
	v_lshlrev_b32_e32 v88, 16, v247
	v_and_b32_e32 v85, 0xffff0000, v247
	v_mul_f32_e32 v88, 0x4038aa3b, v88
	v_mul_f32_e32 v85, 0x4038aa3b, v85
	v_exp_f32_e32 v88, v88
	v_exp_f32_e32 v85, v85
	v_add_f32_e32 v88, 1.0, v88
	v_add_f32_e32 v85, 1.0, v85
	v_rcp_f32_e32 v88, v88
	v_rcp_f32_e32 v89, v85
	s_nop 0
	v_pk_fma_f32 v[88:89], v[88:89], 2.0, 1.0 op_sel_hi:[1,0,0] neg_lo:[1,0,0] neg_hi:[1,0,0]
	s_nop 0
	v_cvt_pk_bf16_f32 v85, v88, v89
	v_lshlrev_b32_e32 v88, 16, v248
	v_and_b32_e32 v86, 0xffff0000, v248
	v_mul_f32_e32 v88, 0x4038aa3b, v88
	v_mul_f32_e32 v86, 0x4038aa3b, v86
	v_exp_f32_e32 v88, v88
	v_exp_f32_e32 v86, v86
	v_add_f32_e32 v88, 1.0, v88
	v_add_f32_e32 v86, 1.0, v86
	v_rcp_f32_e32 v88, v88
	v_rcp_f32_e32 v89, v86
	s_nop 0
	v_pk_fma_f32 v[88:89], v[88:89], 2.0, 1.0 op_sel_hi:[1,0,0] neg_lo:[1,0,0] neg_hi:[1,0,0]
	s_nop 0
	v_cvt_pk_bf16_f32 v86, v88, v89
	v_lshlrev_b32_e32 v88, 16, v249
	v_and_b32_e32 v87, 0xffff0000, v249
	v_mul_f32_e32 v88, 0x4038aa3b, v88
	v_mul_f32_e32 v87, 0x4038aa3b, v87
	v_exp_f32_e32 v88, v88
	v_exp_f32_e32 v87, v87
	v_add_f32_e32 v88, 1.0, v88
	v_add_f32_e32 v87, 1.0, v87
	v_rcp_f32_e32 v88, v88
	v_rcp_f32_e32 v89, v87
	s_nop 0
	v_pk_fma_f32 v[88:89], v[88:89], 2.0, 1.0 op_sel_hi:[1,0,0] neg_lo:[1,0,0] neg_hi:[1,0,0]
	s_nop 0
	v_cvt_pk_bf16_f32 v87, v88, v89
	s_nop 0
	v_mfma_f32_16x16x32_bf16 v[104:107], v[202:205], v[84:87], v[108:111]
	s_nop 0
	v_mfma_f32_16x16x32_bf16 v[108:111], v[206:209], v[80:83], v[92:95]
	s_nop 0
	v_lshl_add_u64 v[178:179], s[66:67], 0, v[150:151]
	global_load_dwordx4 v[198:201], v[178:179], off
	global_load_dwordx4 v[202:205], v[178:179], off offset:64
	global_load_dwordx4 v[232:235], v[178:179], off offset:128
	global_load_dwordx4 v[236:239], v[178:179], off offset:192
	v_mfma_f32_16x16x32_bf16 v[96:99], v[210:213], v[84:87], v[96:99]
	s_nop 0
	v_mfma_f32_16x16x32_bf16 v[100:103], v[214:217], v[80:83], v[100:103]
	v_or_b32_e32 v88, 0x820, v180
	v_mov_b32_e32 v89, v181
	v_lshl_add_u64 v[88:89], v[88:89], 0, v[170:171]
	v_lshlrev_b64 v[92:93], 1, v[88:89]
	v_lshl_add_u64 v[88:89], s[76:77], 0, v[92:93]
	global_load_dwordx4 v[88:91], v[88:89], off
	v_lshl_add_u64 v[92:93], s[78:79], 0, v[92:93]
	global_load_dwordx4 v[92:95], v[92:93], off
	v_or_b32_e32 v180, 0xc20, v180
	s_waitcnt vmcnt(1)
; #define LAS __attribute__((address_space(3)))
; __device__ __forceinline__ float sigmoidf_(float x) { return __builtin_amdgcn_rcpf(1.0f + __builtin_amdgcn_exp2f(-1.4426950408889634f * x)); }
; __device__ __forceinline__ float shx(float v, int o, int lane) { return __builtin_bit_cast(float, __builtin_amdgcn_ds_bpermute((lane ^ o) << 2, __builtin_bit_cast(int, v))); }
; #define lane LANE_()
; template <int MODE>
; __device__ __forceinline__ void scan_prologue(const ScanP& P, int m0, int seqbase, int T, int h, int d, float* slab, LAS float* lw, float* bon, int lane) {
;     ...
;     float bp = 0.f;
; #pragma unroll
;     for (int n = 0; n < 4; ++n) { const int c = 16 * n + 4 * fq, col = h * 64 + c;
;         const f32x4 w0 = *(const f32x4*)(P.w0 + col), a0 = *(const f32x4*)(P.a0 + col), ka = *(const f32x4*)(P.k_a + col);
;         f32x4 wv, bv, kd, av;
; #pragma unroll
;         for (int i = 0; i < 4; ++i) { const float ic = sigmoidf_(Da[n][i] + a0[i]);
;             wv[i] = __builtin_amdgcn_exp2f(-DECAY_SCALE * 1.4426950408889634f * sigmoidf_(Dw[n][i] + w0[i]));
;             const float kk = kk4[n][i] * rs; av[i] = -kk; bv[i] = kk * ic; kd[i] = k4[n][i] * (1.0f + (ic - 1.0f) * ka[i]); }
;         *(LAS f32x4*)(lw + fr * 64 + c) = av; *(LAS f32x4*)(lw + 3072 + fr * 64 + c) = wv; *(LAS f32x4*)(lw + (MODE == 3 ? 1024 : 4096) + fr * 64 + c) = bv;
;         if (MODE != 1) *(f32x4*)(srow + 192 + c) = kd;
;         { LAS float* xsel = (fr == (d ? 15 : 0)) ? lw + 2048 + c : lw + 2304 + lane * 4;
;           if (MODE != 1) *(LAS f32x4*)(xsel + 128) = kd; }
;         if (MODE == 2) { const f32x4 rk = *(const f32x4*)(P.r_k + col); const f32x4 t = r4[n] * kd * rk; bp += (t.x + t.y) + (t.z + t.w); }
;         if ((n & 1) == 1) asm volatile("" ::: "memory");
;     }
;     if (MODE == 2) { bp += shx(bp, 16, lane); bp += shx(bp, 32, lane); if (fq == 0) bon[(size_t)m * 8 + h] = 0.5f * bp; }
	v_mfma_f32_16x16x32_bf16 v[88:91], v[88:91], v[84:87], v[112:115]
	s_nop 2
	v_lshl_add_u64 v[112:113], v[180:181], 0, v[170:171]
	v_lshl_add_u64 v[170:171], s[74:75], 0, v[150:151]
	global_load_dwordx4 v[194:197], v[170:171], off
	global_load_dwordx4 v[206:209], v[170:171], off offset:64
	global_load_dwordx4 v[228:231], v[170:171], off offset:128
	global_load_dwordx4 v[240:243], v[170:171], off offset:192
	s_waitcnt vmcnt(4)
	v_mfma_f32_16x16x32_bf16 v[92:95], v[92:95], v[80:83], v[116:119]
	s_nop 2
	v_lshlrev_b64 v[116:117], 1, v[112:113]
	v_lshl_add_u64 v[112:113], s[76:77], 0, v[116:117]
	global_load_dwordx4 v[112:115], v[112:113], off
	s_waitcnt vmcnt(0)
	v_mfma_f32_16x16x32_bf16 v[84:87], v[112:115], v[84:87], v[120:123]
	v_lshl_add_u64 v[112:113], s[78:79], 0, v[116:117]
	global_load_dwordx4 v[112:115], v[112:113], off
	s_nop 0
	s_nop 0
	s_waitcnt vmcnt(0)
	v_mfma_f32_16x16x32_bf16 v[80:83], v[112:115], v[80:83], v[124:127]
	s_nop 2
	v_lshl_add_u64 v[126:127], s[72:73], 0, v[150:151]
	global_load_dwordx4 v[210:213], v[126:127], off offset:64
	global_load_dwordx4 v[214:217], v[126:127], off offset:128
	global_load_dwordx4 v[244:247], v[126:127], off offset:192
	global_load_dwordx4 v[112:115], v[126:127], off
	s_nop 0
	v_add_f32_e32 v108, v108, v194
	v_add_f32_e32 v110, v110, v196
	v_mul_f32_e32 v108, 0xbfb8aa3b, v108
	v_mul_f32_e32 v110, 0xbfb8aa3b, v110
	v_exp_f32_e32 v108, v108
	v_exp_f32_e32 v110, v110
	v_rsq_f32_e32 v124, v193
	v_add_f32_e32 v108, 1.0, v108
	v_add_f32_e32 v110, 1.0, v110
	v_rcp_f32_e32 v182, v108
	v_add_f32_e32 v108, v109, v195
	v_mul_f32_e32 v108, 0xbfb8aa3b, v108
	v_exp_f32_e32 v108, v108
	s_waitcnt vmcnt(0)
	v_add_f32_e32 v104, v104, v112
	v_add_f32_e32 v105, v105, v113
	v_add_f32_e32 v106, v106, v114
	v_add_f32_e32 v107, v107, v115
	v_mul_f32_e32 v104, 0xbfb8aa3b, v104
	v_mul_f32_e32 v105, 0xbfb8aa3b, v105
	v_pk_mul_f32 v[112:113], v[166:167], v[124:125] op_sel_hi:[1,0]
	v_rcp_f32_e32 v166, v110
	v_mul_f32_e32 v106, 0xbfb8aa3b, v106
	v_add_f32_e32 v110, v111, v197
	v_mul_f32_e32 v107, 0xbfb8aa3b, v107
	v_exp_f32_e32 v104, v104
	v_exp_f32_e32 v105, v105
	v_exp_f32_e32 v106, v106
	v_mul_f32_e32 v110, 0xbfb8aa3b, v110
	v_exp_f32_e32 v107, v107
	v_exp_f32_e32 v110, v110
	v_add_f32_e32 v104, 1.0, v104
	v_add_f32_e32 v105, 1.0, v105
	v_add_f32_e32 v106, 1.0, v106
	v_add_f32_e32 v107, 1.0, v107
	v_rcp_f32_e32 v104, v104
	v_add_f32_e32 v108, 1.0, v108
	v_rcp_f32_e32 v105, v105
	v_rcp_f32_e32 v106, v106
	v_add_f32_e32 v110, 1.0, v110
	v_rcp_f32_e32 v107, v107
	v_rcp_f32_e32 v183, v108
	v_rcp_f32_e32 v167, v110
	v_mul_f32_e32 v104, 0xbf60028a, v104
	v_mul_f32_e32 v105, 0xbf60028a, v105
	v_mul_f32_e32 v106, 0xbf60028a, v106
	v_mul_f32_e32 v107, 0xbf60028a, v107
	v_pk_mul_f32 v[114:115], v[164:165], v[124:125] op_sel_hi:[1,0]
	v_exp_f32_e32 v104, v104
	v_exp_f32_e32 v105, v105
	v_xor_b32_e32 v109, 0x80000000, v113
	v_xor_b32_e32 v108, 0x80000000, v112
	v_exp_f32_e32 v106, v106
	v_exp_f32_e32 v107, v107
	v_xor_b32_e32 v110, 0x80000000, v114
	v_xor_b32_e32 v111, 0x80000000, v115
	v_pk_mul_f32 v[116:117], v[112:113], v[182:183]
	v_pk_mul_f32 v[118:119], v[114:115], v[166:167]
	v_pk_add_f32 v[112:113], v[166:167], -1.0 op_sel_hi:[1,0]
	v_pk_add_f32 v[114:115], v[182:183], -1.0 op_sel_hi:[1,0]
	v_pk_fma_f32 v[112:113], v[200:201], v[112:113], 1.0 op_sel_hi:[1,1,0]
	v_pk_fma_f32 v[114:115], v[198:199], v[114:115], 1.0 op_sel_hi:[1,1,0]
	v_pk_mul_f32 v[122:123], v[152:153], v[112:113]
	v_pk_mul_f32 v[120:121], v[154:155], v[114:115]
	v_add_u32_e32 v114, v188, v185
	ds_write_b128 v114, v[108:111]
	ds_write_b128 v114, v[104:107] offset:11520
	ds_write_b128 v114, v[116:119] offset:15872
	global_store_dwordx4 v[140:141], v[120:123], off offset:768
	v_lshl_add_u64 v[112:113], s[68:69], 0, v[150:151]
	global_load_dwordx4 v[116:119], v[112:113], off offset:64
	global_load_dwordx4 v[150:153], v[112:113], off offset:128
	global_load_dwordx4 v[164:167], v[112:113], off offset:192
	global_load_dwordx4 v[104:107], v[112:113], off
	v_pk_mul_f32 v[70:71], v[70:71], v[122:123]
	v_pk_mul_f32 v[68:69], v[68:69], v[120:121]
	ds_write_b128 v187, v[120:123] offset:512
	s_waitcnt vmcnt(0)
	v_pk_mul_f32 v[70:71], v[106:107], v[70:71]
	v_pk_mul_f32 v[68:69], v[104:105], v[68:69]
	s_nop 0
	v_add_f32_e32 v68, v68, v69
	v_add_f32_e32 v69, v70, v71
	v_add_f32_e32 v68, v68, v69
	v_add_f32_e32 v115, 0, v68
	v_add_f32_e32 v100, v100, v206
	v_add_f32_e32 v96, v96, v210
	v_add_f32_e32 v97, v97, v211
	v_add_f32_e32 v98, v98, v212
	v_add_f32_e32 v99, v99, v213
	v_mul_f32_e32 v96, 0xbfb8aa3b, v96
	v_add_f32_e32 v101, v101, v207
	v_mul_f32_e32 v97, 0xbfb8aa3b, v97
	v_add_f32_e32 v102, v102, v208
	v_mul_f32_e32 v98, 0xbfb8aa3b, v98
	v_add_f32_e32 v103, v103, v209
	v_mul_f32_e32 v99, 0xbfb8aa3b, v99
	v_mul_f32_e32 v100, 0xbfb8aa3b, v100
	v_exp_f32_e32 v96, v96
	v_mul_f32_e32 v101, 0xbfb8aa3b, v101
	v_exp_f32_e32 v97, v97
	v_mul_f32_e32 v102, 0xbfb8aa3b, v102
	v_exp_f32_e32 v98, v98
	v_mul_f32_e32 v103, 0xbfb8aa3b, v103
	v_exp_f32_e32 v99, v99
	v_exp_f32_e32 v100, v100
	v_exp_f32_e32 v101, v101
	v_exp_f32_e32 v102, v102
	v_exp_f32_e32 v103, v103
	v_add_f32_e32 v96, 1.0, v96
	v_add_f32_e32 v97, 1.0, v97
	v_add_f32_e32 v98, 1.0, v98
	v_add_f32_e32 v99, 1.0, v99
	v_add_f32_e32 v100, 1.0, v100
	v_rcp_f32_e32 v96, v96
	v_add_f32_e32 v101, 1.0, v101
	v_rcp_f32_e32 v97, v97
	v_add_f32_e32 v102, 1.0, v102
	v_rcp_f32_e32 v98, v98
	v_add_f32_e32 v103, 1.0, v103
	v_rcp_f32_e32 v99, v99
	v_rcp_f32_e32 v100, v100
	v_rcp_f32_e32 v101, v101
	v_rcp_f32_e32 v102, v102
	v_rcp_f32_e32 v103, v103
	v_mul_f32_e32 v96, 0xbf60028a, v96
	v_mul_f32_e32 v97, 0xbf60028a, v97
; #define LAS __attribute__((address_space(3)))
; __device__ __forceinline__ float sigmoidf_(float x) { return __builtin_amdgcn_rcpf(1.0f + __builtin_amdgcn_exp2f(-1.4426950408889634f * x)); }
; __device__ __forceinline__ float shx(float v, int o, int lane) { return __builtin_bit_cast(float, __builtin_amdgcn_ds_bpermute((lane ^ o) << 2, __builtin_bit_cast(int, v))); }
; #define lane LANE_()
; template <int MODE>
; __device__ __forceinline__ void scan_prologue(const ScanP& P, int m0, int seqbase, int T, int h, int d, float* slab, LAS float* lw, float* bon, int lane) {
;     ...
;     for (int n = 0; n < 4; ++n) { const int c = 16 * n + 4 * fq, col = h * 64 + c;
;         const f32x4 w0 = *(const f32x4*)(P.w0 + col), a0 = *(const f32x4*)(P.a0 + col), ka = *(const f32x4*)(P.k_a + col);
;         f32x4 wv, bv, kd, av;
; #pragma unroll
;         for (int i = 0; i < 4; ++i) { const float ic = sigmoidf_(Da[n][i] + a0[i]);
;             wv[i] = __builtin_amdgcn_exp2f(-DECAY_SCALE * 1.4426950408889634f * sigmoidf_(Dw[n][i] + w0[i]));
;             const float kk = kk4[n][i] * rs; av[i] = -kk; bv[i] = kk * ic; kd[i] = k4[n][i] * (1.0f + (ic - 1.0f) * ka[i]); }
;         *(LAS f32x4*)(lw + fr * 64 + c) = av; *(LAS f32x4*)(lw + 3072 + fr * 64 + c) = wv; *(LAS f32x4*)(lw + (MODE == 3 ? 1024 : 4096) + fr * 64 + c) = bv;
;         if (MODE != 1) *(f32x4*)(srow + 192 + c) = kd;
;         { LAS float* xsel = (fr == (d ? 15 : 0)) ? lw + 2048 + c : lw + 2304 + lane * 4;
;           if (MODE != 1) *(LAS f32x4*)(xsel + 128) = kd; }
;         if (MODE == 2) { const f32x4 rk = *(const f32x4*)(P.r_k + col); const f32x4 t = r4[n] * kd * rk; bp += (t.x + t.y) + (t.z + t.w); }
;         if ((n & 1) == 1) asm volatile("" ::: "memory");
;     }
;     if (MODE == 2) { bp += shx(bp, 16, lane); bp += shx(bp, 32, lane); if (fq == 0) bon[(size_t)m * 8 + h] = 0.5f * bp; }
	v_pk_mul_f32 v[108:109], v[162:163], v[124:125] op_sel_hi:[1,0]
	v_mul_f32_e32 v98, 0xbf60028a, v98
	v_mul_f32_e32 v99, 0xbf60028a, v99
	v_pk_mul_f32 v[110:111], v[156:157], v[124:125] op_sel_hi:[1,0]
	v_exp_f32_e32 v96, v96
	v_exp_f32_e32 v97, v97
	v_xor_b32_e32 v105, 0x80000000, v109
	v_xor_b32_e32 v104, 0x80000000, v108
	v_exp_f32_e32 v98, v98
	v_exp_f32_e32 v99, v99
	v_xor_b32_e32 v106, 0x80000000, v110
	v_xor_b32_e32 v107, 0x80000000, v111
	v_pk_mul_f32 v[108:109], v[108:109], v[100:101]
	v_pk_mul_f32 v[110:111], v[110:111], v[102:103]
	v_pk_add_f32 v[102:103], v[102:103], -1.0 op_sel_hi:[1,0]
	v_pk_add_f32 v[100:101], v[100:101], -1.0 op_sel_hi:[1,0]
	v_pk_fma_f32 v[70:71], v[204:205], v[102:103], 1.0 op_sel_hi:[1,1,0]
	v_pk_fma_f32 v[68:69], v[202:203], v[100:101], 1.0 op_sel_hi:[1,1,0]
	v_pk_mul_f32 v[70:71], v[142:143], v[70:71]
	v_pk_mul_f32 v[68:69], v[144:145], v[68:69]
	ds_write_b128 v114, v[104:107] offset:64
	ds_write_b128 v114, v[96:99] offset:11584
	ds_write_b128 v114, v[108:111] offset:15936
	global_store_dwordx4 v[140:141], v[68:71], off offset:832
	s_nop 0
	v_pk_mul_f32 v[66:67], v[66:67], v[70:71]
	v_pk_mul_f32 v[64:65], v[64:65], v[68:69]
	ds_write_b128 v186, v[68:71] offset:512
	v_pk_mul_f32 v[66:67], v[118:119], v[66:67]
	v_pk_mul_f32 v[64:65], v[116:117], v[64:65]
	s_nop 0
	v_add_f32_e32 v64, v64, v65
	v_add_f32_e32 v65, v66, v67
	v_add_f32_e32 v64, v64, v65
	v_add_f32_e32 v100, v115, v64
	v_add_f32_e32 v68, v88, v214
	v_add_f32_e32 v69, v89, v215
	v_add_f32_e32 v70, v90, v216
	v_add_f32_e32 v71, v91, v217
	v_add_f32_e32 v92, v92, v228
	v_mul_f32_e32 v68, 0xbfb8aa3b, v68
	v_add_f32_e32 v88, v93, v229
	v_mul_f32_e32 v69, 0xbfb8aa3b, v69
	v_add_f32_e32 v94, v94, v230
	v_mul_f32_e32 v70, 0xbfb8aa3b, v70
	v_add_f32_e32 v90, v95, v231
	v_mul_f32_e32 v71, 0xbfb8aa3b, v71
	v_mul_f32_e32 v92, 0xbfb8aa3b, v92
	v_exp_f32_e32 v68, v68
	v_mul_f32_e32 v88, 0xbfb8aa3b, v88
	v_exp_f32_e32 v69, v69
	v_mul_f32_e32 v94, 0xbfb8aa3b, v94
	v_exp_f32_e32 v70, v70
	v_mul_f32_e32 v90, 0xbfb8aa3b, v90
	v_exp_f32_e32 v71, v71
	v_exp_f32_e32 v92, v92
	v_exp_f32_e32 v88, v88
	v_exp_f32_e32 v94, v94
	v_exp_f32_e32 v90, v90
	v_add_f32_e32 v68, 1.0, v68
	v_add_f32_e32 v69, 1.0, v69
	v_add_f32_e32 v70, 1.0, v70
	v_add_f32_e32 v71, 1.0, v71
	v_add_f32_e32 v92, 1.0, v92
	v_rcp_f32_e32 v68, v68
	v_add_f32_e32 v88, 1.0, v88
	v_rcp_f32_e32 v69, v69
	v_add_f32_e32 v94, 1.0, v94
	v_rcp_f32_e32 v70, v70
	v_add_f32_e32 v90, 1.0, v90
	v_rcp_f32_e32 v71, v71
	v_rcp_f32_e32 v96, v92
	v_rcp_f32_e32 v97, v88
	v_rcp_f32_e32 v98, v94
	v_rcp_f32_e32 v99, v90
	v_mul_f32_e32 v68, 0xbf60028a, v68
	v_mul_f32_e32 v69, 0xbf60028a, v69
	v_pk_mul_f32 v[92:93], v[172:173], v[124:125] op_sel_hi:[1,0]
	v_mul_f32_e32 v70, 0xbf60028a, v70
	v_mul_f32_e32 v71, 0xbf60028a, v71
	v_pk_mul_f32 v[94:95], v[168:169], v[124:125] op_sel_hi:[1,0]
	v_exp_f32_e32 v68, v68
	v_exp_f32_e32 v69, v69
	v_xor_b32_e32 v89, 0x80000000, v93
	v_xor_b32_e32 v88, 0x80000000, v92
	v_exp_f32_e32 v70, v70
	v_exp_f32_e32 v71, v71
	v_xor_b32_e32 v90, 0x80000000, v94
	v_xor_b32_e32 v91, 0x80000000, v95
	v_pk_mul_f32 v[92:93], v[92:93], v[96:97]
	v_pk_mul_f32 v[94:95], v[94:95], v[98:99]
	v_pk_add_f32 v[98:99], v[98:99], -1.0 op_sel_hi:[1,0]
	v_pk_add_f32 v[96:97], v[96:97], -1.0 op_sel_hi:[1,0]
	v_pk_fma_f32 v[66:67], v[234:235], v[98:99], 1.0 op_sel_hi:[1,1,0]
	v_pk_fma_f32 v[64:65], v[232:233], v[96:97], 1.0 op_sel_hi:[1,1,0]
	v_pk_mul_f32 v[66:67], v[146:147], v[66:67]
	v_pk_mul_f32 v[64:65], v[148:149], v[64:65]
	ds_write_b128 v114, v[88:91] offset:128
	ds_write_b128 v114, v[68:71] offset:11648
	ds_write_b128 v114, v[92:95] offset:16000
	global_store_dwordx4 v[140:141], v[64:67], off offset:896
	s_nop 0
	ds_write_b128 v189, v[64:67] offset:512
	v_pk_mul_f32 v[66:67], v[78:79], v[66:67]
	v_pk_mul_f32 v[64:65], v[76:77], v[64:65]
	v_pk_mul_f32 v[66:67], v[152:153], v[66:67]
	v_pk_mul_f32 v[64:65], v[150:151], v[64:65]
	s_nop 0
	v_add_f32_e32 v64, v64, v65
	v_add_f32_e32 v65, v66, v67
	v_add_f32_e32 v64, v64, v65
	v_add_f32_e32 v76, v100, v64
	v_add_f32_e32 v68, v80, v240
	v_add_f32_e32 v69, v81, v241
	v_add_f32_e32 v70, v82, v242
	v_add_f32_e32 v71, v83, v243
	v_mul_f32_e32 v68, 0xbfb8aa3b, v68
	v_mul_f32_e32 v69, 0xbfb8aa3b, v69
	v_mul_f32_e32 v70, 0xbfb8aa3b, v70
	v_mul_f32_e32 v71, 0xbfb8aa3b, v71
	v_exp_f32_e32 v68, v68
	v_exp_f32_e32 v69, v69
	v_exp_f32_e32 v70, v70
	v_exp_f32_e32 v71, v71
	v_add_f32_e32 v68, 1.0, v68
	v_add_f32_e32 v69, 1.0, v69
	v_add_f32_e32 v70, 1.0, v70
	v_add_f32_e32 v71, 1.0, v71
	v_rcp_f32_e32 v92, v68
	v_add_f32_e32 v68, v84, v244
	v_rcp_f32_e32 v93, v69
	v_add_f32_e32 v69, v85, v245
	v_rcp_f32_e32 v88, v70
	v_add_f32_e32 v70, v86, v246
	v_rcp_f32_e32 v89, v71
	v_add_f32_e32 v71, v87, v247
	v_mul_f32_e32 v68, 0xbfb8aa3b, v68
	v_mul_f32_e32 v69, 0xbfb8aa3b, v69
	v_mul_f32_e32 v70, 0xbfb8aa3b, v70
	v_mul_f32_e32 v71, 0xbfb8aa3b, v71
	v_exp_f32_e32 v68, v68
	v_exp_f32_e32 v69, v69
	v_exp_f32_e32 v70, v70
	v_exp_f32_e32 v71, v71
	v_add_f32_e32 v68, 1.0, v68
	v_add_f32_e32 v69, 1.0, v69
	v_add_f32_e32 v70, 1.0, v70
	v_add_f32_e32 v71, 1.0, v71
	v_rcp_f32_e32 v68, v68
	v_rcp_f32_e32 v69, v69
	v_rcp_f32_e32 v70, v70
	v_rcp_f32_e32 v71, v71
	v_mul_f32_e32 v68, 0xbf60028a, v68
	v_mul_f32_e32 v69, 0xbf60028a, v69
	v_pk_mul_f32 v[84:85], v[176:177], v[124:125] op_sel_hi:[1,0]
	v_mul_f32_e32 v70, 0xbf60028a, v70
	v_mul_f32_e32 v71, 0xbf60028a, v71
	v_pk_mul_f32 v[86:87], v[174:175], v[124:125] op_sel_hi:[1,0]
	v_exp_f32_e32 v68, v68
	v_exp_f32_e32 v69, v69
	v_xor_b32_e32 v79, 0x80000000, v85
	v_xor_b32_e32 v78, 0x80000000, v84
	v_exp_f32_e32 v70, v70
	v_exp_f32_e32 v71, v71
	v_xor_b32_e32 v80, 0x80000000, v86
	v_xor_b32_e32 v81, 0x80000000, v87
	v_pk_mul_f32 v[82:83], v[84:85], v[92:93]
	v_pk_mul_f32 v[84:85], v[86:87], v[88:89]
	v_pk_add_f32 v[86:87], v[88:89], -1.0 op_sel_hi:[1,0]
	v_pk_add_f32 v[88:89], v[92:93], -1.0 op_sel_hi:[1,0]
	v_pk_fma_f32 v[66:67], v[238:239], v[86:87], 1.0 op_sel_hi:[1,1,0]
	v_pk_fma_f32 v[64:65], v[236:237], v[88:89], 1.0 op_sel_hi:[1,1,0]
	v_pk_mul_f32 v[66:67], v[158:159], v[66:67]
	v_pk_mul_f32 v[64:65], v[160:161], v[64:65]
	ds_write_b128 v114, v[78:81] offset:192
	ds_write_b128 v114, v[68:71] offset:11712
	ds_write_b128 v114, v[82:85] offset:16064
	global_store_dwordx4 v[140:141], v[64:67], off offset:960
	s_nop 0
	ds_write_b128 v192, v[64:67] offset:512
	v_pk_mul_f32 v[66:67], v[74:75], v[66:67]
	v_pk_mul_f32 v[64:65], v[72:73], v[64:65]
	v_pk_mul_f32 v[66:67], v[166:167], v[66:67]
	v_pk_mul_f32 v[64:65], v[164:165], v[64:65]
	s_nop 0
	v_add_f32_e32 v64, v64, v65
	v_add_f32_e32 v65, v66, v67
	v_add_f32_e32 v64, v64, v65
	v_add_f32_e32 v64, v76, v64
	ds_bpermute_b32 v65, v191, v64
	s_waitcnt lgkmcnt(0)
	v_add_f32_e32 v64, v64, v65
	ds_bpermute_b32 v65, v190, v64
	s_and_saveexec_b64 s[4:5], vcc
	s_cbranch_execz .LBB0_551
	s_waitcnt lgkmcnt(0)
	v_add_f32_e32 v64, v64, v65
	v_mul_f32_e32 v66, 0.5, v64
	v_lshlrev_b64 v[64:65], 5, v[138:139]
	v_lshl_add_u64 v[64:65], s[80:81], 0, v[64:65]
	global_store_dword v[64:65], v66, off
; #define GAS __attribute__((address_space(1)))
; #define LAS __attribute__((address_space(3)))
; #define LDS_WAIT() asm volatile("s_waitcnt lgkmcnt(0)" ::: "memory")
; #define lane LANE_()
; template <int MODE>
; __device__ __forceinline__ void scan_item(const CAS Args* A, int l, int item, float* slab0, LAS float* ldsw, int lane) {
;     ...
;         asm volatile("" ::: "memory");
;     ...
;         const GAS float* sl = (const GAS float*)slab + lane;
;         LDS_WAIT();
;         float nw[1], nb[1], nk[1], nv[1];
;         { const LAS float* xl = ldsw + 2048 + lane; nw[0] = 0.f; nb[0] = 0.f; nk[0] = 0.f; nv[0] = 0.f; if (MODE != 1) { nk[0] = xl[128]; nv[0] = xl[192]; } }
; #pragma nounroll
;         for (int st = 0; st < 16; ++st) {
;             const int s = d ? 15 - st : st;
;             const float cw = nw[0], cb = nb[0], ck = nk[0], vv = nv[0];
;             if (st < 15) { const GAS float* p = sl + (d ? s - 1 : s + 1) * 384;  if (MODE != 1) { nk[0] = p[192]; nv[0] = p[320]; } }
;             const LAS f32x4* ua = (const LAS f32x4*)(ldsw + s * 64); const LAS f32x4* ur = (const LAS f32x4*)(ldsw + 1024 + s * 64); const LAS f32x4* uw = (const LAS f32x4*)(ldsw + 3072 + s * 64); const LAS f32x4* ub = (const LAS f32x4*)(ldsw + (MODE == 3 ? 1024 : 4096) + s * 64);
;             f2 sa2 = (f2){0.f, 0.f}, sb2 = (f2){0.f, 0.f}, pa2 = (f2){0.f, 0.f}, pb2 = (f2){0.f, 0.f};
; #pragma unroll
;             for (int j = 0; j < 16; ++j) { const f32x4 aq = ua[j]; const f2 a0 = (f2){aq.x, aq.y}, a1 = (f2){aq.z, aq.w}; sa2 = S[2 * j] * a0 + sa2; sb2 = S[2 * j + 1] * a1 + sb2;
;                 if (MODE == 3) { pa2 = Pm[2 * j] * a0 + pa2; pb2 = Pm[2 * j + 1] * a1 + pb2; } }
;             const float sa = (sa2.x + sa2.y) + (sb2.x + sb2.y), pa = (pa2.x + pa2.y) + (pb2.x + pb2.y); const f2 pas = (f2){pa, pa};
;             const f2 sas = (f2){sa, sa}, vvs = (f2){vv, vv};
;             f2 y2 = (f2){0.f, 0.f}, y3 = (f2){0.f, 0.f};
;             f32x4 nwq[2], nbq[2], nrq[2];
;             nwq[0] = uw[0]; nwq[1] = uw[1]; nbq[0] = ub[0]; nbq[1] = ub[1]; nrq[0] = (f32x4){0.f, 0.f, 0.f, 0.f}; nrq[1] = nrq[0];
;             if (MODE == 2) { nrq[0] = ur[0]; nrq[1] = ur[1]; }
.LBB0_551:
	s_or_b64 exec, exec, s[4:5]
	s_waitcnt lgkmcnt(0)
	s_waitcnt lgkmcnt(0)
	v_subrev_u32_e32 v106, s94, v129
	v_and_b32_e32 v98, 60, v106
	v_add_u32_e32 v98, s94, v98
	v_and_b32_e32 v106, 0xc0, v106
	v_sub_u32_e32 v102, 0, v106
	v_ashrrev_i32_e32 v103, 31, v102
	v_lshl_add_u64 v[102:103], v[102:103], 0, v[134:135]
	s_and_b64 s[24:25], s[82:83], exec
	s_cselect_b32 s14, 0, 15
	s_mul_i32 s8, s14, 0x110
	v_add_u32_e32 v99, s8, v98
	ds_read_b32 v64, v99 offset:0
	ds_read_b32 v65, v99 offset:64
	ds_read_b32 v66, v99 offset:128
	ds_read_b32 v67, v99 offset:192
	ds_read_b32 v76, v98 offset:9216
	ds_read_b32 v77, v98 offset:9280
	ds_read_b32 v78, v98 offset:9344
	ds_read_b32 v79, v98 offset:9408
	ds_read_b32 v88, v129 offset:9472
	s_waitcnt lgkmcnt(0)
	ds_read_b32 v68, v99 offset:11520
	ds_read_b32 v72, v99 offset:15872
	ds_read_b32 v80, v99 offset:4352
	ds_read_b32 v69, v99 offset:11584
	ds_read_b32 v73, v99 offset:15936
	ds_read_b32 v81, v99 offset:4416
	ds_read_b32 v70, v99 offset:11648
	ds_read_b32 v74, v99 offset:16000
	ds_read_b32 v82, v99 offset:4480
	ds_read_b32 v71, v99 offset:11712
	ds_read_b32 v75, v99 offset:16064
	ds_read_b32 v83, v99 offset:4544
	s_mov_b32 s4, 0
	s_mov_b32 s5, 15
	s_setprio 1
.Lscan_c_step:
	s_and_b64 s[24:25], s[82:83], exec
	s_cselect_b32 s14, s4, s5
	s_add_i32 s8, s14, s27
	s_max_i32 s8, s8, 0
	s_min_i32 s8, s8, 15
	s_mul_i32 s9, s8, 0x110
	v_add_u32_e32 v100, s9, v98
	s_mul_i32 s24, s8, 0x600
	s_ashr_i32 s25, s24, 31
	v_lshl_add_u64 v[104:105], v[102:103], 0, s[24:25]
	global_load_dword v84, v[104:105], off offset:768
	global_load_dword v85, v[104:105], off offset:832
	global_load_dword v86, v[104:105], off offset:896
	global_load_dword v87, v[104:105], off offset:960
	s_nop 0
	v_lshl_add_u64 v[104:105], v[134:135], 0, s[24:25]
	global_load_dword v89, v[104:105], off offset:1280
	s_waitcnt lgkmcnt(12)
	v_mul_f32_dpp v90, v64, v12 row_newbcast:0 row_mask:0xf bank_mask:0xf
	v_mul_f32_dpp v91, v64, v13 row_newbcast:1 row_mask:0xf bank_mask:0xf
	v_mul_f32_dpp v92, v64, v14 row_newbcast:2 row_mask:0xf bank_mask:0xf
	v_mul_f32_dpp v93, v64, v15 row_newbcast:3 row_mask:0xf bank_mask:0xf
	v_fmac_f32_dpp v90, v64, v8 row_newbcast:4 row_mask:0xf bank_mask:0xf
	v_fmac_f32_dpp v91, v64, v9 row_newbcast:5 row_mask:0xf bank_mask:0xf
	v_fmac_f32_dpp v92, v64, v10 row_newbcast:6 row_mask:0xf bank_mask:0xf
	v_fmac_f32_dpp v93, v64, v11 row_newbcast:7 row_mask:0xf bank_mask:0xf
	v_fmac_f32_dpp v90, v64, v4 row_newbcast:8 row_mask:0xf bank_mask:0xf
	v_fmac_f32_dpp v91, v64, v5 row_newbcast:9 row_mask:0xf bank_mask:0xf
	v_fmac_f32_dpp v92, v64, v6 row_newbcast:10 row_mask:0xf bank_mask:0xf
	v_fmac_f32_dpp v93, v64, v7 row_newbcast:11 row_mask:0xf bank_mask:0xf
	v_fmac_f32_dpp v90, v64, v0 row_newbcast:12 row_mask:0xf bank_mask:0xf
	v_fmac_f32_dpp v91, v64, v1 row_newbcast:13 row_mask:0xf bank_mask:0xf
	v_fmac_f32_dpp v92, v64, v2 row_newbcast:14 row_mask:0xf bank_mask:0xf
	v_fmac_f32_dpp v93, v64, v3 row_newbcast:15 row_mask:0xf bank_mask:0xf
	v_fmac_f32_dpp v90, v65, v28 row_newbcast:0 row_mask:0xf bank_mask:0xf
	v_fmac_f32_dpp v91, v65, v29 row_newbcast:1 row_mask:0xf bank_mask:0xf
	v_fmac_f32_dpp v92, v65, v30 row_newbcast:2 row_mask:0xf bank_mask:0xf
	v_fmac_f32_dpp v93, v65, v31 row_newbcast:3 row_mask:0xf bank_mask:0xf
	v_fmac_f32_dpp v90, v65, v24 row_newbcast:4 row_mask:0xf bank_mask:0xf
	v_fmac_f32_dpp v91, v65, v25 row_newbcast:5 row_mask:0xf bank_mask:0xf
	v_fmac_f32_dpp v92, v65, v26 row_newbcast:6 row_mask:0xf bank_mask:0xf
	v_fmac_f32_dpp v93, v65, v27 row_newbcast:7 row_mask:0xf bank_mask:0xf
	v_fmac_f32_dpp v90, v65, v20 row_newbcast:8 row_mask:0xf bank_mask:0xf
	v_fmac_f32_dpp v91, v65, v21 row_newbcast:9 row_mask:0xf bank_mask:0xf
	v_fmac_f32_dpp v92, v65, v22 row_newbcast:10 row_mask:0xf bank_mask:0xf
	v_fmac_f32_dpp v93, v65, v23 row_newbcast:11 row_mask:0xf bank_mask:0xf
	v_fmac_f32_dpp v90, v65, v16 row_newbcast:12 row_mask:0xf bank_mask:0xf
	v_fmac_f32_dpp v91, v65, v17 row_newbcast:13 row_mask:0xf bank_mask:0xf
	v_fmac_f32_dpp v92, v65, v18 row_newbcast:14 row_mask:0xf bank_mask:0xf
	v_fmac_f32_dpp v93, v65, v19 row_newbcast:15 row_mask:0xf bank_mask:0xf
	v_fmac_f32_dpp v90, v66, v44 row_newbcast:0 row_mask:0xf bank_mask:0xf
	v_fmac_f32_dpp v91, v66, v45 row_newbcast:1 row_mask:0xf bank_mask:0xf
	v_fmac_f32_dpp v92, v66, v46 row_newbcast:2 row_mask:0xf bank_mask:0xf
	v_fmac_f32_dpp v93, v66, v47 row_newbcast:3 row_mask:0xf bank_mask:0xf
	v_fmac_f32_dpp v90, v66, v40 row_newbcast:4 row_mask:0xf bank_mask:0xf
	v_fmac_f32_dpp v91, v66, v41 row_newbcast:5 row_mask:0xf bank_mask:0xf
	v_fmac_f32_dpp v92, v66, v42 row_newbcast:6 row_mask:0xf bank_mask:0xf
	v_fmac_f32_dpp v93, v66, v43 row_newbcast:7 row_mask:0xf bank_mask:0xf
	v_fmac_f32_dpp v90, v66, v36 row_newbcast:8 row_mask:0xf bank_mask:0xf
	v_fmac_f32_dpp v91, v66, v37 row_newbcast:9 row_mask:0xf bank_mask:0xf
	v_fmac_f32_dpp v92, v66, v38 row_newbcast:10 row_mask:0xf bank_mask:0xf
	v_fmac_f32_dpp v93, v66, v39 row_newbcast:11 row_mask:0xf bank_mask:0xf
	v_fmac_f32_dpp v90, v66, v32 row_newbcast:12 row_mask:0xf bank_mask:0xf
	v_fmac_f32_dpp v91, v66, v33 row_newbcast:13 row_mask:0xf bank_mask:0xf
	v_fmac_f32_dpp v92, v66, v34 row_newbcast:14 row_mask:0xf bank_mask:0xf
	v_fmac_f32_dpp v93, v66, v35 row_newbcast:15 row_mask:0xf bank_mask:0xf
	v_fmac_f32_dpp v90, v67, v60 row_newbcast:0 row_mask:0xf bank_mask:0xf
	v_fmac_f32_dpp v91, v67, v61 row_newbcast:1 row_mask:0xf bank_mask:0xf
	v_fmac_f32_dpp v92, v67, v62 row_newbcast:2 row_mask:0xf bank_mask:0xf
	v_fmac_f32_dpp v93, v67, v63 row_newbcast:3 row_mask:0xf bank_mask:0xf
	v_fmac_f32_dpp v90, v67, v56 row_newbcast:4 row_mask:0xf bank_mask:0xf
	v_fmac_f32_dpp v91, v67, v57 row_newbcast:5 row_mask:0xf bank_mask:0xf
	v_fmac_f32_dpp v92, v67, v58 row_newbcast:6 row_mask:0xf bank_mask:0xf
	v_fmac_f32_dpp v93, v67, v59 row_newbcast:7 row_mask:0xf bank_mask:0xf
	v_fmac_f32_dpp v90, v67, v52 row_newbcast:8 row_mask:0xf bank_mask:0xf
	v_fmac_f32_dpp v91, v67, v53 row_newbcast:9 row_mask:0xf bank_mask:0xf
	v_fmac_f32_dpp v92, v67, v54 row_newbcast:10 row_mask:0xf bank_mask:0xf
	v_fmac_f32_dpp v93, v67, v55 row_newbcast:11 row_mask:0xf bank_mask:0xf
	v_fmac_f32_dpp v90, v67, v48 row_newbcast:12 row_mask:0xf bank_mask:0xf
	v_fmac_f32_dpp v91, v67, v49 row_newbcast:13 row_mask:0xf bank_mask:0xf
	v_fmac_f32_dpp v92, v67, v50 row_newbcast:14 row_mask:0xf bank_mask:0xf
	v_fmac_f32_dpp v93, v67, v51 row_newbcast:15 row_mask:0xf bank_mask:0xf
	v_add_f32_e32 v90, v90, v91
	v_add_f32_e32 v92, v92, v93
	s_waitcnt lgkmcnt(0)
; #define RL2(x, j) (f2){__builtin_bit_cast(float, __builtin_amdgcn_readlane(__builtin_bit_cast(int, x), 2 * (j))), __builtin_bit_cast(float, __builtin_amdgcn_readlane(__builtin_bit_cast(int, x), 2 * (j) + 1))}
; template <int MODE>
; __device__ __forceinline__ void scan_item(const CAS Args* A, int l, int item, float* slab0, LAS float* ldsw, int lane) {
;     ...
; #pragma unroll
;             for (int g = 0; g < 8; ++g) {
;                 const f32x4 cwq0 = nwq[0], cwq1 = nwq[1], cbq0 = nbq[0], cbq1 = nbq[1], crq0 = nrq[0], crq1 = nrq[1];
;                 if (g < 7) { nwq[0] = uw[2 * g + 2]; nwq[1] = uw[2 * g + 3]; nbq[0] = ub[2 * g + 2]; nbq[1] = ub[2 * g + 3];
;                     if (MODE == 2) { nrq[0] = ur[2 * g + 2]; nrq[1] = ur[2 * g + 3]; } }
;                 f2 bb[4], ww[4], kq[4], rr[4];
;                 ww[0] = (f2){cwq0.x, cwq0.y}; ww[1] = (f2){cwq0.z, cwq0.w}; ww[2] = (f2){cwq1.x, cwq1.y}; ww[3] = (f2){cwq1.z, cwq1.w};
;                 bb[0] = (f2){cbq0.x, cbq0.y}; bb[1] = (f2){cbq0.z, cbq0.w}; bb[2] = (f2){cbq1.x, cbq1.y}; bb[3] = (f2){cbq1.z, cbq1.w};
;                 rr[0] = (f2){crq0.x, crq0.y}; rr[1] = (f2){crq0.z, crq0.w}; rr[2] = (f2){crq1.x, crq1.y}; rr[3] = (f2){crq1.z, crq1.w};
; #pragma unroll
;                 for (int q = 0; q < 4; ++q) { const int j = g * 4 + q; if (MODE != 1) kq[q] = RL2(ck, j); }
;                 __builtin_amdgcn_sched_barrier(0);
; #pragma unroll
;                 for (int q = 0; q < 4; ++q) { const int j = g * 4 + q;
;                     f2 t = sas * bb[q];
;                     if (MODE != 1) t = vvs * kq[q] + t;
;                     S[j] = S[j] * ww[q] + t;
;                     if (MODE == 3) Pm[j] = Pm[j] * ww[q] + pas * bb[q];
;                     if (MODE == 2) { if (j & 1) y3 = S[j] * rr[q] + y3; else y2 = S[j] * rr[q] + y2; } }
;             }
	ds_read_b32 v64, v100 offset:0
	ds_read_b32 v65, v100 offset:64
	ds_read_b32 v66, v100 offset:128
	ds_read_b32 v67, v100 offset:192
	v_add_f32_e32 v90, v90, v92
	v_mul_f32_dpp v12, v68, v12 row_newbcast:0 row_mask:0xf bank_mask:0xf
	v_mul_f32_dpp v13, v68, v13 row_newbcast:1 row_mask:0xf bank_mask:0xf
	v_mul_f32_dpp v14, v68, v14 row_newbcast:2 row_mask:0xf bank_mask:0xf
	v_mul_f32_dpp v15, v68, v15 row_newbcast:3 row_mask:0xf bank_mask:0xf
	v_fmac_f32_dpp v12, v72, v90 row_newbcast:0 row_mask:0xf bank_mask:0xf
	v_fmac_f32_dpp v13, v72, v90 row_newbcast:1 row_mask:0xf bank_mask:0xf
	v_fmac_f32_dpp v14, v72, v90 row_newbcast:2 row_mask:0xf bank_mask:0xf
	v_fmac_f32_dpp v15, v72, v90 row_newbcast:3 row_mask:0xf bank_mask:0xf
	v_fmac_f32_dpp v12, v76, v88 row_newbcast:0 row_mask:0xf bank_mask:0xf
	v_fmac_f32_dpp v13, v76, v88 row_newbcast:1 row_mask:0xf bank_mask:0xf
	v_fmac_f32_dpp v14, v76, v88 row_newbcast:2 row_mask:0xf bank_mask:0xf
	v_fmac_f32_dpp v15, v76, v88 row_newbcast:3 row_mask:0xf bank_mask:0xf
	v_mul_f32_dpp v94, v80, v12 row_newbcast:0 row_mask:0xf bank_mask:0xf
	v_mul_f32_dpp v95, v80, v13 row_newbcast:1 row_mask:0xf bank_mask:0xf
	v_mul_f32_dpp v96, v80, v14 row_newbcast:2 row_mask:0xf bank_mask:0xf
	v_mul_f32_dpp v97, v80, v15 row_newbcast:3 row_mask:0xf bank_mask:0xf
	v_mul_f32_dpp v8, v68, v8 row_newbcast:4 row_mask:0xf bank_mask:0xf
	v_mul_f32_dpp v9, v68, v9 row_newbcast:5 row_mask:0xf bank_mask:0xf
	v_mul_f32_dpp v10, v68, v10 row_newbcast:6 row_mask:0xf bank_mask:0xf
	v_mul_f32_dpp v11, v68, v11 row_newbcast:7 row_mask:0xf bank_mask:0xf
	v_fmac_f32_dpp v8, v72, v90 row_newbcast:4 row_mask:0xf bank_mask:0xf
	v_fmac_f32_dpp v9, v72, v90 row_newbcast:5 row_mask:0xf bank_mask:0xf
	v_fmac_f32_dpp v10, v72, v90 row_newbcast:6 row_mask:0xf bank_mask:0xf
	v_fmac_f32_dpp v11, v72, v90 row_newbcast:7 row_mask:0xf bank_mask:0xf
	v_fmac_f32_dpp v8, v76, v88 row_newbcast:4 row_mask:0xf bank_mask:0xf
	v_fmac_f32_dpp v9, v76, v88 row_newbcast:5 row_mask:0xf bank_mask:0xf
	v_fmac_f32_dpp v10, v76, v88 row_newbcast:6 row_mask:0xf bank_mask:0xf
	v_fmac_f32_dpp v11, v76, v88 row_newbcast:7 row_mask:0xf bank_mask:0xf
	v_fmac_f32_dpp v94, v80, v8 row_newbcast:4 row_mask:0xf bank_mask:0xf
	v_fmac_f32_dpp v95, v80, v9 row_newbcast:5 row_mask:0xf bank_mask:0xf
	v_fmac_f32_dpp v96, v80, v10 row_newbcast:6 row_mask:0xf bank_mask:0xf
	v_fmac_f32_dpp v97, v80, v11 row_newbcast:7 row_mask:0xf bank_mask:0xf
	v_mul_f32_dpp v4, v68, v4 row_newbcast:8 row_mask:0xf bank_mask:0xf
	v_mul_f32_dpp v5, v68, v5 row_newbcast:9 row_mask:0xf bank_mask:0xf
	v_mul_f32_dpp v6, v68, v6 row_newbcast:10 row_mask:0xf bank_mask:0xf
	v_mul_f32_dpp v7, v68, v7 row_newbcast:11 row_mask:0xf bank_mask:0xf
	v_fmac_f32_dpp v4, v72, v90 row_newbcast:8 row_mask:0xf bank_mask:0xf
	v_fmac_f32_dpp v5, v72, v90 row_newbcast:9 row_mask:0xf bank_mask:0xf
	v_fmac_f32_dpp v6, v72, v90 row_newbcast:10 row_mask:0xf bank_mask:0xf
	v_fmac_f32_dpp v7, v72, v90 row_newbcast:11 row_mask:0xf bank_mask:0xf
	v_fmac_f32_dpp v4, v76, v88 row_newbcast:8 row_mask:0xf bank_mask:0xf
	v_fmac_f32_dpp v5, v76, v88 row_newbcast:9 row_mask:0xf bank_mask:0xf
	v_fmac_f32_dpp v6, v76, v88 row_newbcast:10 row_mask:0xf bank_mask:0xf
	v_fmac_f32_dpp v7, v76, v88 row_newbcast:11 row_mask:0xf bank_mask:0xf
	v_fmac_f32_dpp v94, v80, v4 row_newbcast:8 row_mask:0xf bank_mask:0xf
	v_fmac_f32_dpp v95, v80, v5 row_newbcast:9 row_mask:0xf bank_mask:0xf
	v_fmac_f32_dpp v96, v80, v6 row_newbcast:10 row_mask:0xf bank_mask:0xf
	v_fmac_f32_dpp v97, v80, v7 row_newbcast:11 row_mask:0xf bank_mask:0xf
	v_mul_f32_dpp v0, v68, v0 row_newbcast:12 row_mask:0xf bank_mask:0xf
	v_mul_f32_dpp v1, v68, v1 row_newbcast:13 row_mask:0xf bank_mask:0xf
	v_mul_f32_dpp v2, v68, v2 row_newbcast:14 row_mask:0xf bank_mask:0xf
	v_mul_f32_dpp v3, v68, v3 row_newbcast:15 row_mask:0xf bank_mask:0xf
	v_fmac_f32_dpp v0, v72, v90 row_newbcast:12 row_mask:0xf bank_mask:0xf
	v_fmac_f32_dpp v1, v72, v90 row_newbcast:13 row_mask:0xf bank_mask:0xf
	v_fmac_f32_dpp v2, v72, v90 row_newbcast:14 row_mask:0xf bank_mask:0xf
	v_fmac_f32_dpp v3, v72, v90 row_newbcast:15 row_mask:0xf bank_mask:0xf
	v_fmac_f32_dpp v0, v76, v88 row_newbcast:12 row_mask:0xf bank_mask:0xf
	v_fmac_f32_dpp v1, v76, v88 row_newbcast:13 row_mask:0xf bank_mask:0xf
	v_fmac_f32_dpp v2, v76, v88 row_newbcast:14 row_mask:0xf bank_mask:0xf
	v_fmac_f32_dpp v3, v76, v88 row_newbcast:15 row_mask:0xf bank_mask:0xf
	v_fmac_f32_dpp v94, v80, v0 row_newbcast:12 row_mask:0xf bank_mask:0xf
	v_fmac_f32_dpp v95, v80, v1 row_newbcast:13 row_mask:0xf bank_mask:0xf
	v_fmac_f32_dpp v96, v80, v2 row_newbcast:14 row_mask:0xf bank_mask:0xf
	v_fmac_f32_dpp v97, v80, v3 row_newbcast:15 row_mask:0xf bank_mask:0xf
	ds_read_b32 v68, v100 offset:11520
	ds_read_b32 v72, v100 offset:15872
	ds_read_b32 v80, v100 offset:4352
	v_mul_f32_dpp v28, v69, v28 row_newbcast:0 row_mask:0xf bank_mask:0xf
	v_mul_f32_dpp v29, v69, v29 row_newbcast:1 row_mask:0xf bank_mask:0xf
	v_mul_f32_dpp v30, v69, v30 row_newbcast:2 row_mask:0xf bank_mask:0xf
	v_mul_f32_dpp v31, v69, v31 row_newbcast:3 row_mask:0xf bank_mask:0xf
	v_fmac_f32_dpp v28, v73, v90 row_newbcast:0 row_mask:0xf bank_mask:0xf
	v_fmac_f32_dpp v29, v73, v90 row_newbcast:1 row_mask:0xf bank_mask:0xf
	v_fmac_f32_dpp v30, v73, v90 row_newbcast:2 row_mask:0xf bank_mask:0xf
	v_fmac_f32_dpp v31, v73, v90 row_newbcast:3 row_mask:0xf bank_mask:0xf
	v_fmac_f32_dpp v28, v77, v88 row_newbcast:0 row_mask:0xf bank_mask:0xf
	v_fmac_f32_dpp v29, v77, v88 row_newbcast:1 row_mask:0xf bank_mask:0xf
	v_fmac_f32_dpp v30, v77, v88 row_newbcast:2 row_mask:0xf bank_mask:0xf
; #define RL2(x, j) (f2){__builtin_bit_cast(float, __builtin_amdgcn_readlane(__builtin_bit_cast(int, x), 2 * (j))), __builtin_bit_cast(float, __builtin_amdgcn_readlane(__builtin_bit_cast(int, x), 2 * (j) + 1))}
; template <int MODE>
; __device__ __forceinline__ void scan_item(const CAS Args* A, int l, int item, float* slab0, LAS float* ldsw, int lane) {
;     ...
; #pragma unroll
;             for (int g = 0; g < 8; ++g) {
;                 const f32x4 cwq0 = nwq[0], cwq1 = nwq[1], cbq0 = nbq[0], cbq1 = nbq[1], crq0 = nrq[0], crq1 = nrq[1];
;                 if (g < 7) { nwq[0] = uw[2 * g + 2]; nwq[1] = uw[2 * g + 3]; nbq[0] = ub[2 * g + 2]; nbq[1] = ub[2 * g + 3];
;                     if (MODE == 2) { nrq[0] = ur[2 * g + 2]; nrq[1] = ur[2 * g + 3]; } }
;                 f2 bb[4], ww[4], kq[4], rr[4];
;                 ww[0] = (f2){cwq0.x, cwq0.y}; ww[1] = (f2){cwq0.z, cwq0.w}; ww[2] = (f2){cwq1.x, cwq1.y}; ww[3] = (f2){cwq1.z, cwq1.w};
;                 bb[0] = (f2){cbq0.x, cbq0.y}; bb[1] = (f2){cbq0.z, cbq0.w}; bb[2] = (f2){cbq1.x, cbq1.y}; bb[3] = (f2){cbq1.z, cbq1.w};
;                 rr[0] = (f2){crq0.x, crq0.y}; rr[1] = (f2){crq0.z, crq0.w}; rr[2] = (f2){crq1.x, crq1.y}; rr[3] = (f2){crq1.z, crq1.w};
; #pragma unroll
;                 for (int q = 0; q < 4; ++q) { const int j = g * 4 + q; if (MODE != 1) kq[q] = RL2(ck, j); }
;                 __builtin_amdgcn_sched_barrier(0);
; #pragma unroll
;                 for (int q = 0; q < 4; ++q) { const int j = g * 4 + q;
;                     f2 t = sas * bb[q];
;                     if (MODE != 1) t = vvs * kq[q] + t;
;                     S[j] = S[j] * ww[q] + t;
;                     if (MODE == 3) Pm[j] = Pm[j] * ww[q] + pas * bb[q];
;                     if (MODE == 2) { if (j & 1) y3 = S[j] * rr[q] + y3; else y2 = S[j] * rr[q] + y2; } }
;             }
	v_fmac_f32_dpp v31, v77, v88 row_newbcast:3 row_mask:0xf bank_mask:0xf
	v_fmac_f32_dpp v94, v81, v28 row_newbcast:0 row_mask:0xf bank_mask:0xf
	v_fmac_f32_dpp v95, v81, v29 row_newbcast:1 row_mask:0xf bank_mask:0xf
	v_fmac_f32_dpp v96, v81, v30 row_newbcast:2 row_mask:0xf bank_mask:0xf
	v_fmac_f32_dpp v97, v81, v31 row_newbcast:3 row_mask:0xf bank_mask:0xf
	v_mul_f32_dpp v24, v69, v24 row_newbcast:4 row_mask:0xf bank_mask:0xf
	v_mul_f32_dpp v25, v69, v25 row_newbcast:5 row_mask:0xf bank_mask:0xf
	v_mul_f32_dpp v26, v69, v26 row_newbcast:6 row_mask:0xf bank_mask:0xf
	v_mul_f32_dpp v27, v69, v27 row_newbcast:7 row_mask:0xf bank_mask:0xf
	v_fmac_f32_dpp v24, v73, v90 row_newbcast:4 row_mask:0xf bank_mask:0xf
	v_fmac_f32_dpp v25, v73, v90 row_newbcast:5 row_mask:0xf bank_mask:0xf
	v_fmac_f32_dpp v26, v73, v90 row_newbcast:6 row_mask:0xf bank_mask:0xf
	v_fmac_f32_dpp v27, v73, v90 row_newbcast:7 row_mask:0xf bank_mask:0xf
	v_fmac_f32_dpp v24, v77, v88 row_newbcast:4 row_mask:0xf bank_mask:0xf
	v_fmac_f32_dpp v25, v77, v88 row_newbcast:5 row_mask:0xf bank_mask:0xf
	v_fmac_f32_dpp v26, v77, v88 row_newbcast:6 row_mask:0xf bank_mask:0xf
	v_fmac_f32_dpp v27, v77, v88 row_newbcast:7 row_mask:0xf bank_mask:0xf
	v_fmac_f32_dpp v94, v81, v24 row_newbcast:4 row_mask:0xf bank_mask:0xf
	v_fmac_f32_dpp v95, v81, v25 row_newbcast:5 row_mask:0xf bank_mask:0xf
	v_fmac_f32_dpp v96, v81, v26 row_newbcast:6 row_mask:0xf bank_mask:0xf
	v_fmac_f32_dpp v97, v81, v27 row_newbcast:7 row_mask:0xf bank_mask:0xf
	v_mul_f32_dpp v20, v69, v20 row_newbcast:8 row_mask:0xf bank_mask:0xf
	v_mul_f32_dpp v21, v69, v21 row_newbcast:9 row_mask:0xf bank_mask:0xf
	v_mul_f32_dpp v22, v69, v22 row_newbcast:10 row_mask:0xf bank_mask:0xf
	v_mul_f32_dpp v23, v69, v23 row_newbcast:11 row_mask:0xf bank_mask:0xf
	v_fmac_f32_dpp v20, v73, v90 row_newbcast:8 row_mask:0xf bank_mask:0xf
	v_fmac_f32_dpp v21, v73, v90 row_newbcast:9 row_mask:0xf bank_mask:0xf
	v_fmac_f32_dpp v22, v73, v90 row_newbcast:10 row_mask:0xf bank_mask:0xf
	v_fmac_f32_dpp v23, v73, v90 row_newbcast:11 row_mask:0xf bank_mask:0xf
	v_fmac_f32_dpp v20, v77, v88 row_newbcast:8 row_mask:0xf bank_mask:0xf
	v_fmac_f32_dpp v21, v77, v88 row_newbcast:9 row_mask:0xf bank_mask:0xf
	v_fmac_f32_dpp v22, v77, v88 row_newbcast:10 row_mask:0xf bank_mask:0xf
	v_fmac_f32_dpp v23, v77, v88 row_newbcast:11 row_mask:0xf bank_mask:0xf
	v_fmac_f32_dpp v94, v81, v20 row_newbcast:8 row_mask:0xf bank_mask:0xf
	v_fmac_f32_dpp v95, v81, v21 row_newbcast:9 row_mask:0xf bank_mask:0xf
	v_fmac_f32_dpp v96, v81, v22 row_newbcast:10 row_mask:0xf bank_mask:0xf
	v_fmac_f32_dpp v97, v81, v23 row_newbcast:11 row_mask:0xf bank_mask:0xf
	v_mul_f32_dpp v16, v69, v16 row_newbcast:12 row_mask:0xf bank_mask:0xf
	v_mul_f32_dpp v17, v69, v17 row_newbcast:13 row_mask:0xf bank_mask:0xf
	v_mul_f32_dpp v18, v69, v18 row_newbcast:14 row_mask:0xf bank_mask:0xf
	v_mul_f32_dpp v19, v69, v19 row_newbcast:15 row_mask:0xf bank_mask:0xf
	v_fmac_f32_dpp v16, v73, v90 row_newbcast:12 row_mask:0xf bank_mask:0xf
	v_fmac_f32_dpp v17, v73, v90 row_newbcast:13 row_mask:0xf bank_mask:0xf
	v_fmac_f32_dpp v18, v73, v90 row_newbcast:14 row_mask:0xf bank_mask:0xf
	v_fmac_f32_dpp v19, v73, v90 row_newbcast:15 row_mask:0xf bank_mask:0xf
	v_fmac_f32_dpp v16, v77, v88 row_newbcast:12 row_mask:0xf bank_mask:0xf
	v_fmac_f32_dpp v17, v77, v88 row_newbcast:13 row_mask:0xf bank_mask:0xf
	v_fmac_f32_dpp v18, v77, v88 row_newbcast:14 row_mask:0xf bank_mask:0xf
	v_fmac_f32_dpp v19, v77, v88 row_newbcast:15 row_mask:0xf bank_mask:0xf
	v_fmac_f32_dpp v94, v81, v16 row_newbcast:12 row_mask:0xf bank_mask:0xf
	v_fmac_f32_dpp v95, v81, v17 row_newbcast:13 row_mask:0xf bank_mask:0xf
	v_fmac_f32_dpp v96, v81, v18 row_newbcast:14 row_mask:0xf bank_mask:0xf
	v_fmac_f32_dpp v97, v81, v19 row_newbcast:15 row_mask:0xf bank_mask:0xf
	ds_read_b32 v69, v100 offset:11584
	ds_read_b32 v73, v100 offset:15936
	ds_read_b32 v81, v100 offset:4416
	v_mul_f32_dpp v44, v70, v44 row_newbcast:0 row_mask:0xf bank_mask:0xf
	v_mul_f32_dpp v45, v70, v45 row_newbcast:1 row_mask:0xf bank_mask:0xf
	v_mul_f32_dpp v46, v70, v46 row_newbcast:2 row_mask:0xf bank_mask:0xf
	v_mul_f32_dpp v47, v70, v47 row_newbcast:3 row_mask:0xf bank_mask:0xf
	v_fmac_f32_dpp v44, v74, v90 row_newbcast:0 row_mask:0xf bank_mask:0xf
	v_fmac_f32_dpp v45, v74, v90 row_newbcast:1 row_mask:0xf bank_mask:0xf
	v_fmac_f32_dpp v46, v74, v90 row_newbcast:2 row_mask:0xf bank_mask:0xf
	v_fmac_f32_dpp v47, v74, v90 row_newbcast:3 row_mask:0xf bank_mask:0xf
	v_fmac_f32_dpp v44, v78, v88 row_newbcast:0 row_mask:0xf bank_mask:0xf
	v_fmac_f32_dpp v45, v78, v88 row_newbcast:1 row_mask:0xf bank_mask:0xf
	v_fmac_f32_dpp v46, v78, v88 row_newbcast:2 row_mask:0xf bank_mask:0xf
	v_fmac_f32_dpp v47, v78, v88 row_newbcast:3 row_mask:0xf bank_mask:0xf
	v_fmac_f32_dpp v94, v82, v44 row_newbcast:0 row_mask:0xf bank_mask:0xf
	v_fmac_f32_dpp v95, v82, v45 row_newbcast:1 row_mask:0xf bank_mask:0xf
	v_fmac_f32_dpp v96, v82, v46 row_newbcast:2 row_mask:0xf bank_mask:0xf
	v_fmac_f32_dpp v97, v82, v47 row_newbcast:3 row_mask:0xf bank_mask:0xf
	v_mul_f32_dpp v40, v70, v40 row_newbcast:4 row_mask:0xf bank_mask:0xf
	v_mul_f32_dpp v41, v70, v41 row_newbcast:5 row_mask:0xf bank_mask:0xf
	v_mul_f32_dpp v42, v70, v42 row_newbcast:6 row_mask:0xf bank_mask:0xf
	v_mul_f32_dpp v43, v70, v43 row_newbcast:7 row_mask:0xf bank_mask:0xf
	v_fmac_f32_dpp v40, v74, v90 row_newbcast:4 row_mask:0xf bank_mask:0xf
	v_fmac_f32_dpp v41, v74, v90 row_newbcast:5 row_mask:0xf bank_mask:0xf
	v_fmac_f32_dpp v42, v74, v90 row_newbcast:6 row_mask:0xf bank_mask:0xf
	v_fmac_f32_dpp v43, v74, v90 row_newbcast:7 row_mask:0xf bank_mask:0xf
; #define RL2(x, j) (f2){__builtin_bit_cast(float, __builtin_amdgcn_readlane(__builtin_bit_cast(int, x), 2 * (j))), __builtin_bit_cast(float, __builtin_amdgcn_readlane(__builtin_bit_cast(int, x), 2 * (j) + 1))}
; template <int MODE>
; __device__ __forceinline__ void scan_item(const CAS Args* A, int l, int item, float* slab0, LAS float* ldsw, int lane) {
;     ...
; #pragma unroll
;             for (int g = 0; g < 8; ++g) {
;                 const f32x4 cwq0 = nwq[0], cwq1 = nwq[1], cbq0 = nbq[0], cbq1 = nbq[1], crq0 = nrq[0], crq1 = nrq[1];
;                 if (g < 7) { nwq[0] = uw[2 * g + 2]; nwq[1] = uw[2 * g + 3]; nbq[0] = ub[2 * g + 2]; nbq[1] = ub[2 * g + 3];
;                     if (MODE == 2) { nrq[0] = ur[2 * g + 2]; nrq[1] = ur[2 * g + 3]; } }
;                 f2 bb[4], ww[4], kq[4], rr[4];
;                 ww[0] = (f2){cwq0.x, cwq0.y}; ww[1] = (f2){cwq0.z, cwq0.w}; ww[2] = (f2){cwq1.x, cwq1.y}; ww[3] = (f2){cwq1.z, cwq1.w};
;                 bb[0] = (f2){cbq0.x, cbq0.y}; bb[1] = (f2){cbq0.z, cbq0.w}; bb[2] = (f2){cbq1.x, cbq1.y}; bb[3] = (f2){cbq1.z, cbq1.w};
;                 rr[0] = (f2){crq0.x, crq0.y}; rr[1] = (f2){crq0.z, crq0.w}; rr[2] = (f2){crq1.x, crq1.y}; rr[3] = (f2){crq1.z, crq1.w};
; #pragma unroll
;                 for (int q = 0; q < 4; ++q) { const int j = g * 4 + q; if (MODE != 1) kq[q] = RL2(ck, j); }
;                 __builtin_amdgcn_sched_barrier(0);
; #pragma unroll
;                 for (int q = 0; q < 4; ++q) { const int j = g * 4 + q;
;                     f2 t = sas * bb[q];
;                     if (MODE != 1) t = vvs * kq[q] + t;
;                     S[j] = S[j] * ww[q] + t;
;                     if (MODE == 3) Pm[j] = Pm[j] * ww[q] + pas * bb[q];
;                     if (MODE == 2) { if (j & 1) y3 = S[j] * rr[q] + y3; else y2 = S[j] * rr[q] + y2; } }
;             }
	v_fmac_f32_dpp v40, v78, v88 row_newbcast:4 row_mask:0xf bank_mask:0xf
	v_fmac_f32_dpp v41, v78, v88 row_newbcast:5 row_mask:0xf bank_mask:0xf
	v_fmac_f32_dpp v42, v78, v88 row_newbcast:6 row_mask:0xf bank_mask:0xf
	v_fmac_f32_dpp v43, v78, v88 row_newbcast:7 row_mask:0xf bank_mask:0xf
	v_fmac_f32_dpp v94, v82, v40 row_newbcast:4 row_mask:0xf bank_mask:0xf
	v_fmac_f32_dpp v95, v82, v41 row_newbcast:5 row_mask:0xf bank_mask:0xf
	v_fmac_f32_dpp v96, v82, v42 row_newbcast:6 row_mask:0xf bank_mask:0xf
	v_fmac_f32_dpp v97, v82, v43 row_newbcast:7 row_mask:0xf bank_mask:0xf
	v_mul_f32_dpp v36, v70, v36 row_newbcast:8 row_mask:0xf bank_mask:0xf
	v_mul_f32_dpp v37, v70, v37 row_newbcast:9 row_mask:0xf bank_mask:0xf
	v_mul_f32_dpp v38, v70, v38 row_newbcast:10 row_mask:0xf bank_mask:0xf
	v_mul_f32_dpp v39, v70, v39 row_newbcast:11 row_mask:0xf bank_mask:0xf
	v_fmac_f32_dpp v36, v74, v90 row_newbcast:8 row_mask:0xf bank_mask:0xf
	v_fmac_f32_dpp v37, v74, v90 row_newbcast:9 row_mask:0xf bank_mask:0xf
	v_fmac_f32_dpp v38, v74, v90 row_newbcast:10 row_mask:0xf bank_mask:0xf
	v_fmac_f32_dpp v39, v74, v90 row_newbcast:11 row_mask:0xf bank_mask:0xf
	v_fmac_f32_dpp v36, v78, v88 row_newbcast:8 row_mask:0xf bank_mask:0xf
	v_fmac_f32_dpp v37, v78, v88 row_newbcast:9 row_mask:0xf bank_mask:0xf
	v_fmac_f32_dpp v38, v78, v88 row_newbcast:10 row_mask:0xf bank_mask:0xf
	v_fmac_f32_dpp v39, v78, v88 row_newbcast:11 row_mask:0xf bank_mask:0xf
	v_fmac_f32_dpp v94, v82, v36 row_newbcast:8 row_mask:0xf bank_mask:0xf
	v_fmac_f32_dpp v95, v82, v37 row_newbcast:9 row_mask:0xf bank_mask:0xf
	v_fmac_f32_dpp v96, v82, v38 row_newbcast:10 row_mask:0xf bank_mask:0xf
	v_fmac_f32_dpp v97, v82, v39 row_newbcast:11 row_mask:0xf bank_mask:0xf
	v_mul_f32_dpp v32, v70, v32 row_newbcast:12 row_mask:0xf bank_mask:0xf
	v_mul_f32_dpp v33, v70, v33 row_newbcast:13 row_mask:0xf bank_mask:0xf
	v_mul_f32_dpp v34, v70, v34 row_newbcast:14 row_mask:0xf bank_mask:0xf
	v_mul_f32_dpp v35, v70, v35 row_newbcast:15 row_mask:0xf bank_mask:0xf
	v_fmac_f32_dpp v32, v74, v90 row_newbcast:12 row_mask:0xf bank_mask:0xf
	v_fmac_f32_dpp v33, v74, v90 row_newbcast:13 row_mask:0xf bank_mask:0xf
	v_fmac_f32_dpp v34, v74, v90 row_newbcast:14 row_mask:0xf bank_mask:0xf
	v_fmac_f32_dpp v35, v74, v90 row_newbcast:15 row_mask:0xf bank_mask:0xf
	v_fmac_f32_dpp v32, v78, v88 row_newbcast:12 row_mask:0xf bank_mask:0xf
	v_fmac_f32_dpp v33, v78, v88 row_newbcast:13 row_mask:0xf bank_mask:0xf
	v_fmac_f32_dpp v34, v78, v88 row_newbcast:14 row_mask:0xf bank_mask:0xf
	v_fmac_f32_dpp v35, v78, v88 row_newbcast:15 row_mask:0xf bank_mask:0xf
	v_fmac_f32_dpp v94, v82, v32 row_newbcast:12 row_mask:0xf bank_mask:0xf
	v_fmac_f32_dpp v95, v82, v33 row_newbcast:13 row_mask:0xf bank_mask:0xf
	v_fmac_f32_dpp v96, v82, v34 row_newbcast:14 row_mask:0xf bank_mask:0xf
	v_fmac_f32_dpp v97, v82, v35 row_newbcast:15 row_mask:0xf bank_mask:0xf
	ds_read_b32 v70, v100 offset:11648
	ds_read_b32 v74, v100 offset:16000
	ds_read_b32 v82, v100 offset:4480
	v_mul_f32_dpp v60, v71, v60 row_newbcast:0 row_mask:0xf bank_mask:0xf
	v_mul_f32_dpp v61, v71, v61 row_newbcast:1 row_mask:0xf bank_mask:0xf
	v_mul_f32_dpp v62, v71, v62 row_newbcast:2 row_mask:0xf bank_mask:0xf
	v_mul_f32_dpp v63, v71, v63 row_newbcast:3 row_mask:0xf bank_mask:0xf
	v_fmac_f32_dpp v60, v75, v90 row_newbcast:0 row_mask:0xf bank_mask:0xf
	v_fmac_f32_dpp v61, v75, v90 row_newbcast:1 row_mask:0xf bank_mask:0xf
	v_fmac_f32_dpp v62, v75, v90 row_newbcast:2 row_mask:0xf bank_mask:0xf
	v_fmac_f32_dpp v63, v75, v90 row_newbcast:3 row_mask:0xf bank_mask:0xf
	v_fmac_f32_dpp v60, v79, v88 row_newbcast:0 row_mask:0xf bank_mask:0xf
	v_fmac_f32_dpp v61, v79, v88 row_newbcast:1 row_mask:0xf bank_mask:0xf
	v_fmac_f32_dpp v62, v79, v88 row_newbcast:2 row_mask:0xf bank_mask:0xf
	v_fmac_f32_dpp v63, v79, v88 row_newbcast:3 row_mask:0xf bank_mask:0xf
	v_fmac_f32_dpp v94, v83, v60 row_newbcast:0 row_mask:0xf bank_mask:0xf
	v_fmac_f32_dpp v95, v83, v61 row_newbcast:1 row_mask:0xf bank_mask:0xf
	v_fmac_f32_dpp v96, v83, v62 row_newbcast:2 row_mask:0xf bank_mask:0xf
	v_fmac_f32_dpp v97, v83, v63 row_newbcast:3 row_mask:0xf bank_mask:0xf
; __device__ __forceinline__ unsigned f2bf(float f) { return pk2(f, f) & 0xffffu; }
; #define RL2(x, j) (f2){__builtin_bit_cast(float, __builtin_amdgcn_readlane(__builtin_bit_cast(int, x), 2 * (j))), __builtin_bit_cast(float, __builtin_amdgcn_readlane(__builtin_bit_cast(int, x), 2 * (j) + 1))}
; #define lane LANE_()
; template <int MODE>
; __device__ __forceinline__ void scan_item(const CAS Args* A, int l, int item, float* slab0, LAS float* ldsw, int lane) {
;     ...
;             for (int g = 0; g < 8; ++g) {
;                 const f32x4 cwq0 = nwq[0], cwq1 = nwq[1], cbq0 = nbq[0], cbq1 = nbq[1], crq0 = nrq[0], crq1 = nrq[1];
;                 if (g < 7) { nwq[0] = uw[2 * g + 2]; nwq[1] = uw[2 * g + 3]; nbq[0] = ub[2 * g + 2]; nbq[1] = ub[2 * g + 3];
;                     if (MODE == 2) { nrq[0] = ur[2 * g + 2]; nrq[1] = ur[2 * g + 3]; } }
;                 f2 bb[4], ww[4], kq[4], rr[4];
;                 ww[0] = (f2){cwq0.x, cwq0.y}; ww[1] = (f2){cwq0.z, cwq0.w}; ww[2] = (f2){cwq1.x, cwq1.y}; ww[3] = (f2){cwq1.z, cwq1.w};
;                 bb[0] = (f2){cbq0.x, cbq0.y}; bb[1] = (f2){cbq0.z, cbq0.w}; bb[2] = (f2){cbq1.x, cbq1.y}; bb[3] = (f2){cbq1.z, cbq1.w};
;                 rr[0] = (f2){crq0.x, crq0.y}; rr[1] = (f2){crq0.z, crq0.w}; rr[2] = (f2){crq1.x, crq1.y}; rr[3] = (f2){crq1.z, crq1.w};
; #pragma unroll
;                 for (int q = 0; q < 4; ++q) { const int j = g * 4 + q; if (MODE != 1) kq[q] = RL2(ck, j); }
;                 __builtin_amdgcn_sched_barrier(0);
; #pragma unroll
;                 for (int q = 0; q < 4; ++q) { const int j = g * 4 + q;
;                     f2 t = sas * bb[q];
;                     if (MODE != 1) t = vvs * kq[q] + t;
;                     S[j] = S[j] * ww[q] + t;
;                     if (MODE == 3) Pm[j] = Pm[j] * ww[q] + pas * bb[q];
;                     if (MODE == 2) { if (j & 1) y3 = S[j] * rr[q] + y3; else y2 = S[j] * rr[q] + y2; } }
;             }
;             if (MODE == 2) yb[(size_t)(t0 + s) * 512 + h * 64 + lane] = (bf16)f2bf((y2.x + y2.y) + (y3.x + y3.y));
	v_mul_f32_dpp v56, v71, v56 row_newbcast:4 row_mask:0xf bank_mask:0xf
	v_mul_f32_dpp v57, v71, v57 row_newbcast:5 row_mask:0xf bank_mask:0xf
	v_mul_f32_dpp v58, v71, v58 row_newbcast:6 row_mask:0xf bank_mask:0xf
	v_mul_f32_dpp v59, v71, v59 row_newbcast:7 row_mask:0xf bank_mask:0xf
	v_fmac_f32_dpp v56, v75, v90 row_newbcast:4 row_mask:0xf bank_mask:0xf
	v_fmac_f32_dpp v57, v75, v90 row_newbcast:5 row_mask:0xf bank_mask:0xf
	v_fmac_f32_dpp v58, v75, v90 row_newbcast:6 row_mask:0xf bank_mask:0xf
	v_fmac_f32_dpp v59, v75, v90 row_newbcast:7 row_mask:0xf bank_mask:0xf
	v_fmac_f32_dpp v56, v79, v88 row_newbcast:4 row_mask:0xf bank_mask:0xf
	v_fmac_f32_dpp v57, v79, v88 row_newbcast:5 row_mask:0xf bank_mask:0xf
	v_fmac_f32_dpp v58, v79, v88 row_newbcast:6 row_mask:0xf bank_mask:0xf
	v_fmac_f32_dpp v59, v79, v88 row_newbcast:7 row_mask:0xf bank_mask:0xf
	v_fmac_f32_dpp v94, v83, v56 row_newbcast:4 row_mask:0xf bank_mask:0xf
	v_fmac_f32_dpp v95, v83, v57 row_newbcast:5 row_mask:0xf bank_mask:0xf
	v_fmac_f32_dpp v96, v83, v58 row_newbcast:6 row_mask:0xf bank_mask:0xf
	v_fmac_f32_dpp v97, v83, v59 row_newbcast:7 row_mask:0xf bank_mask:0xf
	v_mul_f32_dpp v52, v71, v52 row_newbcast:8 row_mask:0xf bank_mask:0xf
	v_mul_f32_dpp v53, v71, v53 row_newbcast:9 row_mask:0xf bank_mask:0xf
	v_mul_f32_dpp v54, v71, v54 row_newbcast:10 row_mask:0xf bank_mask:0xf
	v_mul_f32_dpp v55, v71, v55 row_newbcast:11 row_mask:0xf bank_mask:0xf
	v_fmac_f32_dpp v52, v75, v90 row_newbcast:8 row_mask:0xf bank_mask:0xf
	v_fmac_f32_dpp v53, v75, v90 row_newbcast:9 row_mask:0xf bank_mask:0xf
	v_fmac_f32_dpp v54, v75, v90 row_newbcast:10 row_mask:0xf bank_mask:0xf
	v_fmac_f32_dpp v55, v75, v90 row_newbcast:11 row_mask:0xf bank_mask:0xf
	v_fmac_f32_dpp v52, v79, v88 row_newbcast:8 row_mask:0xf bank_mask:0xf
	v_fmac_f32_dpp v53, v79, v88 row_newbcast:9 row_mask:0xf bank_mask:0xf
	v_fmac_f32_dpp v54, v79, v88 row_newbcast:10 row_mask:0xf bank_mask:0xf
	v_fmac_f32_dpp v55, v79, v88 row_newbcast:11 row_mask:0xf bank_mask:0xf
	v_fmac_f32_dpp v94, v83, v52 row_newbcast:8 row_mask:0xf bank_mask:0xf
	v_fmac_f32_dpp v95, v83, v53 row_newbcast:9 row_mask:0xf bank_mask:0xf
	v_fmac_f32_dpp v96, v83, v54 row_newbcast:10 row_mask:0xf bank_mask:0xf
	v_fmac_f32_dpp v97, v83, v55 row_newbcast:11 row_mask:0xf bank_mask:0xf
	v_mul_f32_dpp v48, v71, v48 row_newbcast:12 row_mask:0xf bank_mask:0xf
	v_mul_f32_dpp v49, v71, v49 row_newbcast:13 row_mask:0xf bank_mask:0xf
	v_mul_f32_dpp v50, v71, v50 row_newbcast:14 row_mask:0xf bank_mask:0xf
	v_mul_f32_dpp v51, v71, v51 row_newbcast:15 row_mask:0xf bank_mask:0xf
	v_fmac_f32_dpp v48, v75, v90 row_newbcast:12 row_mask:0xf bank_mask:0xf
	v_fmac_f32_dpp v49, v75, v90 row_newbcast:13 row_mask:0xf bank_mask:0xf
	v_fmac_f32_dpp v50, v75, v90 row_newbcast:14 row_mask:0xf bank_mask:0xf
	v_fmac_f32_dpp v51, v75, v90 row_newbcast:15 row_mask:0xf bank_mask:0xf
	v_fmac_f32_dpp v48, v79, v88 row_newbcast:12 row_mask:0xf bank_mask:0xf
	v_fmac_f32_dpp v49, v79, v88 row_newbcast:13 row_mask:0xf bank_mask:0xf
	v_fmac_f32_dpp v50, v79, v88 row_newbcast:14 row_mask:0xf bank_mask:0xf
	v_fmac_f32_dpp v51, v79, v88 row_newbcast:15 row_mask:0xf bank_mask:0xf
	v_fmac_f32_dpp v94, v83, v48 row_newbcast:12 row_mask:0xf bank_mask:0xf
	v_fmac_f32_dpp v95, v83, v49 row_newbcast:13 row_mask:0xf bank_mask:0xf
	v_fmac_f32_dpp v96, v83, v50 row_newbcast:14 row_mask:0xf bank_mask:0xf
	v_fmac_f32_dpp v97, v83, v51 row_newbcast:15 row_mask:0xf bank_mask:0xf
	ds_read_b32 v71, v100 offset:11712
	ds_read_b32 v75, v100 offset:16064
	ds_read_b32 v83, v100 offset:4544
	v_add_f32_e32 v94, v94, v95
	v_add_f32_e32 v96, v96, v97
	s_or_b32 s8, s14, s44
	s_ashr_i32 s9, s8, 31
	s_lshl_b64 s[8:9], s[8:9], 10
	v_add_f32_e32 v94, v94, v96
	s_add_i32 s4, s4, 1
	s_add_i32 s5, s5, -1
	v_lshl_add_u64 v[104:105], v[136:137], 0, s[8:9]
	v_cvt_pk_bf16_f32 v94, v94, v94
	s_cmp_eq_u32 s4, 16
	global_store_short v[104:105], v94, off
	s_cbranch_scc1 .Lscan_c_exit
	s_waitcnt vmcnt(1)
	v_mov_b32_e32 v76, v84
	v_mov_b32_e32 v77, v85
	v_mov_b32_e32 v78, v86
	v_mov_b32_e32 v79, v87
	v_mov_b32_e32 v88, v89
	s_branch .Lscan_c_step
